# PRIO-MERGE: the 40 adjacent s_setprio 0 / s_setprio 1 pairs between MFMA blocks of the GEMM K-loops removed - both blocks run under one priority raise (on REL-FIRST)
# baseline (speedup 1.0000x reference)
.LBB0_212:
	s_ashr_i32 s27, s26, 31
	s_lshl_b64 s[30:31], s[26:27], 19
	s_ashr_i32 s25, s24, 31
	v_lshl_add_u64 v[148:149], v[130:131], 0, s[30:31]
	s_lshl_b64 s[30:31], s[24:25], 19
	v_lshl_add_u64 v[150:151], v[132:133], 0, s[30:31]
	v_cndmask_b32_e64 v152, v2, v150, s[4:5]
	v_lshl_add_u64 v[156:157], v[2:3], 0, s[20:21]
	v_mov_b32_e32 v2, 0
	v_cndmask_b32_e64 v1, v5, v149, s[4:5]
	v_cndmask_b32_e64 v138, v4, v148, s[4:5]
	v_cndmask_b32_e64 v153, v3, v151, s[4:5]
	v_lshl_add_u64 v[154:155], v[4:5], 0, s[16:17]
	s_mov_b32 s7, -2
	ds_read_b128 v[168:171], v160
	ds_read_b128 v[172:175], v160 offset:1024
	ds_read_b128 v[176:179], v160 offset:2048
	ds_read_b128 v[180:183], v160 offset:3072
	ds_read_b128 v[184:187], v161
	ds_read_b128 v[188:191], v161 offset:1024
	ds_read_b128 v[192:195], v161 offset:2048
	ds_read_b128 v[196:199], v161 offset:3072
	s_cmp_eq_u32 s7, 12
	v_lshl_add_u64 v[200:201], v[154:155], 0, s[22:23]
	s_cselect_b64 vcc, -1, 0
	v_cndmask_b32_e32 v233, v201, v1, vcc
	v_cndmask_b32_e32 v232, v200, v138, vcc
	v_cndmask_b32_e32 v235, v157, v153, vcc
	v_cndmask_b32_e32 v234, v156, v152, vcc
	s_mov_b32 m0, s42
	v_lshl_add_u64 v[236:237], v[154:155], 0, v[140:141]
	ds_read_b128 v[200:203], v162
	ds_read_b128 v[204:207], v162 offset:1024
	ds_read_b128 v[208:211], v162 offset:2048
	ds_read_b128 v[212:215], v162 offset:3072
	ds_read_b128 v[216:219], v162 offset:4096
	ds_read_b128 v[220:223], v162 offset:5120
	ds_read_b128 v[224:227], v162 offset:6144
	ds_read_b128 v[228:231], v162 offset:7168
	global_load_lds_dwordx4 v[236:237], off
	v_lshl_add_u64 v[236:237], v[154:155], 0, v[142:143]
	s_mov_b32 m0, s43
	s_nop 0
	global_load_lds_dwordx4 v[236:237], off
	s_waitcnt vmcnt(8)
	s_waitcnt lgkmcnt(0)
	s_barrier
	s_setprio 1
	s_waitcnt lgkmcnt(0)
	v_mfma_f32_16x16x32_bf16 v[126:129], v[168:171], v[200:203], 0
	v_mfma_f32_16x16x32_bf16 v[122:125], v[176:179], v[200:203], 0
	v_mfma_f32_16x16x32_bf16 v[110:113], v[168:171], v[208:211], 0
	v_mfma_f32_16x16x32_bf16 v[106:109], v[176:179], v[208:211], 0
	v_mfma_f32_16x16x32_bf16 v[94:97], v[168:171], v[216:219], 0
	v_mfma_f32_16x16x32_bf16 v[90:93], v[176:179], v[216:219], 0
	v_mfma_f32_16x16x32_bf16 v[78:81], v[168:171], v[224:227], 0
	v_mfma_f32_16x16x32_bf16 v[74:77], v[176:179], v[224:227], 0
	v_mfma_f32_16x16x32_bf16 v[126:129], v[172:175], v[204:207], v[126:129]
	v_mfma_f32_16x16x32_bf16 v[122:125], v[180:183], v[204:207], v[122:125]
	v_mfma_f32_16x16x32_bf16 v[110:113], v[172:175], v[212:215], v[110:113]
	v_mfma_f32_16x16x32_bf16 v[106:109], v[180:183], v[212:215], v[106:109]
	v_mfma_f32_16x16x32_bf16 v[94:97], v[172:175], v[220:223], v[94:97]
	v_mfma_f32_16x16x32_bf16 v[90:93], v[180:183], v[220:223], v[90:93]
	v_mfma_f32_16x16x32_bf16 v[78:81], v[172:175], v[228:231], v[78:81]
	v_mfma_f32_16x16x32_bf16 v[74:77], v[180:183], v[228:231], v[74:77]
	v_mfma_f32_16x16x32_bf16 v[118:121], v[184:187], v[200:203], 0
	v_mfma_f32_16x16x32_bf16 v[114:117], v[192:195], v[200:203], 0
	v_mfma_f32_16x16x32_bf16 v[102:105], v[184:187], v[208:211], 0
	v_mfma_f32_16x16x32_bf16 v[98:101], v[192:195], v[208:211], 0
	v_mfma_f32_16x16x32_bf16 v[86:89], v[184:187], v[216:219], 0
	v_mfma_f32_16x16x32_bf16 v[82:85], v[192:195], v[216:219], 0
	v_mfma_f32_16x16x32_bf16 v[70:73], v[184:187], v[224:227], 0
	v_mfma_f32_16x16x32_bf16 v[66:69], v[192:195], v[224:227], 0
	v_mfma_f32_16x16x32_bf16 v[118:121], v[188:191], v[204:207], v[118:121]
	v_mfma_f32_16x16x32_bf16 v[114:117], v[196:199], v[204:207], v[114:117]
	v_mfma_f32_16x16x32_bf16 v[102:105], v[188:191], v[212:215], v[102:105]
	v_mfma_f32_16x16x32_bf16 v[98:101], v[196:199], v[212:215], v[98:101]
	v_mfma_f32_16x16x32_bf16 v[86:89], v[188:191], v[220:223], v[86:89]
	v_mfma_f32_16x16x32_bf16 v[82:85], v[196:199], v[220:223], v[82:85]
	v_mfma_f32_16x16x32_bf16 v[70:73], v[188:191], v[228:231], v[70:73]
	v_mfma_f32_16x16x32_bf16 v[66:69], v[196:199], v[228:231], v[66:69]
	s_setprio 0
	s_barrier
	s_mov_b32 m0, s44
	v_lshl_add_u64 v[236:237], v[234:235], 0, v[134:135]
	ds_read_b128 v[200:203], v162 offset:16384
	ds_read_b128 v[204:207], v162 offset:17408
	ds_read_b128 v[208:211], v162 offset:18432
	ds_read_b128 v[212:215], v162 offset:19456
	ds_read_b128 v[216:219], v162 offset:20480
	ds_read_b128 v[220:223], v162 offset:21504
	ds_read_b128 v[224:227], v162 offset:22528
	ds_read_b128 v[228:231], v162 offset:23552
	global_load_lds_dwordx4 v[236:237], off
	v_lshl_add_u64 v[238:239], v[234:235], 0, v[136:137]
	s_mov_b32 m0, s45
	v_lshl_add_u64 v[240:241], v[234:235], 0, s[10:11]
	global_load_lds_dwordx4 v[238:239], off
	v_lshl_add_u64 v[242:243], v[240:241], 0, v[134:135]
	s_mov_b32 m0, s46
	v_lshl_add_u64 v[240:241], v[240:241], 0, v[136:137]
	global_load_lds_dwordx4 v[242:243], off
	s_mov_b32 m0, s47
	v_lshl_add_u64 v[242:243], v[232:233], 0, v[136:137]
	global_load_lds_dwordx4 v[240:241], off
	v_lshl_add_u64 v[240:241], v[232:233], 0, v[134:135]
	s_mov_b32 m0, s0
	s_nop 0
	global_load_lds_dwordx4 v[240:241], off
	s_mov_b32 m0, s1
	s_nop 0
	global_load_lds_dwordx4 v[242:243], off
	s_waitcnt vmcnt(8)
	s_waitcnt lgkmcnt(0)
	s_barrier
	s_setprio 1
	s_waitcnt lgkmcnt(0)
	v_mfma_f32_16x16x32_bf16 v[62:65], v[168:171], v[200:203], 0
	v_mfma_f32_16x16x32_bf16 v[58:61], v[176:179], v[200:203], 0
	v_mfma_f32_16x16x32_bf16 v[46:49], v[168:171], v[208:211], 0
	v_mfma_f32_16x16x32_bf16 v[42:45], v[176:179], v[208:211], 0
	v_mfma_f32_16x16x32_bf16 v[30:33], v[168:171], v[216:219], 0
	v_mfma_f32_16x16x32_bf16 v[26:29], v[176:179], v[216:219], 0
	v_mfma_f32_16x16x32_bf16 v[14:17], v[168:171], v[224:227], 0
	v_mfma_f32_16x16x32_bf16 v[10:13], v[176:179], v[224:227], 0
	v_mfma_f32_16x16x32_bf16 v[62:65], v[172:175], v[204:207], v[62:65]
	v_mfma_f32_16x16x32_bf16 v[58:61], v[180:183], v[204:207], v[58:61]
	v_mfma_f32_16x16x32_bf16 v[46:49], v[172:175], v[212:215], v[46:49]
	v_mfma_f32_16x16x32_bf16 v[42:45], v[180:183], v[212:215], v[42:45]
	v_mfma_f32_16x16x32_bf16 v[30:33], v[172:175], v[220:223], v[30:33]
	v_mfma_f32_16x16x32_bf16 v[26:29], v[180:183], v[220:223], v[26:29]
	v_mfma_f32_16x16x32_bf16 v[14:17], v[172:175], v[228:231], v[14:17]
	v_mfma_f32_16x16x32_bf16 v[10:13], v[180:183], v[228:231], v[10:13]
	v_mfma_f32_16x16x32_bf16 v[54:57], v[184:187], v[200:203], 0
	v_mfma_f32_16x16x32_bf16 v[50:53], v[192:195], v[200:203], 0
	v_mfma_f32_16x16x32_bf16 v[38:41], v[184:187], v[208:211], 0
	v_mfma_f32_16x16x32_bf16 v[34:37], v[192:195], v[208:211], 0
	v_mfma_f32_16x16x32_bf16 v[22:25], v[184:187], v[216:219], 0
	v_mfma_f32_16x16x32_bf16 v[18:21], v[192:195], v[216:219], 0
	v_mfma_f32_16x16x32_bf16 v[6:9], v[184:187], v[224:227], 0
	v_mfma_f32_16x16x32_bf16 v[2:5], v[192:195], v[224:227], 0
	v_mfma_f32_16x16x32_bf16 v[54:57], v[188:191], v[204:207], v[54:57]
	v_mfma_f32_16x16x32_bf16 v[50:53], v[196:199], v[204:207], v[50:53]
	v_mfma_f32_16x16x32_bf16 v[38:41], v[188:191], v[212:215], v[38:41]
	v_mfma_f32_16x16x32_bf16 v[34:37], v[196:199], v[212:215], v[34:37]
	v_mfma_f32_16x16x32_bf16 v[22:25], v[188:191], v[220:223], v[22:25]
	v_mfma_f32_16x16x32_bf16 v[18:21], v[196:199], v[220:223], v[18:21]
	v_mfma_f32_16x16x32_bf16 v[6:9], v[188:191], v[228:231], v[6:9]
	v_mfma_f32_16x16x32_bf16 v[2:5], v[196:199], v[228:231], v[2:5]
	s_setprio 0
	s_barrier
	ds_read_b128 v[168:171], v163
	ds_read_b128 v[172:175], v163 offset:1024
	ds_read_b128 v[176:179], v163 offset:2048
	ds_read_b128 v[180:183], v163 offset:3072
	ds_read_b128 v[184:187], v164
	ds_read_b128 v[188:191], v164 offset:1024
	ds_read_b128 v[192:195], v164 offset:2048
	ds_read_b128 v[196:199], v164 offset:3072
	v_lshl_add_u64 v[232:233], v[232:233], 0, s[10:11]
	s_mov_b32 m0, s2
	v_lshl_add_u64 v[244:245], v[232:233], 0, v[134:135]
	ds_read_b128 v[200:203], v162 offset:32768
	ds_read_b128 v[204:207], v162 offset:33792
	ds_read_b128 v[208:211], v162 offset:34816
	ds_read_b128 v[212:215], v162 offset:35840
	ds_read_b128 v[216:219], v162 offset:36864
	ds_read_b128 v[220:223], v162 offset:37888
	ds_read_b128 v[224:227], v162 offset:38912
	ds_read_b128 v[228:231], v162 offset:39936
	global_load_lds_dwordx4 v[244:245], off
	v_lshl_add_u64 v[232:233], v[232:233], 0, v[136:137]
	s_mov_b32 m0, s3
	s_nop 0
	global_load_lds_dwordx4 v[232:233], off
	s_waitcnt vmcnt(8)
	s_waitcnt lgkmcnt(0)
	s_barrier
	s_setprio 1
	s_waitcnt lgkmcnt(0)
	v_mfma_f32_16x16x32_bf16 v[126:129], v[168:171], v[200:203], v[126:129]
	v_mfma_f32_16x16x32_bf16 v[122:125], v[176:179], v[200:203], v[122:125]
	v_mfma_f32_16x16x32_bf16 v[110:113], v[168:171], v[208:211], v[110:113]
	v_mfma_f32_16x16x32_bf16 v[106:109], v[176:179], v[208:211], v[106:109]
	v_mfma_f32_16x16x32_bf16 v[94:97], v[168:171], v[216:219], v[94:97]
	v_mfma_f32_16x16x32_bf16 v[90:93], v[176:179], v[216:219], v[90:93]
	v_mfma_f32_16x16x32_bf16 v[78:81], v[168:171], v[224:227], v[78:81]
	v_mfma_f32_16x16x32_bf16 v[74:77], v[176:179], v[224:227], v[74:77]
	v_mfma_f32_16x16x32_bf16 v[126:129], v[172:175], v[204:207], v[126:129]
	v_mfma_f32_16x16x32_bf16 v[122:125], v[180:183], v[204:207], v[122:125]
	v_mfma_f32_16x16x32_bf16 v[110:113], v[172:175], v[212:215], v[110:113]
	v_mfma_f32_16x16x32_bf16 v[106:109], v[180:183], v[212:215], v[106:109]
	v_mfma_f32_16x16x32_bf16 v[94:97], v[172:175], v[220:223], v[94:97]
	v_mfma_f32_16x16x32_bf16 v[90:93], v[180:183], v[220:223], v[90:93]
	v_mfma_f32_16x16x32_bf16 v[78:81], v[172:175], v[228:231], v[78:81]
	v_mfma_f32_16x16x32_bf16 v[74:77], v[180:183], v[228:231], v[74:77]
	v_mfma_f32_16x16x32_bf16 v[118:121], v[184:187], v[200:203], v[118:121]
	v_mfma_f32_16x16x32_bf16 v[114:117], v[192:195], v[200:203], v[114:117]
	v_mfma_f32_16x16x32_bf16 v[102:105], v[184:187], v[208:211], v[102:105]
	v_mfma_f32_16x16x32_bf16 v[98:101], v[192:195], v[208:211], v[98:101]
	v_mfma_f32_16x16x32_bf16 v[86:89], v[184:187], v[216:219], v[86:89]
	v_mfma_f32_16x16x32_bf16 v[82:85], v[192:195], v[216:219], v[82:85]
	v_mfma_f32_16x16x32_bf16 v[70:73], v[184:187], v[224:227], v[70:73]
	v_mfma_f32_16x16x32_bf16 v[66:69], v[192:195], v[224:227], v[66:69]
	v_mfma_f32_16x16x32_bf16 v[118:121], v[188:191], v[204:207], v[118:121]
	v_mfma_f32_16x16x32_bf16 v[114:117], v[196:199], v[204:207], v[114:117]
	v_mfma_f32_16x16x32_bf16 v[102:105], v[188:191], v[212:215], v[102:105]
	v_mfma_f32_16x16x32_bf16 v[98:101], v[196:199], v[212:215], v[98:101]
	v_mfma_f32_16x16x32_bf16 v[86:89], v[188:191], v[220:223], v[86:89]
	v_mfma_f32_16x16x32_bf16 v[82:85], v[196:199], v[220:223], v[82:85]
	v_mfma_f32_16x16x32_bf16 v[70:73], v[188:191], v[228:231], v[70:73]
	v_mfma_f32_16x16x32_bf16 v[66:69], v[196:199], v[228:231], v[66:69]
	s_setprio 0
	s_barrier
	s_mov_b32 m0, s48
	v_lshl_add_u64 v[232:233], v[236:237], 0, s[14:15]
	ds_read_b128 v[200:203], v162 offset:49152
	ds_read_b128 v[204:207], v162 offset:50176
	ds_read_b128 v[208:211], v162 offset:51200
	ds_read_b128 v[212:215], v162 offset:52224
	ds_read_b128 v[216:219], v162 offset:53248
	ds_read_b128 v[220:223], v162 offset:54272
	ds_read_b128 v[224:227], v162 offset:55296
	ds_read_b128 v[228:231], v162 offset:56320
	global_load_lds_dwordx4 v[232:233], off
	v_lshl_add_u64 v[232:233], v[238:239], 0, s[14:15]
	s_mov_b32 m0, s51
	s_nop 0
	global_load_lds_dwordx4 v[232:233], off
	v_lshl_add_u64 v[232:233], v[234:235], 0, s[16:17]
	v_lshl_add_u64 v[234:235], v[232:233], 0, v[134:135]
	s_mov_b32 m0, s52
	v_lshl_add_u64 v[232:233], v[232:233], 0, v[136:137]
	global_load_lds_dwordx4 v[234:235], off
	s_add_i32 m0, s52, 0x2000
	s_nop 0
	global_load_lds_dwordx4 v[232:233], off
	v_lshl_add_u64 v[232:233], v[240:241], 0, s[14:15]
	s_mov_b32 m0, s34
	s_nop 0
	global_load_lds_dwordx4 v[232:233], off
	v_lshl_add_u64 v[232:233], v[242:243], 0, s[14:15]
	s_mov_b32 m0, s35
	s_nop 0
	global_load_lds_dwordx4 v[232:233], off
	s_waitcnt vmcnt(8)
	s_waitcnt lgkmcnt(0)
	s_barrier
	s_setprio 1
	s_waitcnt lgkmcnt(0)
	v_mfma_f32_16x16x32_bf16 v[62:65], v[168:171], v[200:203], v[62:65]
	v_mfma_f32_16x16x32_bf16 v[58:61], v[176:179], v[200:203], v[58:61]
	v_mfma_f32_16x16x32_bf16 v[46:49], v[168:171], v[208:211], v[46:49]
	v_mfma_f32_16x16x32_bf16 v[42:45], v[176:179], v[208:211], v[42:45]
	v_mfma_f32_16x16x32_bf16 v[30:33], v[168:171], v[216:219], v[30:33]
	v_mfma_f32_16x16x32_bf16 v[26:29], v[176:179], v[216:219], v[26:29]
	v_mfma_f32_16x16x32_bf16 v[14:17], v[168:171], v[224:227], v[14:17]
	v_mfma_f32_16x16x32_bf16 v[10:13], v[176:179], v[224:227], v[10:13]
	v_mfma_f32_16x16x32_bf16 v[62:65], v[172:175], v[204:207], v[62:65]
	v_mfma_f32_16x16x32_bf16 v[58:61], v[180:183], v[204:207], v[58:61]
	v_mfma_f32_16x16x32_bf16 v[46:49], v[172:175], v[212:215], v[46:49]
	v_mfma_f32_16x16x32_bf16 v[42:45], v[180:183], v[212:215], v[42:45]
	v_mfma_f32_16x16x32_bf16 v[30:33], v[172:175], v[220:223], v[30:33]
	v_mfma_f32_16x16x32_bf16 v[26:29], v[180:183], v[220:223], v[26:29]
	v_mfma_f32_16x16x32_bf16 v[14:17], v[172:175], v[228:231], v[14:17]
	v_mfma_f32_16x16x32_bf16 v[10:13], v[180:183], v[228:231], v[10:13]
	v_mfma_f32_16x16x32_bf16 v[54:57], v[184:187], v[200:203], v[54:57]
	v_mfma_f32_16x16x32_bf16 v[50:53], v[192:195], v[200:203], v[50:53]
	v_mfma_f32_16x16x32_bf16 v[38:41], v[184:187], v[208:211], v[38:41]
	v_mfma_f32_16x16x32_bf16 v[34:37], v[192:195], v[208:211], v[34:37]
	v_mfma_f32_16x16x32_bf16 v[22:25], v[184:187], v[216:219], v[22:25]
	v_mfma_f32_16x16x32_bf16 v[18:21], v[192:195], v[216:219], v[18:21]
	v_mfma_f32_16x16x32_bf16 v[6:9], v[184:187], v[224:227], v[6:9]
	v_mfma_f32_16x16x32_bf16 v[2:5], v[192:195], v[224:227], v[2:5]
	v_mfma_f32_16x16x32_bf16 v[54:57], v[188:191], v[204:207], v[54:57]
	v_mfma_f32_16x16x32_bf16 v[50:53], v[196:199], v[204:207], v[50:53]
	v_mfma_f32_16x16x32_bf16 v[38:41], v[188:191], v[212:215], v[38:41]
	v_mfma_f32_16x16x32_bf16 v[34:37], v[196:199], v[212:215], v[34:37]
	v_mfma_f32_16x16x32_bf16 v[22:25], v[188:191], v[220:223], v[22:25]
	v_mfma_f32_16x16x32_bf16 v[18:21], v[196:199], v[220:223], v[18:21]
	v_mfma_f32_16x16x32_bf16 v[6:9], v[188:191], v[228:231], v[6:9]
	v_mfma_f32_16x16x32_bf16 v[2:5], v[196:199], v[228:231], v[2:5]
	s_setprio 0
	s_barrier
	s_add_i32 s7, s7, 2
	v_lshl_add_u64 v[154:155], v[154:155], 0, s[20:21]
	s_cmp_gt_u32 s7, 13
	v_lshl_add_u64 v[156:157], v[156:157], 0, s[20:21]
	s_cbranch_scc0 .LBB0_213
	s_branch .Lpeel_exit_1
.LBB0_213:
	ds_read_b128 v[168:171], v160
	ds_read_b128 v[172:175], v160 offset:1024
	ds_read_b128 v[176:179], v160 offset:2048
	ds_read_b128 v[180:183], v160 offset:3072
	ds_read_b128 v[184:187], v161
	ds_read_b128 v[188:191], v161 offset:1024
	ds_read_b128 v[192:195], v161 offset:2048
	ds_read_b128 v[196:199], v161 offset:3072
	s_cmp_eq_u32 s7, 12
	v_lshl_add_u64 v[200:201], v[154:155], 0, s[22:23]
	s_cselect_b64 vcc, -1, 0
	v_cndmask_b32_e32 v233, v201, v1, vcc
	v_cndmask_b32_e32 v232, v200, v138, vcc
	v_cndmask_b32_e32 v235, v157, v153, vcc
	v_cndmask_b32_e32 v234, v156, v152, vcc
	s_mov_b32 m0, s42
	v_lshl_add_u64 v[236:237], v[154:155], 0, v[140:141]
	ds_read_b128 v[200:203], v162
	ds_read_b128 v[204:207], v162 offset:1024
	ds_read_b128 v[208:211], v162 offset:2048
	ds_read_b128 v[212:215], v162 offset:3072
	ds_read_b128 v[216:219], v162 offset:4096
	ds_read_b128 v[220:223], v162 offset:5120
	ds_read_b128 v[224:227], v162 offset:6144
	ds_read_b128 v[228:231], v162 offset:7168
	global_load_lds_dwordx4 v[236:237], off
	v_lshl_add_u64 v[236:237], v[154:155], 0, v[142:143]
	s_mov_b32 m0, s43
	s_nop 0
	global_load_lds_dwordx4 v[236:237], off
	s_waitcnt vmcnt(8)
	s_waitcnt lgkmcnt(0)
	s_barrier
	s_setprio 1
	s_waitcnt lgkmcnt(0)
	v_mfma_f32_16x16x32_bf16 v[126:129], v[168:171], v[200:203], v[126:129]
	v_mfma_f32_16x16x32_bf16 v[122:125], v[176:179], v[200:203], v[122:125]
	v_mfma_f32_16x16x32_bf16 v[110:113], v[168:171], v[208:211], v[110:113]
	v_mfma_f32_16x16x32_bf16 v[106:109], v[176:179], v[208:211], v[106:109]
	v_mfma_f32_16x16x32_bf16 v[94:97], v[168:171], v[216:219], v[94:97]
	v_mfma_f32_16x16x32_bf16 v[90:93], v[176:179], v[216:219], v[90:93]
	v_mfma_f32_16x16x32_bf16 v[78:81], v[168:171], v[224:227], v[78:81]
	v_mfma_f32_16x16x32_bf16 v[74:77], v[176:179], v[224:227], v[74:77]
	v_mfma_f32_16x16x32_bf16 v[126:129], v[172:175], v[204:207], v[126:129]
	v_mfma_f32_16x16x32_bf16 v[122:125], v[180:183], v[204:207], v[122:125]
	v_mfma_f32_16x16x32_bf16 v[110:113], v[172:175], v[212:215], v[110:113]
	v_mfma_f32_16x16x32_bf16 v[106:109], v[180:183], v[212:215], v[106:109]
	v_mfma_f32_16x16x32_bf16 v[94:97], v[172:175], v[220:223], v[94:97]
	v_mfma_f32_16x16x32_bf16 v[90:93], v[180:183], v[220:223], v[90:93]
	v_mfma_f32_16x16x32_bf16 v[78:81], v[172:175], v[228:231], v[78:81]
	v_mfma_f32_16x16x32_bf16 v[74:77], v[180:183], v[228:231], v[74:77]
	v_mfma_f32_16x16x32_bf16 v[118:121], v[184:187], v[200:203], v[118:121]
	v_mfma_f32_16x16x32_bf16 v[114:117], v[192:195], v[200:203], v[114:117]
	v_mfma_f32_16x16x32_bf16 v[102:105], v[184:187], v[208:211], v[102:105]
	v_mfma_f32_16x16x32_bf16 v[98:101], v[192:195], v[208:211], v[98:101]
	v_mfma_f32_16x16x32_bf16 v[86:89], v[184:187], v[216:219], v[86:89]
	v_mfma_f32_16x16x32_bf16 v[82:85], v[192:195], v[216:219], v[82:85]
	v_mfma_f32_16x16x32_bf16 v[70:73], v[184:187], v[224:227], v[70:73]
	v_mfma_f32_16x16x32_bf16 v[66:69], v[192:195], v[224:227], v[66:69]
	v_mfma_f32_16x16x32_bf16 v[118:121], v[188:191], v[204:207], v[118:121]
	v_mfma_f32_16x16x32_bf16 v[114:117], v[196:199], v[204:207], v[114:117]
	v_mfma_f32_16x16x32_bf16 v[102:105], v[188:191], v[212:215], v[102:105]
	v_mfma_f32_16x16x32_bf16 v[98:101], v[196:199], v[212:215], v[98:101]
	v_mfma_f32_16x16x32_bf16 v[86:89], v[188:191], v[220:223], v[86:89]
	v_mfma_f32_16x16x32_bf16 v[82:85], v[196:199], v[220:223], v[82:85]
	v_mfma_f32_16x16x32_bf16 v[70:73], v[188:191], v[228:231], v[70:73]
	v_mfma_f32_16x16x32_bf16 v[66:69], v[196:199], v[228:231], v[66:69]
	s_setprio 0
	s_barrier
	s_mov_b32 m0, s44
	v_lshl_add_u64 v[236:237], v[234:235], 0, v[134:135]
	ds_read_b128 v[200:203], v162 offset:16384
	ds_read_b128 v[204:207], v162 offset:17408
	ds_read_b128 v[208:211], v162 offset:18432
	ds_read_b128 v[212:215], v162 offset:19456
	ds_read_b128 v[216:219], v162 offset:20480
	ds_read_b128 v[220:223], v162 offset:21504
	ds_read_b128 v[224:227], v162 offset:22528
	ds_read_b128 v[228:231], v162 offset:23552
	global_load_lds_dwordx4 v[236:237], off
	v_lshl_add_u64 v[238:239], v[234:235], 0, v[136:137]
	s_mov_b32 m0, s45
	v_lshl_add_u64 v[240:241], v[234:235], 0, s[10:11]
	global_load_lds_dwordx4 v[238:239], off
	v_lshl_add_u64 v[242:243], v[240:241], 0, v[134:135]
	s_mov_b32 m0, s46
	v_lshl_add_u64 v[240:241], v[240:241], 0, v[136:137]
	global_load_lds_dwordx4 v[242:243], off
	s_mov_b32 m0, s47
	v_lshl_add_u64 v[242:243], v[232:233], 0, v[136:137]
	global_load_lds_dwordx4 v[240:241], off
	v_lshl_add_u64 v[240:241], v[232:233], 0, v[134:135]
	s_mov_b32 m0, s0
	s_nop 0
	global_load_lds_dwordx4 v[240:241], off
	s_mov_b32 m0, s1
	s_nop 0
	global_load_lds_dwordx4 v[242:243], off
	s_waitcnt vmcnt(8)
	s_waitcnt lgkmcnt(0)
	s_barrier
	s_setprio 1
	s_waitcnt lgkmcnt(0)
	v_mfma_f32_16x16x32_bf16 v[62:65], v[168:171], v[200:203], v[62:65]
	v_mfma_f32_16x16x32_bf16 v[58:61], v[176:179], v[200:203], v[58:61]
	v_mfma_f32_16x16x32_bf16 v[46:49], v[168:171], v[208:211], v[46:49]
	v_mfma_f32_16x16x32_bf16 v[42:45], v[176:179], v[208:211], v[42:45]
	v_mfma_f32_16x16x32_bf16 v[30:33], v[168:171], v[216:219], v[30:33]
	v_mfma_f32_16x16x32_bf16 v[26:29], v[176:179], v[216:219], v[26:29]
	v_mfma_f32_16x16x32_bf16 v[14:17], v[168:171], v[224:227], v[14:17]
	v_mfma_f32_16x16x32_bf16 v[10:13], v[176:179], v[224:227], v[10:13]
	v_mfma_f32_16x16x32_bf16 v[62:65], v[172:175], v[204:207], v[62:65]
	v_mfma_f32_16x16x32_bf16 v[58:61], v[180:183], v[204:207], v[58:61]
	v_mfma_f32_16x16x32_bf16 v[46:49], v[172:175], v[212:215], v[46:49]
	v_mfma_f32_16x16x32_bf16 v[42:45], v[180:183], v[212:215], v[42:45]
	v_mfma_f32_16x16x32_bf16 v[30:33], v[172:175], v[220:223], v[30:33]
	v_mfma_f32_16x16x32_bf16 v[26:29], v[180:183], v[220:223], v[26:29]
	v_mfma_f32_16x16x32_bf16 v[14:17], v[172:175], v[228:231], v[14:17]
	v_mfma_f32_16x16x32_bf16 v[10:13], v[180:183], v[228:231], v[10:13]
	v_mfma_f32_16x16x32_bf16 v[54:57], v[184:187], v[200:203], v[54:57]
	v_mfma_f32_16x16x32_bf16 v[50:53], v[192:195], v[200:203], v[50:53]
	v_mfma_f32_16x16x32_bf16 v[38:41], v[184:187], v[208:211], v[38:41]
	v_mfma_f32_16x16x32_bf16 v[34:37], v[192:195], v[208:211], v[34:37]
	v_mfma_f32_16x16x32_bf16 v[22:25], v[184:187], v[216:219], v[22:25]
	v_mfma_f32_16x16x32_bf16 v[18:21], v[192:195], v[216:219], v[18:21]
	v_mfma_f32_16x16x32_bf16 v[6:9], v[184:187], v[224:227], v[6:9]
	v_mfma_f32_16x16x32_bf16 v[2:5], v[192:195], v[224:227], v[2:5]
	v_mfma_f32_16x16x32_bf16 v[54:57], v[188:191], v[204:207], v[54:57]
	v_mfma_f32_16x16x32_bf16 v[50:53], v[196:199], v[204:207], v[50:53]
	v_mfma_f32_16x16x32_bf16 v[38:41], v[188:191], v[212:215], v[38:41]
	v_mfma_f32_16x16x32_bf16 v[34:37], v[196:199], v[212:215], v[34:37]
	v_mfma_f32_16x16x32_bf16 v[22:25], v[188:191], v[220:223], v[22:25]
	v_mfma_f32_16x16x32_bf16 v[18:21], v[196:199], v[220:223], v[18:21]
	v_mfma_f32_16x16x32_bf16 v[6:9], v[188:191], v[228:231], v[6:9]
	v_mfma_f32_16x16x32_bf16 v[2:5], v[196:199], v[228:231], v[2:5]
	s_setprio 0
	s_barrier
	ds_read_b128 v[168:171], v163
	ds_read_b128 v[172:175], v163 offset:1024
	ds_read_b128 v[176:179], v163 offset:2048
	ds_read_b128 v[180:183], v163 offset:3072
	ds_read_b128 v[184:187], v164
	ds_read_b128 v[188:191], v164 offset:1024
	ds_read_b128 v[192:195], v164 offset:2048
	ds_read_b128 v[196:199], v164 offset:3072
	v_lshl_add_u64 v[232:233], v[232:233], 0, s[10:11]
	s_mov_b32 m0, s2
	v_lshl_add_u64 v[244:245], v[232:233], 0, v[134:135]
	ds_read_b128 v[200:203], v162 offset:32768
	ds_read_b128 v[204:207], v162 offset:33792
	ds_read_b128 v[208:211], v162 offset:34816
	ds_read_b128 v[212:215], v162 offset:35840
	ds_read_b128 v[216:219], v162 offset:36864
	ds_read_b128 v[220:223], v162 offset:37888
	ds_read_b128 v[224:227], v162 offset:38912
	ds_read_b128 v[228:231], v162 offset:39936
	global_load_lds_dwordx4 v[244:245], off
	v_lshl_add_u64 v[232:233], v[232:233], 0, v[136:137]
	s_mov_b32 m0, s3
	s_nop 0
	global_load_lds_dwordx4 v[232:233], off
	s_waitcnt vmcnt(8)
	s_waitcnt lgkmcnt(0)
	s_barrier
	s_setprio 1
	s_waitcnt lgkmcnt(0)
	v_mfma_f32_16x16x32_bf16 v[126:129], v[168:171], v[200:203], v[126:129]
	v_mfma_f32_16x16x32_bf16 v[122:125], v[176:179], v[200:203], v[122:125]
	v_mfma_f32_16x16x32_bf16 v[110:113], v[168:171], v[208:211], v[110:113]
	v_mfma_f32_16x16x32_bf16 v[106:109], v[176:179], v[208:211], v[106:109]
	v_mfma_f32_16x16x32_bf16 v[94:97], v[168:171], v[216:219], v[94:97]
	v_mfma_f32_16x16x32_bf16 v[90:93], v[176:179], v[216:219], v[90:93]
	v_mfma_f32_16x16x32_bf16 v[78:81], v[168:171], v[224:227], v[78:81]
	v_mfma_f32_16x16x32_bf16 v[74:77], v[176:179], v[224:227], v[74:77]
	v_mfma_f32_16x16x32_bf16 v[126:129], v[172:175], v[204:207], v[126:129]
	v_mfma_f32_16x16x32_bf16 v[122:125], v[180:183], v[204:207], v[122:125]
	v_mfma_f32_16x16x32_bf16 v[110:113], v[172:175], v[212:215], v[110:113]
	v_mfma_f32_16x16x32_bf16 v[106:109], v[180:183], v[212:215], v[106:109]
	v_mfma_f32_16x16x32_bf16 v[94:97], v[172:175], v[220:223], v[94:97]
	v_mfma_f32_16x16x32_bf16 v[90:93], v[180:183], v[220:223], v[90:93]
	v_mfma_f32_16x16x32_bf16 v[78:81], v[172:175], v[228:231], v[78:81]
	v_mfma_f32_16x16x32_bf16 v[74:77], v[180:183], v[228:231], v[74:77]
	v_mfma_f32_16x16x32_bf16 v[118:121], v[184:187], v[200:203], v[118:121]
	v_mfma_f32_16x16x32_bf16 v[114:117], v[192:195], v[200:203], v[114:117]
	v_mfma_f32_16x16x32_bf16 v[102:105], v[184:187], v[208:211], v[102:105]
	v_mfma_f32_16x16x32_bf16 v[98:101], v[192:195], v[208:211], v[98:101]
	v_mfma_f32_16x16x32_bf16 v[86:89], v[184:187], v[216:219], v[86:89]
	v_mfma_f32_16x16x32_bf16 v[82:85], v[192:195], v[216:219], v[82:85]
	v_mfma_f32_16x16x32_bf16 v[70:73], v[184:187], v[224:227], v[70:73]
	v_mfma_f32_16x16x32_bf16 v[66:69], v[192:195], v[224:227], v[66:69]
	v_mfma_f32_16x16x32_bf16 v[118:121], v[188:191], v[204:207], v[118:121]
	v_mfma_f32_16x16x32_bf16 v[114:117], v[196:199], v[204:207], v[114:117]
	v_mfma_f32_16x16x32_bf16 v[102:105], v[188:191], v[212:215], v[102:105]
	v_mfma_f32_16x16x32_bf16 v[98:101], v[196:199], v[212:215], v[98:101]
	v_mfma_f32_16x16x32_bf16 v[86:89], v[188:191], v[220:223], v[86:89]
	v_mfma_f32_16x16x32_bf16 v[82:85], v[196:199], v[220:223], v[82:85]
	v_mfma_f32_16x16x32_bf16 v[70:73], v[188:191], v[228:231], v[70:73]
	v_mfma_f32_16x16x32_bf16 v[66:69], v[196:199], v[228:231], v[66:69]
	s_setprio 0
	s_barrier
	s_mov_b32 m0, s48
	v_lshl_add_u64 v[232:233], v[236:237], 0, s[14:15]
	ds_read_b128 v[200:203], v162 offset:49152
	ds_read_b128 v[204:207], v162 offset:50176
	ds_read_b128 v[208:211], v162 offset:51200
	ds_read_b128 v[212:215], v162 offset:52224
	ds_read_b128 v[216:219], v162 offset:53248
	ds_read_b128 v[220:223], v162 offset:54272
	ds_read_b128 v[224:227], v162 offset:55296
	ds_read_b128 v[228:231], v162 offset:56320
	global_load_lds_dwordx4 v[232:233], off
	v_lshl_add_u64 v[232:233], v[238:239], 0, s[14:15]
	s_mov_b32 m0, s51
	s_nop 0
	global_load_lds_dwordx4 v[232:233], off
	v_lshl_add_u64 v[232:233], v[234:235], 0, s[16:17]
	v_lshl_add_u64 v[234:235], v[232:233], 0, v[134:135]
	s_mov_b32 m0, s52
	v_lshl_add_u64 v[232:233], v[232:233], 0, v[136:137]
	global_load_lds_dwordx4 v[234:235], off
	s_add_i32 m0, s52, 0x2000
	s_nop 0
	global_load_lds_dwordx4 v[232:233], off
	v_lshl_add_u64 v[232:233], v[240:241], 0, s[14:15]
	s_mov_b32 m0, s34
	s_nop 0
	global_load_lds_dwordx4 v[232:233], off
	v_lshl_add_u64 v[232:233], v[242:243], 0, s[14:15]
	s_mov_b32 m0, s35
	s_nop 0
	global_load_lds_dwordx4 v[232:233], off
	s_waitcnt vmcnt(8)
	s_waitcnt lgkmcnt(0)
	s_barrier
	s_setprio 1
	s_waitcnt lgkmcnt(0)
	v_mfma_f32_16x16x32_bf16 v[62:65], v[168:171], v[200:203], v[62:65]
	v_mfma_f32_16x16x32_bf16 v[58:61], v[176:179], v[200:203], v[58:61]
	v_mfma_f32_16x16x32_bf16 v[46:49], v[168:171], v[208:211], v[46:49]
	v_mfma_f32_16x16x32_bf16 v[42:45], v[176:179], v[208:211], v[42:45]
	v_mfma_f32_16x16x32_bf16 v[30:33], v[168:171], v[216:219], v[30:33]
	v_mfma_f32_16x16x32_bf16 v[26:29], v[176:179], v[216:219], v[26:29]
	v_mfma_f32_16x16x32_bf16 v[14:17], v[168:171], v[224:227], v[14:17]
	v_mfma_f32_16x16x32_bf16 v[10:13], v[176:179], v[224:227], v[10:13]
	v_mfma_f32_16x16x32_bf16 v[62:65], v[172:175], v[204:207], v[62:65]
	v_mfma_f32_16x16x32_bf16 v[58:61], v[180:183], v[204:207], v[58:61]
	v_mfma_f32_16x16x32_bf16 v[46:49], v[172:175], v[212:215], v[46:49]
	v_mfma_f32_16x16x32_bf16 v[42:45], v[180:183], v[212:215], v[42:45]
	v_mfma_f32_16x16x32_bf16 v[30:33], v[172:175], v[220:223], v[30:33]
	v_mfma_f32_16x16x32_bf16 v[26:29], v[180:183], v[220:223], v[26:29]
	v_mfma_f32_16x16x32_bf16 v[14:17], v[172:175], v[228:231], v[14:17]
	v_mfma_f32_16x16x32_bf16 v[10:13], v[180:183], v[228:231], v[10:13]
	v_mfma_f32_16x16x32_bf16 v[54:57], v[184:187], v[200:203], v[54:57]
	v_mfma_f32_16x16x32_bf16 v[50:53], v[192:195], v[200:203], v[50:53]
	v_mfma_f32_16x16x32_bf16 v[38:41], v[184:187], v[208:211], v[38:41]
	v_mfma_f32_16x16x32_bf16 v[34:37], v[192:195], v[208:211], v[34:37]
	v_mfma_f32_16x16x32_bf16 v[22:25], v[184:187], v[216:219], v[22:25]
	v_mfma_f32_16x16x32_bf16 v[18:21], v[192:195], v[216:219], v[18:21]
	v_mfma_f32_16x16x32_bf16 v[6:9], v[184:187], v[224:227], v[6:9]
	v_mfma_f32_16x16x32_bf16 v[2:5], v[192:195], v[224:227], v[2:5]
	v_mfma_f32_16x16x32_bf16 v[54:57], v[188:191], v[204:207], v[54:57]
	v_mfma_f32_16x16x32_bf16 v[50:53], v[196:199], v[204:207], v[50:53]
	v_mfma_f32_16x16x32_bf16 v[38:41], v[188:191], v[212:215], v[38:41]
	v_mfma_f32_16x16x32_bf16 v[34:37], v[196:199], v[212:215], v[34:37]
	v_mfma_f32_16x16x32_bf16 v[22:25], v[188:191], v[220:223], v[22:25]
	v_mfma_f32_16x16x32_bf16 v[18:21], v[196:199], v[220:223], v[18:21]
	v_mfma_f32_16x16x32_bf16 v[6:9], v[188:191], v[228:231], v[6:9]
	v_mfma_f32_16x16x32_bf16 v[2:5], v[196:199], v[228:231], v[2:5]
	s_setprio 0
	s_barrier
	s_add_i32 s7, s7, 2
	v_lshl_add_u64 v[154:155], v[154:155], 0, s[20:21]
	s_cmp_gt_u32 s7, 13
	v_lshl_add_u64 v[156:157], v[156:157], 0, s[20:21]
	s_cbranch_scc0 .LBB0_213

.LBB0_675:
	s_ashr_i32 s45, s44, 31
	s_lshl_b64 s[8:9], s[44:45], 19
	s_ashr_i32 s43, s42, 31
	v_lshl_add_u64 v[162:163], v[146:147], 0, s[8:9]
	s_lshl_b64 s[8:9], s[42:43], 19
	v_lshl_add_u64 v[164:165], v[140:141], 0, s[8:9]
	v_cndmask_b32_e64 v132, v2, v164, s[4:5]
	v_lshl_add_u64 v[136:137], v[2:3], 0, s[36:37]
	v_mov_b32_e32 v2, 0
	v_cndmask_b32_e64 v1, v5, v163, s[4:5]
	v_cndmask_b32_e64 v130, v4, v162, s[4:5]
	v_cndmask_b32_e64 v131, v3, v165, s[4:5]
	v_lshl_add_u64 v[134:135], v[4:5], 0, s[26:27]
	s_mov_b32 s3, -2
	ds_read_b128 v[168:171], v180
	ds_read_b128 v[172:175], v180 offset:1024
	ds_read_b128 v[184:187], v180 offset:2048
	ds_read_b128 v[188:191], v180 offset:3072
	ds_read_b128 v[192:195], v181
	ds_read_b128 v[200:203], v181 offset:1024
	ds_read_b128 v[204:207], v181 offset:2048
	ds_read_b128 v[208:211], v181 offset:3072
	s_cmp_eq_u32 s3, 12
	v_lshl_add_u64 v[196:197], v[134:135], 0, s[38:39]
	s_cselect_b64 vcc, -1, 0
	v_cndmask_b32_e32 v197, v197, v1, vcc
	v_cndmask_b32_e32 v196, v196, v130, vcc
	v_cndmask_b32_e32 v245, v137, v131, vcc
	v_cndmask_b32_e32 v244, v136, v132, vcc
	s_mov_b32 m0, s56
	v_lshl_add_u64 v[246:247], v[134:135], 0, v[156:157]
	ds_read_b128 v[212:215], v178
	ds_read_b128 v[216:219], v178 offset:1024
	ds_read_b128 v[220:223], v178 offset:2048
	ds_read_b128 v[224:227], v178 offset:3072
	ds_read_b128 v[228:231], v178 offset:4096
	ds_read_b128 v[232:235], v178 offset:5120
	ds_read_b128 v[236:239], v178 offset:6144
	ds_read_b128 v[240:243], v178 offset:7168
	global_load_lds_dwordx4 v[246:247], off
	v_lshl_add_u64 v[246:247], v[134:135], 0, v[158:159]
	s_mov_b32 m0, s57
	s_nop 0
	global_load_lds_dwordx4 v[246:247], off
	s_waitcnt vmcnt(8)
	s_waitcnt lgkmcnt(0)
	s_barrier
	s_setprio 1
	s_waitcnt lgkmcnt(0)
	v_mfma_f32_16x16x32_bf16 v[126:129], v[168:171], v[212:215], 0
	v_mfma_f32_16x16x32_bf16 v[122:125], v[184:187], v[212:215], 0
	v_mfma_f32_16x16x32_bf16 v[110:113], v[168:171], v[220:223], 0
	v_mfma_f32_16x16x32_bf16 v[106:109], v[184:187], v[220:223], 0
	v_mfma_f32_16x16x32_bf16 v[94:97], v[168:171], v[228:231], 0
	v_mfma_f32_16x16x32_bf16 v[90:93], v[184:187], v[228:231], 0
	v_mfma_f32_16x16x32_bf16 v[78:81], v[168:171], v[236:239], 0
	v_mfma_f32_16x16x32_bf16 v[74:77], v[184:187], v[236:239], 0
	v_mfma_f32_16x16x32_bf16 v[126:129], v[172:175], v[216:219], v[126:129]
	v_mfma_f32_16x16x32_bf16 v[122:125], v[188:191], v[216:219], v[122:125]
	v_mfma_f32_16x16x32_bf16 v[110:113], v[172:175], v[224:227], v[110:113]
	v_mfma_f32_16x16x32_bf16 v[106:109], v[188:191], v[224:227], v[106:109]
	v_mfma_f32_16x16x32_bf16 v[94:97], v[172:175], v[232:235], v[94:97]
	v_mfma_f32_16x16x32_bf16 v[90:93], v[188:191], v[232:235], v[90:93]
	v_mfma_f32_16x16x32_bf16 v[78:81], v[172:175], v[240:243], v[78:81]
	v_mfma_f32_16x16x32_bf16 v[74:77], v[188:191], v[240:243], v[74:77]
	v_mfma_f32_16x16x32_bf16 v[118:121], v[192:195], v[212:215], 0
	v_mfma_f32_16x16x32_bf16 v[114:117], v[204:207], v[212:215], 0
	v_mfma_f32_16x16x32_bf16 v[102:105], v[192:195], v[220:223], 0
	v_mfma_f32_16x16x32_bf16 v[98:101], v[204:207], v[220:223], 0
	v_mfma_f32_16x16x32_bf16 v[86:89], v[192:195], v[228:231], 0
	v_mfma_f32_16x16x32_bf16 v[82:85], v[204:207], v[228:231], 0
	v_mfma_f32_16x16x32_bf16 v[70:73], v[192:195], v[236:239], 0
	v_mfma_f32_16x16x32_bf16 v[66:69], v[204:207], v[236:239], 0
	v_mfma_f32_16x16x32_bf16 v[118:121], v[200:203], v[216:219], v[118:121]
	v_mfma_f32_16x16x32_bf16 v[114:117], v[208:211], v[216:219], v[114:117]
	v_mfma_f32_16x16x32_bf16 v[102:105], v[200:203], v[224:227], v[102:105]
	v_mfma_f32_16x16x32_bf16 v[98:101], v[208:211], v[224:227], v[98:101]
	v_mfma_f32_16x16x32_bf16 v[86:89], v[200:203], v[232:235], v[86:89]
	v_mfma_f32_16x16x32_bf16 v[82:85], v[208:211], v[232:235], v[82:85]
	v_mfma_f32_16x16x32_bf16 v[70:73], v[200:203], v[240:243], v[70:73]
	v_mfma_f32_16x16x32_bf16 v[66:69], v[208:211], v[240:243], v[66:69]
	s_setprio 0
	s_barrier
	s_mov_b32 m0, s58
	v_lshl_add_u64 v[246:247], v[244:245], 0, v[142:143]
	ds_read_b128 v[212:215], v178 offset:16384
	ds_read_b128 v[216:219], v178 offset:17408
	ds_read_b128 v[220:223], v178 offset:18432
	ds_read_b128 v[224:227], v178 offset:19456
	ds_read_b128 v[228:231], v178 offset:20480
	ds_read_b128 v[232:235], v178 offset:21504
	ds_read_b128 v[236:239], v178 offset:22528
	ds_read_b128 v[240:243], v178 offset:23552
	global_load_lds_dwordx4 v[246:247], off
	v_lshl_add_u64 v[248:249], v[244:245], 0, v[144:145]
	s_add_i32 m0, s58, 0x2000
	v_lshl_add_u64 v[250:251], v[244:245], 0, s[16:17]
	s_add_i32 s7, s55, s0
	global_load_lds_dwordx4 v[248:249], off
	v_lshl_add_u64 v[252:253], v[250:251], 0, v[142:143]
	s_mov_b32 m0, s7
	v_lshl_add_u64 v[250:251], v[250:251], 0, v[144:145]
	global_load_lds_dwordx4 v[252:253], off
	s_add_i32 m0, s7, 0x2000
	v_lshl_add_u64 v[252:253], v[196:197], 0, v[144:145]
	global_load_lds_dwordx4 v[250:251], off
	v_lshl_add_u64 v[250:251], v[196:197], 0, v[142:143]
	s_mov_b32 m0, s1
	s_nop 0
	global_load_lds_dwordx4 v[250:251], off
	s_mov_b32 m0, s2
	s_nop 0
	global_load_lds_dwordx4 v[252:253], off
	s_waitcnt vmcnt(8)
	s_waitcnt lgkmcnt(0)
	s_barrier
	s_setprio 1
	s_waitcnt lgkmcnt(0)
	v_mfma_f32_16x16x32_bf16 v[62:65], v[168:171], v[212:215], 0
	v_mfma_f32_16x16x32_bf16 v[58:61], v[184:187], v[212:215], 0
	v_mfma_f32_16x16x32_bf16 v[46:49], v[168:171], v[220:223], 0
	v_mfma_f32_16x16x32_bf16 v[42:45], v[184:187], v[220:223], 0
	v_mfma_f32_16x16x32_bf16 v[30:33], v[168:171], v[228:231], 0
	v_mfma_f32_16x16x32_bf16 v[26:29], v[184:187], v[228:231], 0
	v_mfma_f32_16x16x32_bf16 v[14:17], v[168:171], v[236:239], 0
	v_mfma_f32_16x16x32_bf16 v[10:13], v[184:187], v[236:239], 0
	v_mfma_f32_16x16x32_bf16 v[62:65], v[172:175], v[216:219], v[62:65]
	v_mfma_f32_16x16x32_bf16 v[58:61], v[188:191], v[216:219], v[58:61]
	v_mfma_f32_16x16x32_bf16 v[46:49], v[172:175], v[224:227], v[46:49]
	v_mfma_f32_16x16x32_bf16 v[42:45], v[188:191], v[224:227], v[42:45]
	v_mfma_f32_16x16x32_bf16 v[30:33], v[172:175], v[232:235], v[30:33]
	v_mfma_f32_16x16x32_bf16 v[26:29], v[188:191], v[232:235], v[26:29]
	v_mfma_f32_16x16x32_bf16 v[14:17], v[172:175], v[240:243], v[14:17]
	v_mfma_f32_16x16x32_bf16 v[10:13], v[188:191], v[240:243], v[10:13]
	v_mfma_f32_16x16x32_bf16 v[54:57], v[192:195], v[212:215], 0
	v_mfma_f32_16x16x32_bf16 v[50:53], v[204:207], v[212:215], 0
	v_mfma_f32_16x16x32_bf16 v[38:41], v[192:195], v[220:223], 0
	v_mfma_f32_16x16x32_bf16 v[34:37], v[204:207], v[220:223], 0
	v_mfma_f32_16x16x32_bf16 v[22:25], v[192:195], v[228:231], 0
	v_mfma_f32_16x16x32_bf16 v[18:21], v[204:207], v[228:231], 0
	v_mfma_f32_16x16x32_bf16 v[6:9], v[192:195], v[236:239], 0
	v_mfma_f32_16x16x32_bf16 v[2:5], v[204:207], v[236:239], 0
	v_mfma_f32_16x16x32_bf16 v[54:57], v[200:203], v[216:219], v[54:57]
	v_mfma_f32_16x16x32_bf16 v[50:53], v[208:211], v[216:219], v[50:53]
	v_mfma_f32_16x16x32_bf16 v[38:41], v[200:203], v[224:227], v[38:41]
	v_mfma_f32_16x16x32_bf16 v[34:37], v[208:211], v[224:227], v[34:37]
	v_mfma_f32_16x16x32_bf16 v[22:25], v[200:203], v[232:235], v[22:25]
	v_mfma_f32_16x16x32_bf16 v[18:21], v[208:211], v[232:235], v[18:21]
	v_mfma_f32_16x16x32_bf16 v[6:9], v[200:203], v[240:243], v[6:9]
	v_mfma_f32_16x16x32_bf16 v[2:5], v[208:211], v[240:243], v[2:5]
	s_setprio 0
	s_barrier
	s_add_i32 s7, 0, 0x18000
	v_add_u32_e32 v133, s7, v177
	s_add_i32 s8, 0, 0x1c000
	ds_read_b128 v[168:171], v133
	ds_read_b128 v[172:175], v133 offset:1024
	ds_read_b128 v[184:187], v133 offset:2048
	ds_read_b128 v[188:191], v133 offset:3072
	v_add_u32_e32 v133, s8, v177
	ds_read_b128 v[192:195], v133
	ds_read_b128 v[200:203], v133 offset:1024
	ds_read_b128 v[204:207], v133 offset:2048
	ds_read_b128 v[208:211], v133 offset:3072
	v_lshl_add_u64 v[196:197], v[196:197], 0, s[16:17]
	s_mov_b32 m0, s33
	v_lshl_add_u64 v[198:199], v[196:197], 0, v[142:143]
	ds_read_b128 v[212:215], v178 offset:32768
	ds_read_b128 v[216:219], v178 offset:33792
	ds_read_b128 v[220:223], v178 offset:34816
	ds_read_b128 v[224:227], v178 offset:35840
	ds_read_b128 v[228:231], v178 offset:36864
	ds_read_b128 v[232:235], v178 offset:37888
	ds_read_b128 v[236:239], v178 offset:38912
	ds_read_b128 v[240:243], v178 offset:39936
	global_load_lds_dwordx4 v[198:199], off
	v_lshl_add_u64 v[196:197], v[196:197], 0, v[144:145]
	s_mov_b32 m0, s34
	s_nop 0
	global_load_lds_dwordx4 v[196:197], off
	s_waitcnt vmcnt(8)
	s_waitcnt lgkmcnt(0)
	s_barrier
	s_setprio 1
	s_waitcnt lgkmcnt(0)
	v_mfma_f32_16x16x32_bf16 v[126:129], v[168:171], v[212:215], v[126:129]
	v_mfma_f32_16x16x32_bf16 v[122:125], v[184:187], v[212:215], v[122:125]
	v_mfma_f32_16x16x32_bf16 v[110:113], v[168:171], v[220:223], v[110:113]
	v_mfma_f32_16x16x32_bf16 v[106:109], v[184:187], v[220:223], v[106:109]
	v_mfma_f32_16x16x32_bf16 v[94:97], v[168:171], v[228:231], v[94:97]
	v_mfma_f32_16x16x32_bf16 v[90:93], v[184:187], v[228:231], v[90:93]
	v_mfma_f32_16x16x32_bf16 v[78:81], v[168:171], v[236:239], v[78:81]
	v_mfma_f32_16x16x32_bf16 v[74:77], v[184:187], v[236:239], v[74:77]
	v_mfma_f32_16x16x32_bf16 v[126:129], v[172:175], v[216:219], v[126:129]
	v_mfma_f32_16x16x32_bf16 v[122:125], v[188:191], v[216:219], v[122:125]
	v_mfma_f32_16x16x32_bf16 v[110:113], v[172:175], v[224:227], v[110:113]
	v_mfma_f32_16x16x32_bf16 v[106:109], v[188:191], v[224:227], v[106:109]
	v_mfma_f32_16x16x32_bf16 v[94:97], v[172:175], v[232:235], v[94:97]
	v_mfma_f32_16x16x32_bf16 v[90:93], v[188:191], v[232:235], v[90:93]
	v_mfma_f32_16x16x32_bf16 v[78:81], v[172:175], v[240:243], v[78:81]
	v_mfma_f32_16x16x32_bf16 v[74:77], v[188:191], v[240:243], v[74:77]
	v_mfma_f32_16x16x32_bf16 v[118:121], v[192:195], v[212:215], v[118:121]
	v_mfma_f32_16x16x32_bf16 v[114:117], v[204:207], v[212:215], v[114:117]
	v_mfma_f32_16x16x32_bf16 v[102:105], v[192:195], v[220:223], v[102:105]
	v_mfma_f32_16x16x32_bf16 v[98:101], v[204:207], v[220:223], v[98:101]
	v_mfma_f32_16x16x32_bf16 v[86:89], v[192:195], v[228:231], v[86:89]
	v_mfma_f32_16x16x32_bf16 v[82:85], v[204:207], v[228:231], v[82:85]
	v_mfma_f32_16x16x32_bf16 v[70:73], v[192:195], v[236:239], v[70:73]
	v_mfma_f32_16x16x32_bf16 v[66:69], v[204:207], v[236:239], v[66:69]
	v_mfma_f32_16x16x32_bf16 v[118:121], v[200:203], v[216:219], v[118:121]
	v_mfma_f32_16x16x32_bf16 v[114:117], v[208:211], v[216:219], v[114:117]
	v_mfma_f32_16x16x32_bf16 v[102:105], v[200:203], v[224:227], v[102:105]
	v_mfma_f32_16x16x32_bf16 v[98:101], v[208:211], v[224:227], v[98:101]
	v_mfma_f32_16x16x32_bf16 v[86:89], v[200:203], v[232:235], v[86:89]
	v_mfma_f32_16x16x32_bf16 v[82:85], v[208:211], v[232:235], v[82:85]
	v_mfma_f32_16x16x32_bf16 v[70:73], v[200:203], v[240:243], v[70:73]
	v_mfma_f32_16x16x32_bf16 v[66:69], v[208:211], v[240:243], v[66:69]
	s_setprio 0
	s_barrier
	s_add_i32 s7, s7, s0
	v_lshl_add_u64 v[196:197], v[246:247], 0, s[24:25]
	s_mov_b32 m0, s7
	ds_read_b128 v[212:215], v178 offset:49152
	ds_read_b128 v[216:219], v178 offset:50176
	ds_read_b128 v[220:223], v178 offset:51200
	ds_read_b128 v[224:227], v178 offset:52224
	ds_read_b128 v[228:231], v178 offset:53248
	ds_read_b128 v[232:235], v178 offset:54272
	ds_read_b128 v[236:239], v178 offset:55296
	ds_read_b128 v[240:243], v178 offset:56320
	global_load_lds_dwordx4 v[196:197], off
	v_lshl_add_u64 v[196:197], v[248:249], 0, s[24:25]
	s_add_i32 m0, s7, 0x2000
	s_add_i32 s7, s8, s0
	global_load_lds_dwordx4 v[196:197], off
	v_lshl_add_u64 v[196:197], v[244:245], 0, s[26:27]
	v_lshl_add_u64 v[198:199], v[196:197], 0, v[142:143]
	s_mov_b32 m0, s7
	v_lshl_add_u64 v[196:197], v[196:197], 0, v[144:145]
	global_load_lds_dwordx4 v[198:199], off
	s_add_i32 m0, s7, 0x2000
	s_nop 0
	global_load_lds_dwordx4 v[196:197], off
	v_lshl_add_u64 v[196:197], v[250:251], 0, s[24:25]
	s_mov_b32 m0, s49
	s_nop 0
	global_load_lds_dwordx4 v[196:197], off
	v_lshl_add_u64 v[196:197], v[252:253], 0, s[24:25]
	s_mov_b32 m0, s50
	s_nop 0
	global_load_lds_dwordx4 v[196:197], off
	s_waitcnt vmcnt(8)
	s_waitcnt lgkmcnt(0)
	s_barrier
	s_setprio 1
	s_waitcnt lgkmcnt(0)
	v_mfma_f32_16x16x32_bf16 v[62:65], v[168:171], v[212:215], v[62:65]
	v_mfma_f32_16x16x32_bf16 v[58:61], v[184:187], v[212:215], v[58:61]
	v_mfma_f32_16x16x32_bf16 v[46:49], v[168:171], v[220:223], v[46:49]
	v_mfma_f32_16x16x32_bf16 v[42:45], v[184:187], v[220:223], v[42:45]
	v_mfma_f32_16x16x32_bf16 v[30:33], v[168:171], v[228:231], v[30:33]
	v_mfma_f32_16x16x32_bf16 v[26:29], v[184:187], v[228:231], v[26:29]
	v_mfma_f32_16x16x32_bf16 v[14:17], v[168:171], v[236:239], v[14:17]
	v_mfma_f32_16x16x32_bf16 v[10:13], v[184:187], v[236:239], v[10:13]
	v_mfma_f32_16x16x32_bf16 v[62:65], v[172:175], v[216:219], v[62:65]
	v_mfma_f32_16x16x32_bf16 v[58:61], v[188:191], v[216:219], v[58:61]
	v_mfma_f32_16x16x32_bf16 v[46:49], v[172:175], v[224:227], v[46:49]
	v_mfma_f32_16x16x32_bf16 v[42:45], v[188:191], v[224:227], v[42:45]
	v_mfma_f32_16x16x32_bf16 v[30:33], v[172:175], v[232:235], v[30:33]
	v_mfma_f32_16x16x32_bf16 v[26:29], v[188:191], v[232:235], v[26:29]
	v_mfma_f32_16x16x32_bf16 v[14:17], v[172:175], v[240:243], v[14:17]
	v_mfma_f32_16x16x32_bf16 v[10:13], v[188:191], v[240:243], v[10:13]
	v_mfma_f32_16x16x32_bf16 v[54:57], v[192:195], v[212:215], v[54:57]
	v_mfma_f32_16x16x32_bf16 v[50:53], v[204:207], v[212:215], v[50:53]
	v_mfma_f32_16x16x32_bf16 v[38:41], v[192:195], v[220:223], v[38:41]
	v_mfma_f32_16x16x32_bf16 v[34:37], v[204:207], v[220:223], v[34:37]
	v_mfma_f32_16x16x32_bf16 v[22:25], v[192:195], v[228:231], v[22:25]
	v_mfma_f32_16x16x32_bf16 v[18:21], v[204:207], v[228:231], v[18:21]
	v_mfma_f32_16x16x32_bf16 v[6:9], v[192:195], v[236:239], v[6:9]
	v_mfma_f32_16x16x32_bf16 v[2:5], v[204:207], v[236:239], v[2:5]
	v_mfma_f32_16x16x32_bf16 v[54:57], v[200:203], v[216:219], v[54:57]
	v_mfma_f32_16x16x32_bf16 v[50:53], v[208:211], v[216:219], v[50:53]
	v_mfma_f32_16x16x32_bf16 v[38:41], v[200:203], v[224:227], v[38:41]
	v_mfma_f32_16x16x32_bf16 v[34:37], v[208:211], v[224:227], v[34:37]
	v_mfma_f32_16x16x32_bf16 v[22:25], v[200:203], v[232:235], v[22:25]
	v_mfma_f32_16x16x32_bf16 v[18:21], v[208:211], v[232:235], v[18:21]
	v_mfma_f32_16x16x32_bf16 v[6:9], v[200:203], v[240:243], v[6:9]
	v_mfma_f32_16x16x32_bf16 v[2:5], v[208:211], v[240:243], v[2:5]
	s_setprio 0
	s_barrier
	s_add_i32 s3, s3, 2
	v_lshl_add_u64 v[134:135], v[134:135], 0, s[36:37]
	s_cmp_gt_u32 s3, 13
	v_lshl_add_u64 v[136:137], v[136:137], 0, s[36:37]
	s_cbranch_scc0 .LBB0_676
	s_branch .Lpeel_exit_2
.LBB0_676:
	ds_read_b128 v[168:171], v180
	ds_read_b128 v[172:175], v180 offset:1024
	ds_read_b128 v[184:187], v180 offset:2048
	ds_read_b128 v[188:191], v180 offset:3072
	ds_read_b128 v[192:195], v181
	ds_read_b128 v[200:203], v181 offset:1024
	ds_read_b128 v[204:207], v181 offset:2048
	ds_read_b128 v[208:211], v181 offset:3072
	s_cmp_eq_u32 s3, 12
	v_lshl_add_u64 v[196:197], v[134:135], 0, s[38:39]
	s_cselect_b64 vcc, -1, 0
	v_cndmask_b32_e32 v197, v197, v1, vcc
	v_cndmask_b32_e32 v196, v196, v130, vcc
	v_cndmask_b32_e32 v245, v137, v131, vcc
	v_cndmask_b32_e32 v244, v136, v132, vcc
	s_mov_b32 m0, s56
	v_lshl_add_u64 v[246:247], v[134:135], 0, v[156:157]
	ds_read_b128 v[212:215], v178
	ds_read_b128 v[216:219], v178 offset:1024
	ds_read_b128 v[220:223], v178 offset:2048
	ds_read_b128 v[224:227], v178 offset:3072
	ds_read_b128 v[228:231], v178 offset:4096
	ds_read_b128 v[232:235], v178 offset:5120
	ds_read_b128 v[236:239], v178 offset:6144
	ds_read_b128 v[240:243], v178 offset:7168
	global_load_lds_dwordx4 v[246:247], off
	v_lshl_add_u64 v[246:247], v[134:135], 0, v[158:159]
	s_mov_b32 m0, s57
	s_nop 0
	global_load_lds_dwordx4 v[246:247], off
	s_waitcnt vmcnt(8)
	s_waitcnt lgkmcnt(0)
	s_barrier
	s_setprio 1
	s_waitcnt lgkmcnt(0)
	v_mfma_f32_16x16x32_bf16 v[126:129], v[168:171], v[212:215], v[126:129]
	v_mfma_f32_16x16x32_bf16 v[122:125], v[184:187], v[212:215], v[122:125]
	v_mfma_f32_16x16x32_bf16 v[110:113], v[168:171], v[220:223], v[110:113]
	v_mfma_f32_16x16x32_bf16 v[106:109], v[184:187], v[220:223], v[106:109]
	v_mfma_f32_16x16x32_bf16 v[94:97], v[168:171], v[228:231], v[94:97]
	v_mfma_f32_16x16x32_bf16 v[90:93], v[184:187], v[228:231], v[90:93]
	v_mfma_f32_16x16x32_bf16 v[78:81], v[168:171], v[236:239], v[78:81]
	v_mfma_f32_16x16x32_bf16 v[74:77], v[184:187], v[236:239], v[74:77]
	v_mfma_f32_16x16x32_bf16 v[126:129], v[172:175], v[216:219], v[126:129]
	v_mfma_f32_16x16x32_bf16 v[122:125], v[188:191], v[216:219], v[122:125]
	v_mfma_f32_16x16x32_bf16 v[110:113], v[172:175], v[224:227], v[110:113]
	v_mfma_f32_16x16x32_bf16 v[106:109], v[188:191], v[224:227], v[106:109]
	v_mfma_f32_16x16x32_bf16 v[94:97], v[172:175], v[232:235], v[94:97]
	v_mfma_f32_16x16x32_bf16 v[90:93], v[188:191], v[232:235], v[90:93]
	v_mfma_f32_16x16x32_bf16 v[78:81], v[172:175], v[240:243], v[78:81]
	v_mfma_f32_16x16x32_bf16 v[74:77], v[188:191], v[240:243], v[74:77]
	v_mfma_f32_16x16x32_bf16 v[118:121], v[192:195], v[212:215], v[118:121]
	v_mfma_f32_16x16x32_bf16 v[114:117], v[204:207], v[212:215], v[114:117]
	v_mfma_f32_16x16x32_bf16 v[102:105], v[192:195], v[220:223], v[102:105]
	v_mfma_f32_16x16x32_bf16 v[98:101], v[204:207], v[220:223], v[98:101]
	v_mfma_f32_16x16x32_bf16 v[86:89], v[192:195], v[228:231], v[86:89]
	v_mfma_f32_16x16x32_bf16 v[82:85], v[204:207], v[228:231], v[82:85]
	v_mfma_f32_16x16x32_bf16 v[70:73], v[192:195], v[236:239], v[70:73]
	v_mfma_f32_16x16x32_bf16 v[66:69], v[204:207], v[236:239], v[66:69]
	v_mfma_f32_16x16x32_bf16 v[118:121], v[200:203], v[216:219], v[118:121]
	v_mfma_f32_16x16x32_bf16 v[114:117], v[208:211], v[216:219], v[114:117]
	v_mfma_f32_16x16x32_bf16 v[102:105], v[200:203], v[224:227], v[102:105]
	v_mfma_f32_16x16x32_bf16 v[98:101], v[208:211], v[224:227], v[98:101]
	v_mfma_f32_16x16x32_bf16 v[86:89], v[200:203], v[232:235], v[86:89]
	v_mfma_f32_16x16x32_bf16 v[82:85], v[208:211], v[232:235], v[82:85]
	v_mfma_f32_16x16x32_bf16 v[70:73], v[200:203], v[240:243], v[70:73]
	v_mfma_f32_16x16x32_bf16 v[66:69], v[208:211], v[240:243], v[66:69]
	s_setprio 0
	s_barrier
	s_mov_b32 m0, s58
	v_lshl_add_u64 v[246:247], v[244:245], 0, v[142:143]
	ds_read_b128 v[212:215], v178 offset:16384
	ds_read_b128 v[216:219], v178 offset:17408
	ds_read_b128 v[220:223], v178 offset:18432
	ds_read_b128 v[224:227], v178 offset:19456
	ds_read_b128 v[228:231], v178 offset:20480
	ds_read_b128 v[232:235], v178 offset:21504
	ds_read_b128 v[236:239], v178 offset:22528
	ds_read_b128 v[240:243], v178 offset:23552
	global_load_lds_dwordx4 v[246:247], off
	v_lshl_add_u64 v[248:249], v[244:245], 0, v[144:145]
	s_add_i32 m0, s58, 0x2000
	v_lshl_add_u64 v[250:251], v[244:245], 0, s[16:17]
	s_add_i32 s7, s55, s0
	global_load_lds_dwordx4 v[248:249], off
	v_lshl_add_u64 v[252:253], v[250:251], 0, v[142:143]
	s_mov_b32 m0, s7
	v_lshl_add_u64 v[250:251], v[250:251], 0, v[144:145]
	global_load_lds_dwordx4 v[252:253], off
	s_add_i32 m0, s7, 0x2000
	v_lshl_add_u64 v[252:253], v[196:197], 0, v[144:145]
	global_load_lds_dwordx4 v[250:251], off
	v_lshl_add_u64 v[250:251], v[196:197], 0, v[142:143]
	s_mov_b32 m0, s1
	s_nop 0
	global_load_lds_dwordx4 v[250:251], off
	s_mov_b32 m0, s2
	s_nop 0
	global_load_lds_dwordx4 v[252:253], off
	s_waitcnt vmcnt(8)
	s_waitcnt lgkmcnt(0)
	s_barrier
	s_setprio 1
	s_waitcnt lgkmcnt(0)
	v_mfma_f32_16x16x32_bf16 v[62:65], v[168:171], v[212:215], v[62:65]
	v_mfma_f32_16x16x32_bf16 v[58:61], v[184:187], v[212:215], v[58:61]
	v_mfma_f32_16x16x32_bf16 v[46:49], v[168:171], v[220:223], v[46:49]
	v_mfma_f32_16x16x32_bf16 v[42:45], v[184:187], v[220:223], v[42:45]
	v_mfma_f32_16x16x32_bf16 v[30:33], v[168:171], v[228:231], v[30:33]
	v_mfma_f32_16x16x32_bf16 v[26:29], v[184:187], v[228:231], v[26:29]
	v_mfma_f32_16x16x32_bf16 v[14:17], v[168:171], v[236:239], v[14:17]
	v_mfma_f32_16x16x32_bf16 v[10:13], v[184:187], v[236:239], v[10:13]
	v_mfma_f32_16x16x32_bf16 v[62:65], v[172:175], v[216:219], v[62:65]
	v_mfma_f32_16x16x32_bf16 v[58:61], v[188:191], v[216:219], v[58:61]
	v_mfma_f32_16x16x32_bf16 v[46:49], v[172:175], v[224:227], v[46:49]
	v_mfma_f32_16x16x32_bf16 v[42:45], v[188:191], v[224:227], v[42:45]
	v_mfma_f32_16x16x32_bf16 v[30:33], v[172:175], v[232:235], v[30:33]
	v_mfma_f32_16x16x32_bf16 v[26:29], v[188:191], v[232:235], v[26:29]
	v_mfma_f32_16x16x32_bf16 v[14:17], v[172:175], v[240:243], v[14:17]
	v_mfma_f32_16x16x32_bf16 v[10:13], v[188:191], v[240:243], v[10:13]
	v_mfma_f32_16x16x32_bf16 v[54:57], v[192:195], v[212:215], v[54:57]
	v_mfma_f32_16x16x32_bf16 v[50:53], v[204:207], v[212:215], v[50:53]
	v_mfma_f32_16x16x32_bf16 v[38:41], v[192:195], v[220:223], v[38:41]
	v_mfma_f32_16x16x32_bf16 v[34:37], v[204:207], v[220:223], v[34:37]
	v_mfma_f32_16x16x32_bf16 v[22:25], v[192:195], v[228:231], v[22:25]
	v_mfma_f32_16x16x32_bf16 v[18:21], v[204:207], v[228:231], v[18:21]
	v_mfma_f32_16x16x32_bf16 v[6:9], v[192:195], v[236:239], v[6:9]
	v_mfma_f32_16x16x32_bf16 v[2:5], v[204:207], v[236:239], v[2:5]
	v_mfma_f32_16x16x32_bf16 v[54:57], v[200:203], v[216:219], v[54:57]
	v_mfma_f32_16x16x32_bf16 v[50:53], v[208:211], v[216:219], v[50:53]
	v_mfma_f32_16x16x32_bf16 v[38:41], v[200:203], v[224:227], v[38:41]
	v_mfma_f32_16x16x32_bf16 v[34:37], v[208:211], v[224:227], v[34:37]
	v_mfma_f32_16x16x32_bf16 v[22:25], v[200:203], v[232:235], v[22:25]
	v_mfma_f32_16x16x32_bf16 v[18:21], v[208:211], v[232:235], v[18:21]
	v_mfma_f32_16x16x32_bf16 v[6:9], v[200:203], v[240:243], v[6:9]
	v_mfma_f32_16x16x32_bf16 v[2:5], v[208:211], v[240:243], v[2:5]
	s_setprio 0
	s_barrier
	s_add_i32 s7, 0, 0x18000
	v_add_u32_e32 v133, s7, v177
	s_add_i32 s8, 0, 0x1c000
	ds_read_b128 v[168:171], v133
	ds_read_b128 v[172:175], v133 offset:1024
	ds_read_b128 v[184:187], v133 offset:2048
	ds_read_b128 v[188:191], v133 offset:3072
	v_add_u32_e32 v133, s8, v177
	ds_read_b128 v[192:195], v133
	ds_read_b128 v[200:203], v133 offset:1024
	ds_read_b128 v[204:207], v133 offset:2048
	ds_read_b128 v[208:211], v133 offset:3072
	v_lshl_add_u64 v[196:197], v[196:197], 0, s[16:17]
	s_mov_b32 m0, s33
	v_lshl_add_u64 v[198:199], v[196:197], 0, v[142:143]
	ds_read_b128 v[212:215], v178 offset:32768
	ds_read_b128 v[216:219], v178 offset:33792
	ds_read_b128 v[220:223], v178 offset:34816
	ds_read_b128 v[224:227], v178 offset:35840
	ds_read_b128 v[228:231], v178 offset:36864
	ds_read_b128 v[232:235], v178 offset:37888
	ds_read_b128 v[236:239], v178 offset:38912
	ds_read_b128 v[240:243], v178 offset:39936
	global_load_lds_dwordx4 v[198:199], off
	v_lshl_add_u64 v[196:197], v[196:197], 0, v[144:145]
	s_mov_b32 m0, s34
	s_nop 0
	global_load_lds_dwordx4 v[196:197], off
	s_waitcnt vmcnt(8)
	s_waitcnt lgkmcnt(0)
	s_barrier
	s_setprio 1
	s_waitcnt lgkmcnt(0)
	v_mfma_f32_16x16x32_bf16 v[126:129], v[168:171], v[212:215], v[126:129]
	v_mfma_f32_16x16x32_bf16 v[122:125], v[184:187], v[212:215], v[122:125]
	v_mfma_f32_16x16x32_bf16 v[110:113], v[168:171], v[220:223], v[110:113]
	v_mfma_f32_16x16x32_bf16 v[106:109], v[184:187], v[220:223], v[106:109]
	v_mfma_f32_16x16x32_bf16 v[94:97], v[168:171], v[228:231], v[94:97]
	v_mfma_f32_16x16x32_bf16 v[90:93], v[184:187], v[228:231], v[90:93]
	v_mfma_f32_16x16x32_bf16 v[78:81], v[168:171], v[236:239], v[78:81]
	v_mfma_f32_16x16x32_bf16 v[74:77], v[184:187], v[236:239], v[74:77]
	v_mfma_f32_16x16x32_bf16 v[126:129], v[172:175], v[216:219], v[126:129]
	v_mfma_f32_16x16x32_bf16 v[122:125], v[188:191], v[216:219], v[122:125]
	v_mfma_f32_16x16x32_bf16 v[110:113], v[172:175], v[224:227], v[110:113]
	v_mfma_f32_16x16x32_bf16 v[106:109], v[188:191], v[224:227], v[106:109]
	v_mfma_f32_16x16x32_bf16 v[94:97], v[172:175], v[232:235], v[94:97]
	v_mfma_f32_16x16x32_bf16 v[90:93], v[188:191], v[232:235], v[90:93]
	v_mfma_f32_16x16x32_bf16 v[78:81], v[172:175], v[240:243], v[78:81]
	v_mfma_f32_16x16x32_bf16 v[74:77], v[188:191], v[240:243], v[74:77]
	v_mfma_f32_16x16x32_bf16 v[118:121], v[192:195], v[212:215], v[118:121]
	v_mfma_f32_16x16x32_bf16 v[114:117], v[204:207], v[212:215], v[114:117]
	v_mfma_f32_16x16x32_bf16 v[102:105], v[192:195], v[220:223], v[102:105]
	v_mfma_f32_16x16x32_bf16 v[98:101], v[204:207], v[220:223], v[98:101]
	v_mfma_f32_16x16x32_bf16 v[86:89], v[192:195], v[228:231], v[86:89]
	v_mfma_f32_16x16x32_bf16 v[82:85], v[204:207], v[228:231], v[82:85]
	v_mfma_f32_16x16x32_bf16 v[70:73], v[192:195], v[236:239], v[70:73]
	v_mfma_f32_16x16x32_bf16 v[66:69], v[204:207], v[236:239], v[66:69]
	v_mfma_f32_16x16x32_bf16 v[118:121], v[200:203], v[216:219], v[118:121]
	v_mfma_f32_16x16x32_bf16 v[114:117], v[208:211], v[216:219], v[114:117]
	v_mfma_f32_16x16x32_bf16 v[102:105], v[200:203], v[224:227], v[102:105]
	v_mfma_f32_16x16x32_bf16 v[98:101], v[208:211], v[224:227], v[98:101]
	v_mfma_f32_16x16x32_bf16 v[86:89], v[200:203], v[232:235], v[86:89]
	v_mfma_f32_16x16x32_bf16 v[82:85], v[208:211], v[232:235], v[82:85]
	v_mfma_f32_16x16x32_bf16 v[70:73], v[200:203], v[240:243], v[70:73]
	v_mfma_f32_16x16x32_bf16 v[66:69], v[208:211], v[240:243], v[66:69]
	s_setprio 0
	s_barrier
	s_add_i32 s7, s7, s0
	v_lshl_add_u64 v[196:197], v[246:247], 0, s[24:25]
	s_mov_b32 m0, s7
	ds_read_b128 v[212:215], v178 offset:49152
	ds_read_b128 v[216:219], v178 offset:50176
	ds_read_b128 v[220:223], v178 offset:51200
	ds_read_b128 v[224:227], v178 offset:52224
	ds_read_b128 v[228:231], v178 offset:53248
	ds_read_b128 v[232:235], v178 offset:54272
	ds_read_b128 v[236:239], v178 offset:55296
	ds_read_b128 v[240:243], v178 offset:56320
	global_load_lds_dwordx4 v[196:197], off
	v_lshl_add_u64 v[196:197], v[248:249], 0, s[24:25]
	s_add_i32 m0, s7, 0x2000
	s_add_i32 s7, s8, s0
	global_load_lds_dwordx4 v[196:197], off
	v_lshl_add_u64 v[196:197], v[244:245], 0, s[26:27]
	v_lshl_add_u64 v[198:199], v[196:197], 0, v[142:143]
	s_mov_b32 m0, s7
	v_lshl_add_u64 v[196:197], v[196:197], 0, v[144:145]
	global_load_lds_dwordx4 v[198:199], off
	s_add_i32 m0, s7, 0x2000
	s_nop 0
	global_load_lds_dwordx4 v[196:197], off
	v_lshl_add_u64 v[196:197], v[250:251], 0, s[24:25]
	s_mov_b32 m0, s49
	s_nop 0
	global_load_lds_dwordx4 v[196:197], off
	v_lshl_add_u64 v[196:197], v[252:253], 0, s[24:25]
	s_mov_b32 m0, s50
	s_nop 0
	global_load_lds_dwordx4 v[196:197], off
	s_waitcnt vmcnt(8)
	s_waitcnt lgkmcnt(0)
	s_barrier
	s_setprio 1
	s_waitcnt lgkmcnt(0)
	v_mfma_f32_16x16x32_bf16 v[62:65], v[168:171], v[212:215], v[62:65]
	v_mfma_f32_16x16x32_bf16 v[58:61], v[184:187], v[212:215], v[58:61]
	v_mfma_f32_16x16x32_bf16 v[46:49], v[168:171], v[220:223], v[46:49]
	v_mfma_f32_16x16x32_bf16 v[42:45], v[184:187], v[220:223], v[42:45]
	v_mfma_f32_16x16x32_bf16 v[30:33], v[168:171], v[228:231], v[30:33]
	v_mfma_f32_16x16x32_bf16 v[26:29], v[184:187], v[228:231], v[26:29]
	v_mfma_f32_16x16x32_bf16 v[14:17], v[168:171], v[236:239], v[14:17]
	v_mfma_f32_16x16x32_bf16 v[10:13], v[184:187], v[236:239], v[10:13]
	v_mfma_f32_16x16x32_bf16 v[62:65], v[172:175], v[216:219], v[62:65]
	v_mfma_f32_16x16x32_bf16 v[58:61], v[188:191], v[216:219], v[58:61]
	v_mfma_f32_16x16x32_bf16 v[46:49], v[172:175], v[224:227], v[46:49]
	v_mfma_f32_16x16x32_bf16 v[42:45], v[188:191], v[224:227], v[42:45]
	v_mfma_f32_16x16x32_bf16 v[30:33], v[172:175], v[232:235], v[30:33]
	v_mfma_f32_16x16x32_bf16 v[26:29], v[188:191], v[232:235], v[26:29]
	v_mfma_f32_16x16x32_bf16 v[14:17], v[172:175], v[240:243], v[14:17]
	v_mfma_f32_16x16x32_bf16 v[10:13], v[188:191], v[240:243], v[10:13]
	v_mfma_f32_16x16x32_bf16 v[54:57], v[192:195], v[212:215], v[54:57]
	v_mfma_f32_16x16x32_bf16 v[50:53], v[204:207], v[212:215], v[50:53]
	v_mfma_f32_16x16x32_bf16 v[38:41], v[192:195], v[220:223], v[38:41]
	v_mfma_f32_16x16x32_bf16 v[34:37], v[204:207], v[220:223], v[34:37]
	v_mfma_f32_16x16x32_bf16 v[22:25], v[192:195], v[228:231], v[22:25]
	v_mfma_f32_16x16x32_bf16 v[18:21], v[204:207], v[228:231], v[18:21]
	v_mfma_f32_16x16x32_bf16 v[6:9], v[192:195], v[236:239], v[6:9]
	v_mfma_f32_16x16x32_bf16 v[2:5], v[204:207], v[236:239], v[2:5]
	v_mfma_f32_16x16x32_bf16 v[54:57], v[200:203], v[216:219], v[54:57]
	v_mfma_f32_16x16x32_bf16 v[50:53], v[208:211], v[216:219], v[50:53]
	v_mfma_f32_16x16x32_bf16 v[38:41], v[200:203], v[224:227], v[38:41]
	v_mfma_f32_16x16x32_bf16 v[34:37], v[208:211], v[224:227], v[34:37]
	v_mfma_f32_16x16x32_bf16 v[22:25], v[200:203], v[232:235], v[22:25]
	v_mfma_f32_16x16x32_bf16 v[18:21], v[208:211], v[232:235], v[18:21]
	v_mfma_f32_16x16x32_bf16 v[6:9], v[200:203], v[240:243], v[6:9]
	v_mfma_f32_16x16x32_bf16 v[2:5], v[208:211], v[240:243], v[2:5]
	s_setprio 0
	s_barrier
	s_add_i32 s3, s3, 2
	v_lshl_add_u64 v[134:135], v[134:135], 0, s[36:37]
	s_cmp_gt_u32 s3, 13
	v_lshl_add_u64 v[136:137], v[136:137], 0, s[36:37]
	s_cbranch_scc0 .LBB0_676

.LBB0_1064:
	s_ashr_i32 s47, s46, 31
	s_lshl_b64 s[12:13], s[46:47], 20
	s_ashr_i32 s49, s48, 31
	s_ashr_i32 s45, s44, 31
	v_lshl_add_u64 v[6:7], v[168:169], 0, s[12:13]
	s_lshl_b64 s[12:13], s[48:49], 7
	s_lshl_b64 s[52:53], s[44:45], 20
	v_lshl_add_u64 v[188:189], v[6:7], 0, s[12:13]
	v_lshl_add_u64 v[6:7], v[170:171], 0, s[52:53]
	v_lshl_add_u64 v[190:191], v[6:7], 0, s[12:13]
	s_waitcnt vmcnt(0)
	v_mov_b32_e32 v66, 0
	v_cndmask_b32_e64 v1, v5, v189, s[50:51]
	v_cndmask_b32_e64 v130, v4, v188, s[50:51]
	v_cndmask_b32_e64 v131, v3, v191, s[50:51]
	v_cndmask_b32_e64 v132, v2, v190, s[50:51]
	s_add_i32 s12, s9, -2
	v_lshl_add_u64 v[134:135], v[4:5], 0, s[24:25]
	v_lshl_add_u64 v[136:137], v[2:3], 0, s[38:39]
	s_mov_b32 s13, 0
	v_add_u32_e32 v133, s65, v204
	ds_read_b128 v[138:141], v207
	ds_read_b128 v[142:145], v207 offset:1024
	ds_read_b128 v[146:149], v207 offset:2048
	ds_read_b128 v[150:153], v207 offset:3072
	ds_read_b128 v[154:157], v133
	ds_read_b128 v[158:161], v133 offset:1024
	ds_read_b128 v[162:165], v133 offset:2048
	ds_read_b128 v[192:195], v133 offset:3072
	s_cmp_eq_u32 s12, s13
	v_lshl_add_u64 v[196:197], v[134:135], 0, s[40:41]
	s_cselect_b64 vcc, -1, 0
	s_add_i32 s13, s13, 2
	v_cndmask_b32_e32 v197, v197, v1, vcc
	v_cndmask_b32_e32 v196, v196, v130, vcc
	v_cndmask_b32_e32 v199, v137, v131, vcc
	v_cndmask_b32_e32 v198, v136, v132, vcc
	v_lshl_add_u64 v[240:241], v[134:135], 0, v[184:185]
	s_add_i32 m0, s1, 0xc000
	ds_read_b128 v[208:211], v205
	ds_read_b128 v[212:215], v205 offset:1024
	ds_read_b128 v[216:219], v205 offset:2048
	ds_read_b128 v[220:223], v205 offset:3072
	ds_read_b128 v[224:227], v205 offset:4096
	ds_read_b128 v[228:231], v205 offset:5120
	ds_read_b128 v[232:235], v205 offset:6144
	ds_read_b128 v[236:239], v205 offset:7168
	global_load_lds_dwordx4 v[240:241], off
	v_lshl_add_u64 v[240:241], v[134:135], 0, v[186:187]
	s_add_i32 m0, s1, 0xe000
	s_nop 0
	global_load_lds_dwordx4 v[240:241], off
	s_waitcnt vmcnt(8)
	s_waitcnt lgkmcnt(0)
	s_barrier
	s_setprio 1
	s_waitcnt lgkmcnt(0)
	v_mfma_f32_16x16x32_bf16 v[62:65], v[138:141], v[208:211], 0
	v_mfma_f32_16x16x32_bf16 v[58:61], v[146:149], v[208:211], 0
	v_mfma_f32_16x16x32_bf16 v[54:57], v[138:141], v[216:219], 0
	v_mfma_f32_16x16x32_bf16 v[50:53], v[146:149], v[216:219], 0
	v_mfma_f32_16x16x32_bf16 v[46:49], v[138:141], v[224:227], 0
	v_mfma_f32_16x16x32_bf16 v[42:45], v[146:149], v[224:227], 0
	v_mfma_f32_16x16x32_bf16 v[38:41], v[138:141], v[232:235], 0
	v_mfma_f32_16x16x32_bf16 v[34:37], v[146:149], v[232:235], 0
	v_mfma_f32_16x16x32_bf16 v[62:65], v[142:145], v[212:215], v[62:65]
	v_mfma_f32_16x16x32_bf16 v[58:61], v[150:153], v[212:215], v[58:61]
	v_mfma_f32_16x16x32_bf16 v[54:57], v[142:145], v[220:223], v[54:57]
	v_mfma_f32_16x16x32_bf16 v[50:53], v[150:153], v[220:223], v[50:53]
	v_mfma_f32_16x16x32_bf16 v[46:49], v[142:145], v[228:231], v[46:49]
	v_mfma_f32_16x16x32_bf16 v[42:45], v[150:153], v[228:231], v[42:45]
	v_mfma_f32_16x16x32_bf16 v[38:41], v[142:145], v[236:239], v[38:41]
	v_mfma_f32_16x16x32_bf16 v[34:37], v[150:153], v[236:239], v[34:37]
	v_mfma_f32_16x16x32_bf16 v[30:33], v[154:157], v[208:211], 0
	v_mfma_f32_16x16x32_bf16 v[26:29], v[162:165], v[208:211], 0
	v_mfma_f32_16x16x32_bf16 v[22:25], v[154:157], v[216:219], 0
	v_mfma_f32_16x16x32_bf16 v[18:21], v[162:165], v[216:219], 0
	v_mfma_f32_16x16x32_bf16 v[14:17], v[154:157], v[224:227], 0
	v_mfma_f32_16x16x32_bf16 v[10:13], v[162:165], v[224:227], 0
	v_mfma_f32_16x16x32_bf16 v[6:9], v[154:157], v[232:235], 0
	v_mfma_f32_16x16x32_bf16 v[2:5], v[162:165], v[232:235], 0
	v_mfma_f32_16x16x32_bf16 v[30:33], v[158:161], v[212:215], v[30:33]
	v_mfma_f32_16x16x32_bf16 v[26:29], v[192:195], v[212:215], v[26:29]
	v_mfma_f32_16x16x32_bf16 v[22:25], v[158:161], v[220:223], v[22:25]
	v_mfma_f32_16x16x32_bf16 v[18:21], v[192:195], v[220:223], v[18:21]
	v_mfma_f32_16x16x32_bf16 v[14:17], v[158:161], v[228:231], v[14:17]
	v_mfma_f32_16x16x32_bf16 v[10:13], v[192:195], v[228:231], v[10:13]
	v_mfma_f32_16x16x32_bf16 v[6:9], v[158:161], v[236:239], v[6:9]
	v_mfma_f32_16x16x32_bf16 v[2:5], v[192:195], v[236:239], v[2:5]
	s_setprio 0
	s_barrier
	s_add_i32 s31, s64, s0
	v_lshl_add_u64 v[240:241], v[198:199], 0, v[172:173]
	s_mov_b32 m0, s31
	ds_read_b128 v[208:211], v205 offset:16384
	ds_read_b128 v[212:215], v205 offset:17408
	ds_read_b128 v[216:219], v205 offset:18432
	ds_read_b128 v[220:223], v205 offset:19456
	ds_read_b128 v[224:227], v205 offset:20480
	ds_read_b128 v[228:231], v205 offset:21504
	ds_read_b128 v[232:235], v205 offset:22528
	ds_read_b128 v[236:239], v205 offset:23552
	global_load_lds_dwordx4 v[240:241], off
	v_lshl_add_u64 v[242:243], v[198:199], 0, v[174:175]
	s_add_i32 m0, s31, 0x2000
	v_lshl_add_u64 v[244:245], v[198:199], 0, s[18:19]
	s_add_i32 s31, s65, s0
	global_load_lds_dwordx4 v[242:243], off
	v_lshl_add_u64 v[246:247], v[244:245], 0, v[172:173]
	s_mov_b32 m0, s31
	v_lshl_add_u64 v[244:245], v[244:245], 0, v[174:175]
	global_load_lds_dwordx4 v[246:247], off
	s_add_i32 m0, s31, 0x2000
	v_lshl_add_u64 v[246:247], v[196:197], 0, v[174:175]
	global_load_lds_dwordx4 v[244:245], off
	v_lshl_add_u64 v[244:245], v[196:197], 0, v[172:173]
	s_mov_b32 m0, s1
	s_nop 0
	global_load_lds_dwordx4 v[244:245], off
	s_mov_b32 m0, s2
	s_nop 0
	global_load_lds_dwordx4 v[246:247], off
	s_waitcnt vmcnt(8)
	s_waitcnt lgkmcnt(0)
	s_barrier
	s_setprio 1
	s_waitcnt lgkmcnt(0)
	v_mfma_f32_16x16x32_bf16 v[126:129], v[138:141], v[208:211], 0
	v_mfma_f32_16x16x32_bf16 v[122:125], v[146:149], v[208:211], 0
	v_mfma_f32_16x16x32_bf16 v[118:121], v[138:141], v[216:219], 0
	v_mfma_f32_16x16x32_bf16 v[114:117], v[146:149], v[216:219], 0
	v_mfma_f32_16x16x32_bf16 v[110:113], v[138:141], v[224:227], 0
	v_mfma_f32_16x16x32_bf16 v[106:109], v[146:149], v[224:227], 0
	v_mfma_f32_16x16x32_bf16 v[102:105], v[138:141], v[232:235], 0
	v_mfma_f32_16x16x32_bf16 v[98:101], v[146:149], v[232:235], 0
	v_mfma_f32_16x16x32_bf16 v[126:129], v[142:145], v[212:215], v[126:129]
	v_mfma_f32_16x16x32_bf16 v[122:125], v[150:153], v[212:215], v[122:125]
	v_mfma_f32_16x16x32_bf16 v[118:121], v[142:145], v[220:223], v[118:121]
	v_mfma_f32_16x16x32_bf16 v[114:117], v[150:153], v[220:223], v[114:117]
	v_mfma_f32_16x16x32_bf16 v[110:113], v[142:145], v[228:231], v[110:113]
	v_mfma_f32_16x16x32_bf16 v[106:109], v[150:153], v[228:231], v[106:109]
	v_mfma_f32_16x16x32_bf16 v[102:105], v[142:145], v[236:239], v[102:105]
	v_mfma_f32_16x16x32_bf16 v[98:101], v[150:153], v[236:239], v[98:101]
	v_mfma_f32_16x16x32_bf16 v[94:97], v[154:157], v[208:211], 0
	v_mfma_f32_16x16x32_bf16 v[90:93], v[162:165], v[208:211], 0
	v_mfma_f32_16x16x32_bf16 v[86:89], v[154:157], v[216:219], 0
	v_mfma_f32_16x16x32_bf16 v[82:85], v[162:165], v[216:219], 0
	v_mfma_f32_16x16x32_bf16 v[78:81], v[154:157], v[224:227], 0
	v_mfma_f32_16x16x32_bf16 v[74:77], v[162:165], v[224:227], 0
	v_mfma_f32_16x16x32_bf16 v[70:73], v[154:157], v[232:235], 0
	v_mfma_f32_16x16x32_bf16 v[66:69], v[162:165], v[232:235], 0
	v_mfma_f32_16x16x32_bf16 v[94:97], v[158:161], v[212:215], v[94:97]
	v_mfma_f32_16x16x32_bf16 v[90:93], v[192:195], v[212:215], v[90:93]
	v_mfma_f32_16x16x32_bf16 v[86:89], v[158:161], v[220:223], v[86:89]
	v_mfma_f32_16x16x32_bf16 v[82:85], v[192:195], v[220:223], v[82:85]
	v_mfma_f32_16x16x32_bf16 v[78:81], v[158:161], v[228:231], v[78:81]
	v_mfma_f32_16x16x32_bf16 v[74:77], v[192:195], v[228:231], v[74:77]
	v_mfma_f32_16x16x32_bf16 v[70:73], v[158:161], v[236:239], v[70:73]
	v_mfma_f32_16x16x32_bf16 v[66:69], v[192:195], v[236:239], v[66:69]
	s_setprio 0
	s_barrier
	s_add_i32 s31, 0, 0x18000
	v_add_u32_e32 v133, s31, v204
	s_add_i32 s45, 0, 0x1c000
	ds_read_b128 v[138:141], v133
	ds_read_b128 v[142:145], v133 offset:1024
	ds_read_b128 v[146:149], v133 offset:2048
	ds_read_b128 v[150:153], v133 offset:3072
	v_add_u32_e32 v133, s45, v204
	ds_read_b128 v[154:157], v133
	ds_read_b128 v[158:161], v133 offset:1024
	ds_read_b128 v[162:165], v133 offset:2048
	ds_read_b128 v[192:195], v133 offset:3072
	v_lshl_add_u64 v[196:197], v[196:197], 0, s[18:19]
	s_mov_b32 m0, s33
	v_lshl_add_u64 v[248:249], v[196:197], 0, v[172:173]
	ds_read_b128 v[208:211], v205 offset:32768
	ds_read_b128 v[212:215], v205 offset:33792
	ds_read_b128 v[216:219], v205 offset:34816
	ds_read_b128 v[220:223], v205 offset:35840
	ds_read_b128 v[224:227], v205 offset:36864
	ds_read_b128 v[228:231], v205 offset:37888
	ds_read_b128 v[232:235], v205 offset:38912
	ds_read_b128 v[236:239], v205 offset:39936
	global_load_lds_dwordx4 v[248:249], off
	v_lshl_add_u64 v[196:197], v[196:197], 0, v[174:175]
	s_mov_b32 m0, s34
	s_nop 0
	global_load_lds_dwordx4 v[196:197], off
	s_waitcnt vmcnt(8)
	s_waitcnt lgkmcnt(0)
	s_barrier
	s_setprio 1
	s_waitcnt lgkmcnt(0)
	v_mfma_f32_16x16x32_bf16 v[62:65], v[138:141], v[208:211], v[62:65]
	v_mfma_f32_16x16x32_bf16 v[58:61], v[146:149], v[208:211], v[58:61]
	v_mfma_f32_16x16x32_bf16 v[54:57], v[138:141], v[216:219], v[54:57]
	v_mfma_f32_16x16x32_bf16 v[50:53], v[146:149], v[216:219], v[50:53]
	v_mfma_f32_16x16x32_bf16 v[46:49], v[138:141], v[224:227], v[46:49]
	v_mfma_f32_16x16x32_bf16 v[42:45], v[146:149], v[224:227], v[42:45]
	v_mfma_f32_16x16x32_bf16 v[38:41], v[138:141], v[232:235], v[38:41]
	v_mfma_f32_16x16x32_bf16 v[34:37], v[146:149], v[232:235], v[34:37]
	v_mfma_f32_16x16x32_bf16 v[62:65], v[142:145], v[212:215], v[62:65]
	v_mfma_f32_16x16x32_bf16 v[58:61], v[150:153], v[212:215], v[58:61]
	v_mfma_f32_16x16x32_bf16 v[54:57], v[142:145], v[220:223], v[54:57]
	v_mfma_f32_16x16x32_bf16 v[50:53], v[150:153], v[220:223], v[50:53]
	v_mfma_f32_16x16x32_bf16 v[46:49], v[142:145], v[228:231], v[46:49]
	v_mfma_f32_16x16x32_bf16 v[42:45], v[150:153], v[228:231], v[42:45]
	v_mfma_f32_16x16x32_bf16 v[38:41], v[142:145], v[236:239], v[38:41]
	v_mfma_f32_16x16x32_bf16 v[34:37], v[150:153], v[236:239], v[34:37]
	v_mfma_f32_16x16x32_bf16 v[30:33], v[154:157], v[208:211], v[30:33]
	v_mfma_f32_16x16x32_bf16 v[26:29], v[162:165], v[208:211], v[26:29]
	v_mfma_f32_16x16x32_bf16 v[22:25], v[154:157], v[216:219], v[22:25]
	v_mfma_f32_16x16x32_bf16 v[18:21], v[162:165], v[216:219], v[18:21]
	v_mfma_f32_16x16x32_bf16 v[14:17], v[154:157], v[224:227], v[14:17]
	v_mfma_f32_16x16x32_bf16 v[10:13], v[162:165], v[224:227], v[10:13]
	v_mfma_f32_16x16x32_bf16 v[6:9], v[154:157], v[232:235], v[6:9]
	v_mfma_f32_16x16x32_bf16 v[2:5], v[162:165], v[232:235], v[2:5]
	v_mfma_f32_16x16x32_bf16 v[30:33], v[158:161], v[212:215], v[30:33]
	v_mfma_f32_16x16x32_bf16 v[26:29], v[192:195], v[212:215], v[26:29]
	v_mfma_f32_16x16x32_bf16 v[22:25], v[158:161], v[220:223], v[22:25]
	v_mfma_f32_16x16x32_bf16 v[18:21], v[192:195], v[220:223], v[18:21]
	v_mfma_f32_16x16x32_bf16 v[14:17], v[158:161], v[228:231], v[14:17]
	v_mfma_f32_16x16x32_bf16 v[10:13], v[192:195], v[228:231], v[10:13]
	v_mfma_f32_16x16x32_bf16 v[6:9], v[158:161], v[236:239], v[6:9]
	v_mfma_f32_16x16x32_bf16 v[2:5], v[192:195], v[236:239], v[2:5]
	s_setprio 0
	s_barrier
	s_add_i32 s31, s31, s0
	v_lshl_add_u64 v[196:197], v[240:241], 0, s[22:23]
	s_mov_b32 m0, s31
	ds_read_b128 v[208:211], v205 offset:49152
	ds_read_b128 v[212:215], v205 offset:50176
	ds_read_b128 v[216:219], v205 offset:51200
	ds_read_b128 v[220:223], v205 offset:52224
	ds_read_b128 v[224:227], v205 offset:53248
	ds_read_b128 v[228:231], v205 offset:54272
	ds_read_b128 v[232:235], v205 offset:55296
	ds_read_b128 v[236:239], v205 offset:56320
	global_load_lds_dwordx4 v[196:197], off
	v_lshl_add_u64 v[196:197], v[242:243], 0, s[22:23]
	s_add_i32 m0, s31, 0x2000
	s_add_i32 s31, s45, s0
	global_load_lds_dwordx4 v[196:197], off
	v_lshl_add_u64 v[196:197], v[198:199], 0, s[24:25]
	v_lshl_add_u64 v[198:199], v[196:197], 0, v[172:173]
	s_mov_b32 m0, s31
	v_lshl_add_u64 v[196:197], v[196:197], 0, v[174:175]
	global_load_lds_dwordx4 v[198:199], off
	s_add_i32 m0, s31, 0x2000
	s_nop 0
	global_load_lds_dwordx4 v[196:197], off
	v_lshl_add_u64 v[196:197], v[244:245], 0, s[22:23]
	s_mov_b32 m0, s56
	s_nop 0
	global_load_lds_dwordx4 v[196:197], off
	v_lshl_add_u64 v[196:197], v[246:247], 0, s[22:23]
	s_mov_b32 m0, s57
	s_nop 0
	global_load_lds_dwordx4 v[196:197], off
	s_waitcnt vmcnt(8)
	s_waitcnt lgkmcnt(0)
	s_barrier
	s_setprio 1
	s_waitcnt lgkmcnt(0)
	v_mfma_f32_16x16x32_bf16 v[126:129], v[138:141], v[208:211], v[126:129]
	v_mfma_f32_16x16x32_bf16 v[122:125], v[146:149], v[208:211], v[122:125]
	v_mfma_f32_16x16x32_bf16 v[118:121], v[138:141], v[216:219], v[118:121]
	v_mfma_f32_16x16x32_bf16 v[114:117], v[146:149], v[216:219], v[114:117]
	v_mfma_f32_16x16x32_bf16 v[110:113], v[138:141], v[224:227], v[110:113]
	v_mfma_f32_16x16x32_bf16 v[106:109], v[146:149], v[224:227], v[106:109]
	v_mfma_f32_16x16x32_bf16 v[102:105], v[138:141], v[232:235], v[102:105]
	v_mfma_f32_16x16x32_bf16 v[98:101], v[146:149], v[232:235], v[98:101]
	v_mfma_f32_16x16x32_bf16 v[126:129], v[142:145], v[212:215], v[126:129]
	v_mfma_f32_16x16x32_bf16 v[122:125], v[150:153], v[212:215], v[122:125]
	v_mfma_f32_16x16x32_bf16 v[118:121], v[142:145], v[220:223], v[118:121]
	v_mfma_f32_16x16x32_bf16 v[114:117], v[150:153], v[220:223], v[114:117]
	v_mfma_f32_16x16x32_bf16 v[110:113], v[142:145], v[228:231], v[110:113]
	v_mfma_f32_16x16x32_bf16 v[106:109], v[150:153], v[228:231], v[106:109]
	v_mfma_f32_16x16x32_bf16 v[102:105], v[142:145], v[236:239], v[102:105]
	v_mfma_f32_16x16x32_bf16 v[98:101], v[150:153], v[236:239], v[98:101]
	v_mfma_f32_16x16x32_bf16 v[94:97], v[154:157], v[208:211], v[94:97]
	v_mfma_f32_16x16x32_bf16 v[90:93], v[162:165], v[208:211], v[90:93]
	v_mfma_f32_16x16x32_bf16 v[86:89], v[154:157], v[216:219], v[86:89]
	v_mfma_f32_16x16x32_bf16 v[82:85], v[162:165], v[216:219], v[82:85]
	v_mfma_f32_16x16x32_bf16 v[78:81], v[154:157], v[224:227], v[78:81]
	v_mfma_f32_16x16x32_bf16 v[74:77], v[162:165], v[224:227], v[74:77]
	v_mfma_f32_16x16x32_bf16 v[70:73], v[154:157], v[232:235], v[70:73]
	v_mfma_f32_16x16x32_bf16 v[66:69], v[162:165], v[232:235], v[66:69]
	v_mfma_f32_16x16x32_bf16 v[94:97], v[158:161], v[212:215], v[94:97]
	v_mfma_f32_16x16x32_bf16 v[90:93], v[192:195], v[212:215], v[90:93]
	v_mfma_f32_16x16x32_bf16 v[86:89], v[158:161], v[220:223], v[86:89]
	v_mfma_f32_16x16x32_bf16 v[82:85], v[192:195], v[220:223], v[82:85]
	v_mfma_f32_16x16x32_bf16 v[78:81], v[158:161], v[228:231], v[78:81]
	v_mfma_f32_16x16x32_bf16 v[74:77], v[192:195], v[228:231], v[74:77]
	v_mfma_f32_16x16x32_bf16 v[70:73], v[158:161], v[236:239], v[70:73]
	v_mfma_f32_16x16x32_bf16 v[66:69], v[192:195], v[236:239], v[66:69]
	s_setprio 0
	s_barrier
	v_lshl_add_u64 v[134:135], v[134:135], 0, s[38:39]
	s_cmp_ge_i32 s13, s9
	v_lshl_add_u64 v[136:137], v[136:137], 0, s[38:39]
	s_cbranch_scc0 .LBB0_1065
	s_branch .Lpeel_exit_3
.LBB0_1065:
	v_add_u32_e32 v133, s65, v204
	ds_read_b128 v[138:141], v207
	ds_read_b128 v[142:145], v207 offset:1024
	ds_read_b128 v[146:149], v207 offset:2048
	ds_read_b128 v[150:153], v207 offset:3072
	ds_read_b128 v[154:157], v133
	ds_read_b128 v[158:161], v133 offset:1024
	ds_read_b128 v[162:165], v133 offset:2048
	ds_read_b128 v[192:195], v133 offset:3072
	s_cmp_eq_u32 s12, s13
	v_lshl_add_u64 v[196:197], v[134:135], 0, s[40:41]
	s_cselect_b64 vcc, -1, 0
	s_add_i32 s13, s13, 2
	v_cndmask_b32_e32 v197, v197, v1, vcc
	v_cndmask_b32_e32 v196, v196, v130, vcc
	v_cndmask_b32_e32 v199, v137, v131, vcc
	v_cndmask_b32_e32 v198, v136, v132, vcc
	v_lshl_add_u64 v[240:241], v[134:135], 0, v[184:185]
	s_add_i32 m0, s1, 0xc000
	ds_read_b128 v[208:211], v205
	ds_read_b128 v[212:215], v205 offset:1024
	ds_read_b128 v[216:219], v205 offset:2048
	ds_read_b128 v[220:223], v205 offset:3072
	ds_read_b128 v[224:227], v205 offset:4096
	ds_read_b128 v[228:231], v205 offset:5120
	ds_read_b128 v[232:235], v205 offset:6144
	ds_read_b128 v[236:239], v205 offset:7168
	global_load_lds_dwordx4 v[240:241], off
	v_lshl_add_u64 v[240:241], v[134:135], 0, v[186:187]
	s_add_i32 m0, s1, 0xe000
	s_nop 0
	global_load_lds_dwordx4 v[240:241], off
	s_waitcnt vmcnt(8)
	s_waitcnt lgkmcnt(0)
	s_barrier
	s_setprio 1
	s_waitcnt lgkmcnt(0)
	v_mfma_f32_16x16x32_bf16 v[62:65], v[138:141], v[208:211], v[62:65]
	v_mfma_f32_16x16x32_bf16 v[58:61], v[146:149], v[208:211], v[58:61]
	v_mfma_f32_16x16x32_bf16 v[54:57], v[138:141], v[216:219], v[54:57]
	v_mfma_f32_16x16x32_bf16 v[50:53], v[146:149], v[216:219], v[50:53]
	v_mfma_f32_16x16x32_bf16 v[46:49], v[138:141], v[224:227], v[46:49]
	v_mfma_f32_16x16x32_bf16 v[42:45], v[146:149], v[224:227], v[42:45]
	v_mfma_f32_16x16x32_bf16 v[38:41], v[138:141], v[232:235], v[38:41]
	v_mfma_f32_16x16x32_bf16 v[34:37], v[146:149], v[232:235], v[34:37]
	v_mfma_f32_16x16x32_bf16 v[62:65], v[142:145], v[212:215], v[62:65]
	v_mfma_f32_16x16x32_bf16 v[58:61], v[150:153], v[212:215], v[58:61]
	v_mfma_f32_16x16x32_bf16 v[54:57], v[142:145], v[220:223], v[54:57]
	v_mfma_f32_16x16x32_bf16 v[50:53], v[150:153], v[220:223], v[50:53]
	v_mfma_f32_16x16x32_bf16 v[46:49], v[142:145], v[228:231], v[46:49]
	v_mfma_f32_16x16x32_bf16 v[42:45], v[150:153], v[228:231], v[42:45]
	v_mfma_f32_16x16x32_bf16 v[38:41], v[142:145], v[236:239], v[38:41]
	v_mfma_f32_16x16x32_bf16 v[34:37], v[150:153], v[236:239], v[34:37]
	v_mfma_f32_16x16x32_bf16 v[30:33], v[154:157], v[208:211], v[30:33]
	v_mfma_f32_16x16x32_bf16 v[26:29], v[162:165], v[208:211], v[26:29]
	v_mfma_f32_16x16x32_bf16 v[22:25], v[154:157], v[216:219], v[22:25]
	v_mfma_f32_16x16x32_bf16 v[18:21], v[162:165], v[216:219], v[18:21]
	v_mfma_f32_16x16x32_bf16 v[14:17], v[154:157], v[224:227], v[14:17]
	v_mfma_f32_16x16x32_bf16 v[10:13], v[162:165], v[224:227], v[10:13]
	v_mfma_f32_16x16x32_bf16 v[6:9], v[154:157], v[232:235], v[6:9]
	v_mfma_f32_16x16x32_bf16 v[2:5], v[162:165], v[232:235], v[2:5]
	v_mfma_f32_16x16x32_bf16 v[30:33], v[158:161], v[212:215], v[30:33]
	v_mfma_f32_16x16x32_bf16 v[26:29], v[192:195], v[212:215], v[26:29]
	v_mfma_f32_16x16x32_bf16 v[22:25], v[158:161], v[220:223], v[22:25]
	v_mfma_f32_16x16x32_bf16 v[18:21], v[192:195], v[220:223], v[18:21]
	v_mfma_f32_16x16x32_bf16 v[14:17], v[158:161], v[228:231], v[14:17]
	v_mfma_f32_16x16x32_bf16 v[10:13], v[192:195], v[228:231], v[10:13]
	v_mfma_f32_16x16x32_bf16 v[6:9], v[158:161], v[236:239], v[6:9]
	v_mfma_f32_16x16x32_bf16 v[2:5], v[192:195], v[236:239], v[2:5]
	s_setprio 0
	s_barrier
	s_add_i32 s31, s64, s0
	v_lshl_add_u64 v[240:241], v[198:199], 0, v[172:173]
	s_mov_b32 m0, s31
	ds_read_b128 v[208:211], v205 offset:16384
	ds_read_b128 v[212:215], v205 offset:17408
	ds_read_b128 v[216:219], v205 offset:18432
	ds_read_b128 v[220:223], v205 offset:19456
	ds_read_b128 v[224:227], v205 offset:20480
	ds_read_b128 v[228:231], v205 offset:21504
	ds_read_b128 v[232:235], v205 offset:22528
	ds_read_b128 v[236:239], v205 offset:23552
	global_load_lds_dwordx4 v[240:241], off
	v_lshl_add_u64 v[242:243], v[198:199], 0, v[174:175]
	s_add_i32 m0, s31, 0x2000
	v_lshl_add_u64 v[244:245], v[198:199], 0, s[18:19]
	s_add_i32 s31, s65, s0
	global_load_lds_dwordx4 v[242:243], off
	v_lshl_add_u64 v[246:247], v[244:245], 0, v[172:173]
	s_mov_b32 m0, s31
	v_lshl_add_u64 v[244:245], v[244:245], 0, v[174:175]
	global_load_lds_dwordx4 v[246:247], off
	s_add_i32 m0, s31, 0x2000
	v_lshl_add_u64 v[246:247], v[196:197], 0, v[174:175]
	global_load_lds_dwordx4 v[244:245], off
	v_lshl_add_u64 v[244:245], v[196:197], 0, v[172:173]
	s_mov_b32 m0, s1
	s_nop 0
	global_load_lds_dwordx4 v[244:245], off
	s_mov_b32 m0, s2
	s_nop 0
	global_load_lds_dwordx4 v[246:247], off
	s_waitcnt vmcnt(8)
	s_waitcnt lgkmcnt(0)
	s_barrier
	s_setprio 1
	s_waitcnt lgkmcnt(0)
	v_mfma_f32_16x16x32_bf16 v[126:129], v[138:141], v[208:211], v[126:129]
	v_mfma_f32_16x16x32_bf16 v[122:125], v[146:149], v[208:211], v[122:125]
	v_mfma_f32_16x16x32_bf16 v[118:121], v[138:141], v[216:219], v[118:121]
	v_mfma_f32_16x16x32_bf16 v[114:117], v[146:149], v[216:219], v[114:117]
	v_mfma_f32_16x16x32_bf16 v[110:113], v[138:141], v[224:227], v[110:113]
	v_mfma_f32_16x16x32_bf16 v[106:109], v[146:149], v[224:227], v[106:109]
	v_mfma_f32_16x16x32_bf16 v[102:105], v[138:141], v[232:235], v[102:105]
	v_mfma_f32_16x16x32_bf16 v[98:101], v[146:149], v[232:235], v[98:101]
	v_mfma_f32_16x16x32_bf16 v[126:129], v[142:145], v[212:215], v[126:129]
	v_mfma_f32_16x16x32_bf16 v[122:125], v[150:153], v[212:215], v[122:125]
	v_mfma_f32_16x16x32_bf16 v[118:121], v[142:145], v[220:223], v[118:121]
	v_mfma_f32_16x16x32_bf16 v[114:117], v[150:153], v[220:223], v[114:117]
	v_mfma_f32_16x16x32_bf16 v[110:113], v[142:145], v[228:231], v[110:113]
	v_mfma_f32_16x16x32_bf16 v[106:109], v[150:153], v[228:231], v[106:109]
	v_mfma_f32_16x16x32_bf16 v[102:105], v[142:145], v[236:239], v[102:105]
	v_mfma_f32_16x16x32_bf16 v[98:101], v[150:153], v[236:239], v[98:101]
	v_mfma_f32_16x16x32_bf16 v[94:97], v[154:157], v[208:211], v[94:97]
	v_mfma_f32_16x16x32_bf16 v[90:93], v[162:165], v[208:211], v[90:93]
	v_mfma_f32_16x16x32_bf16 v[86:89], v[154:157], v[216:219], v[86:89]
	v_mfma_f32_16x16x32_bf16 v[82:85], v[162:165], v[216:219], v[82:85]
	v_mfma_f32_16x16x32_bf16 v[78:81], v[154:157], v[224:227], v[78:81]
	v_mfma_f32_16x16x32_bf16 v[74:77], v[162:165], v[224:227], v[74:77]
	v_mfma_f32_16x16x32_bf16 v[70:73], v[154:157], v[232:235], v[70:73]
	v_mfma_f32_16x16x32_bf16 v[66:69], v[162:165], v[232:235], v[66:69]
	v_mfma_f32_16x16x32_bf16 v[94:97], v[158:161], v[212:215], v[94:97]
	v_mfma_f32_16x16x32_bf16 v[90:93], v[192:195], v[212:215], v[90:93]
	v_mfma_f32_16x16x32_bf16 v[86:89], v[158:161], v[220:223], v[86:89]
	v_mfma_f32_16x16x32_bf16 v[82:85], v[192:195], v[220:223], v[82:85]
	v_mfma_f32_16x16x32_bf16 v[78:81], v[158:161], v[228:231], v[78:81]
	v_mfma_f32_16x16x32_bf16 v[74:77], v[192:195], v[228:231], v[74:77]
	v_mfma_f32_16x16x32_bf16 v[70:73], v[158:161], v[236:239], v[70:73]
	v_mfma_f32_16x16x32_bf16 v[66:69], v[192:195], v[236:239], v[66:69]
	s_setprio 0
	s_barrier
	s_add_i32 s31, 0, 0x18000
	v_add_u32_e32 v133, s31, v204
	s_add_i32 s45, 0, 0x1c000
	ds_read_b128 v[138:141], v133
	ds_read_b128 v[142:145], v133 offset:1024
	ds_read_b128 v[146:149], v133 offset:2048
	ds_read_b128 v[150:153], v133 offset:3072
	v_add_u32_e32 v133, s45, v204
	ds_read_b128 v[154:157], v133
	ds_read_b128 v[158:161], v133 offset:1024
	ds_read_b128 v[162:165], v133 offset:2048
	ds_read_b128 v[192:195], v133 offset:3072
	v_lshl_add_u64 v[196:197], v[196:197], 0, s[18:19]
	s_mov_b32 m0, s33
	v_lshl_add_u64 v[248:249], v[196:197], 0, v[172:173]
	ds_read_b128 v[208:211], v205 offset:32768
	ds_read_b128 v[212:215], v205 offset:33792
	ds_read_b128 v[216:219], v205 offset:34816
	ds_read_b128 v[220:223], v205 offset:35840
	ds_read_b128 v[224:227], v205 offset:36864
	ds_read_b128 v[228:231], v205 offset:37888
	ds_read_b128 v[232:235], v205 offset:38912
	ds_read_b128 v[236:239], v205 offset:39936
	global_load_lds_dwordx4 v[248:249], off
	v_lshl_add_u64 v[196:197], v[196:197], 0, v[174:175]
	s_mov_b32 m0, s34
	s_nop 0
	global_load_lds_dwordx4 v[196:197], off
	s_waitcnt vmcnt(8)
	s_waitcnt lgkmcnt(0)
	s_barrier
	s_setprio 1
	s_waitcnt lgkmcnt(0)
	v_mfma_f32_16x16x32_bf16 v[62:65], v[138:141], v[208:211], v[62:65]
	v_mfma_f32_16x16x32_bf16 v[58:61], v[146:149], v[208:211], v[58:61]
	v_mfma_f32_16x16x32_bf16 v[54:57], v[138:141], v[216:219], v[54:57]
	v_mfma_f32_16x16x32_bf16 v[50:53], v[146:149], v[216:219], v[50:53]
	v_mfma_f32_16x16x32_bf16 v[46:49], v[138:141], v[224:227], v[46:49]
	v_mfma_f32_16x16x32_bf16 v[42:45], v[146:149], v[224:227], v[42:45]
	v_mfma_f32_16x16x32_bf16 v[38:41], v[138:141], v[232:235], v[38:41]
	v_mfma_f32_16x16x32_bf16 v[34:37], v[146:149], v[232:235], v[34:37]
	v_mfma_f32_16x16x32_bf16 v[62:65], v[142:145], v[212:215], v[62:65]
	v_mfma_f32_16x16x32_bf16 v[58:61], v[150:153], v[212:215], v[58:61]
	v_mfma_f32_16x16x32_bf16 v[54:57], v[142:145], v[220:223], v[54:57]
	v_mfma_f32_16x16x32_bf16 v[50:53], v[150:153], v[220:223], v[50:53]
	v_mfma_f32_16x16x32_bf16 v[46:49], v[142:145], v[228:231], v[46:49]
	v_mfma_f32_16x16x32_bf16 v[42:45], v[150:153], v[228:231], v[42:45]
	v_mfma_f32_16x16x32_bf16 v[38:41], v[142:145], v[236:239], v[38:41]
	v_mfma_f32_16x16x32_bf16 v[34:37], v[150:153], v[236:239], v[34:37]
	v_mfma_f32_16x16x32_bf16 v[30:33], v[154:157], v[208:211], v[30:33]
	v_mfma_f32_16x16x32_bf16 v[26:29], v[162:165], v[208:211], v[26:29]
	v_mfma_f32_16x16x32_bf16 v[22:25], v[154:157], v[216:219], v[22:25]
	v_mfma_f32_16x16x32_bf16 v[18:21], v[162:165], v[216:219], v[18:21]
	v_mfma_f32_16x16x32_bf16 v[14:17], v[154:157], v[224:227], v[14:17]
	v_mfma_f32_16x16x32_bf16 v[10:13], v[162:165], v[224:227], v[10:13]
	v_mfma_f32_16x16x32_bf16 v[6:9], v[154:157], v[232:235], v[6:9]
	v_mfma_f32_16x16x32_bf16 v[2:5], v[162:165], v[232:235], v[2:5]
	v_mfma_f32_16x16x32_bf16 v[30:33], v[158:161], v[212:215], v[30:33]
	v_mfma_f32_16x16x32_bf16 v[26:29], v[192:195], v[212:215], v[26:29]
	v_mfma_f32_16x16x32_bf16 v[22:25], v[158:161], v[220:223], v[22:25]
	v_mfma_f32_16x16x32_bf16 v[18:21], v[192:195], v[220:223], v[18:21]
	v_mfma_f32_16x16x32_bf16 v[14:17], v[158:161], v[228:231], v[14:17]
	v_mfma_f32_16x16x32_bf16 v[10:13], v[192:195], v[228:231], v[10:13]
	v_mfma_f32_16x16x32_bf16 v[6:9], v[158:161], v[236:239], v[6:9]
	v_mfma_f32_16x16x32_bf16 v[2:5], v[192:195], v[236:239], v[2:5]
	s_setprio 0
	s_barrier
	s_add_i32 s31, s31, s0
	v_lshl_add_u64 v[196:197], v[240:241], 0, s[22:23]
	s_mov_b32 m0, s31
	ds_read_b128 v[208:211], v205 offset:49152
	ds_read_b128 v[212:215], v205 offset:50176
	ds_read_b128 v[216:219], v205 offset:51200
	ds_read_b128 v[220:223], v205 offset:52224
	ds_read_b128 v[224:227], v205 offset:53248
	ds_read_b128 v[228:231], v205 offset:54272
	ds_read_b128 v[232:235], v205 offset:55296
	ds_read_b128 v[236:239], v205 offset:56320
	global_load_lds_dwordx4 v[196:197], off
	v_lshl_add_u64 v[196:197], v[242:243], 0, s[22:23]
	s_add_i32 m0, s31, 0x2000
	s_add_i32 s31, s45, s0
	global_load_lds_dwordx4 v[196:197], off
	v_lshl_add_u64 v[196:197], v[198:199], 0, s[24:25]
	v_lshl_add_u64 v[198:199], v[196:197], 0, v[172:173]
	s_mov_b32 m0, s31
	v_lshl_add_u64 v[196:197], v[196:197], 0, v[174:175]
	global_load_lds_dwordx4 v[198:199], off
	s_add_i32 m0, s31, 0x2000
	s_nop 0
	global_load_lds_dwordx4 v[196:197], off
	v_lshl_add_u64 v[196:197], v[244:245], 0, s[22:23]
	s_mov_b32 m0, s56
	s_nop 0
	global_load_lds_dwordx4 v[196:197], off
	v_lshl_add_u64 v[196:197], v[246:247], 0, s[22:23]
	s_mov_b32 m0, s57
	s_nop 0
	global_load_lds_dwordx4 v[196:197], off
	s_waitcnt vmcnt(8)
	s_waitcnt lgkmcnt(0)
	s_barrier
	s_setprio 1
	s_waitcnt lgkmcnt(0)
	v_mfma_f32_16x16x32_bf16 v[126:129], v[138:141], v[208:211], v[126:129]
	v_mfma_f32_16x16x32_bf16 v[122:125], v[146:149], v[208:211], v[122:125]
	v_mfma_f32_16x16x32_bf16 v[118:121], v[138:141], v[216:219], v[118:121]
	v_mfma_f32_16x16x32_bf16 v[114:117], v[146:149], v[216:219], v[114:117]
	v_mfma_f32_16x16x32_bf16 v[110:113], v[138:141], v[224:227], v[110:113]
	v_mfma_f32_16x16x32_bf16 v[106:109], v[146:149], v[224:227], v[106:109]
	v_mfma_f32_16x16x32_bf16 v[102:105], v[138:141], v[232:235], v[102:105]
	v_mfma_f32_16x16x32_bf16 v[98:101], v[146:149], v[232:235], v[98:101]
	v_mfma_f32_16x16x32_bf16 v[126:129], v[142:145], v[212:215], v[126:129]
	v_mfma_f32_16x16x32_bf16 v[122:125], v[150:153], v[212:215], v[122:125]
	v_mfma_f32_16x16x32_bf16 v[118:121], v[142:145], v[220:223], v[118:121]
	v_mfma_f32_16x16x32_bf16 v[114:117], v[150:153], v[220:223], v[114:117]
	v_mfma_f32_16x16x32_bf16 v[110:113], v[142:145], v[228:231], v[110:113]
	v_mfma_f32_16x16x32_bf16 v[106:109], v[150:153], v[228:231], v[106:109]
	v_mfma_f32_16x16x32_bf16 v[102:105], v[142:145], v[236:239], v[102:105]
	v_mfma_f32_16x16x32_bf16 v[98:101], v[150:153], v[236:239], v[98:101]
	v_mfma_f32_16x16x32_bf16 v[94:97], v[154:157], v[208:211], v[94:97]
	v_mfma_f32_16x16x32_bf16 v[90:93], v[162:165], v[208:211], v[90:93]
	v_mfma_f32_16x16x32_bf16 v[86:89], v[154:157], v[216:219], v[86:89]
	v_mfma_f32_16x16x32_bf16 v[82:85], v[162:165], v[216:219], v[82:85]
	v_mfma_f32_16x16x32_bf16 v[78:81], v[154:157], v[224:227], v[78:81]
	v_mfma_f32_16x16x32_bf16 v[74:77], v[162:165], v[224:227], v[74:77]
	v_mfma_f32_16x16x32_bf16 v[70:73], v[154:157], v[232:235], v[70:73]
	v_mfma_f32_16x16x32_bf16 v[66:69], v[162:165], v[232:235], v[66:69]
	v_mfma_f32_16x16x32_bf16 v[94:97], v[158:161], v[212:215], v[94:97]
	v_mfma_f32_16x16x32_bf16 v[90:93], v[192:195], v[212:215], v[90:93]
	v_mfma_f32_16x16x32_bf16 v[86:89], v[158:161], v[220:223], v[86:89]
	v_mfma_f32_16x16x32_bf16 v[82:85], v[192:195], v[220:223], v[82:85]
	v_mfma_f32_16x16x32_bf16 v[78:81], v[158:161], v[228:231], v[78:81]
	v_mfma_f32_16x16x32_bf16 v[74:77], v[192:195], v[228:231], v[74:77]
	v_mfma_f32_16x16x32_bf16 v[70:73], v[158:161], v[236:239], v[70:73]
	v_mfma_f32_16x16x32_bf16 v[66:69], v[192:195], v[236:239], v[66:69]
	s_setprio 0
	s_barrier
	v_lshl_add_u64 v[134:135], v[134:135], 0, s[38:39]
	s_cmp_ge_i32 s13, s9
	v_lshl_add_u64 v[136:137], v[136:137], 0, s[38:39]
	s_cbranch_scc0 .LBB0_1065

.LBB0_1251:
	s_ashr_i32 s47, s46, 31
	s_lshl_b64 s[8:9], s[46:47], 19
	s_ashr_i32 s45, s44, 31
	v_lshl_add_u64 v[170:171], v[146:147], 0, s[8:9]
	s_lshl_b64 s[8:9], s[44:45], 19
	v_lshl_add_u64 v[172:173], v[148:149], 0, s[8:9]
	s_waitcnt vmcnt(0)
	v_cndmask_b32_e64 v84, v2, v172, s[4:5]
	v_lshl_add_u64 v[88:89], v[2:3], 0, s[40:41]
	v_mov_b32_e32 v2, 0
	v_cndmask_b32_e64 v1, v5, v171, s[4:5]
	v_cndmask_b32_e64 v82, v4, v170, s[4:5]
	v_cndmask_b32_e64 v83, v3, v173, s[4:5]
	v_lshl_add_u64 v[86:87], v[4:5], 0, s[28:29]
	s_mov_b32 s7, -2
	ds_read_b128 v[94:97], v181
	ds_read_b128 v[98:101], v181 offset:1024
	ds_read_b128 v[174:177], v181 offset:2048
	ds_read_b128 v[186:189], v181 offset:3072
	ds_read_b128 v[190:193], v183
	ds_read_b128 v[194:197], v183 offset:1024
	ds_read_b128 v[200:203], v183 offset:2048
	ds_read_b128 v[204:207], v183 offset:3072
	s_cmp_eq_u32 s7, 12
	v_lshl_add_u64 v[198:199], v[86:87], 0, s[42:43]
	s_cselect_b64 vcc, -1, 0
	v_cndmask_b32_e32 v199, v199, v1, vcc
	v_cndmask_b32_e32 v198, v198, v82, vcc
	v_cndmask_b32_e32 v241, v89, v83, vcc
	v_cndmask_b32_e32 v240, v88, v84, vcc
	v_lshl_add_u64 v[242:243], v[86:87], 0, v[160:161]
	s_add_i32 m0, s1, 0xc000
	ds_read_b128 v[208:211], v182
	ds_read_b128 v[212:215], v182 offset:1024
	ds_read_b128 v[216:219], v182 offset:2048
	ds_read_b128 v[220:223], v182 offset:3072
	ds_read_b128 v[224:227], v182 offset:4096
	ds_read_b128 v[228:231], v182 offset:5120
	ds_read_b128 v[232:235], v182 offset:6144
	ds_read_b128 v[236:239], v182 offset:7168
	global_load_lds_dwordx4 v[242:243], off
	v_lshl_add_u64 v[242:243], v[86:87], 0, v[162:163]
	s_add_i32 m0, s1, 0xe000
	s_nop 0
	global_load_lds_dwordx4 v[242:243], off
	s_waitcnt vmcnt(8)
	s_waitcnt lgkmcnt(0)
	s_barrier
	s_setprio 1
	s_waitcnt lgkmcnt(0)
	v_mfma_f32_16x16x32_bf16 v[102:105], v[94:97], v[208:211], 0
	v_mfma_f32_16x16x32_bf16 v[142:145], v[174:177], v[208:211], 0
	v_mfma_f32_16x16x32_bf16 v[62:65], v[94:97], v[216:219], 0
	v_mfma_f32_16x16x32_bf16 v[110:113], v[174:177], v[216:219], 0
	v_mfma_f32_16x16x32_bf16 v[46:49], v[94:97], v[224:227], 0
	v_mfma_f32_16x16x32_bf16 v[78:81], v[174:177], v[224:227], 0
	v_mfma_f32_16x16x32_bf16 v[38:41], v[94:97], v[232:235], 0
	v_mfma_f32_16x16x32_bf16 v[134:137], v[174:177], v[232:235], 0
	v_mfma_f32_16x16x32_bf16 v[102:105], v[98:101], v[212:215], v[102:105]
	v_mfma_f32_16x16x32_bf16 v[142:145], v[186:189], v[212:215], v[142:145]
	v_mfma_f32_16x16x32_bf16 v[62:65], v[98:101], v[220:223], v[62:65]
	v_mfma_f32_16x16x32_bf16 v[110:113], v[186:189], v[220:223], v[110:113]
	v_mfma_f32_16x16x32_bf16 v[46:49], v[98:101], v[228:231], v[46:49]
	v_mfma_f32_16x16x32_bf16 v[78:81], v[186:189], v[228:231], v[78:81]
	v_mfma_f32_16x16x32_bf16 v[38:41], v[98:101], v[236:239], v[38:41]
	v_mfma_f32_16x16x32_bf16 v[134:137], v[186:189], v[236:239], v[134:137]
	v_mfma_f32_16x16x32_bf16 v[138:141], v[190:193], v[208:211], 0
	v_mfma_f32_16x16x32_bf16 v[90:93], v[200:203], v[208:211], 0
	v_mfma_f32_16x16x32_bf16 v[106:109], v[190:193], v[216:219], 0
	v_mfma_f32_16x16x32_bf16 v[50:53], v[200:203], v[216:219], 0
	v_mfma_f32_16x16x32_bf16 v[74:77], v[190:193], v[224:227], 0
	v_mfma_f32_16x16x32_bf16 v[42:45], v[200:203], v[224:227], 0
	v_mfma_f32_16x16x32_bf16 v[130:133], v[190:193], v[232:235], 0
	v_mfma_f32_16x16x32_bf16 v[34:37], v[200:203], v[232:235], 0
	v_mfma_f32_16x16x32_bf16 v[138:141], v[194:197], v[212:215], v[138:141]
	v_mfma_f32_16x16x32_bf16 v[90:93], v[204:207], v[212:215], v[90:93]
	v_mfma_f32_16x16x32_bf16 v[106:109], v[194:197], v[220:223], v[106:109]
	v_mfma_f32_16x16x32_bf16 v[50:53], v[204:207], v[220:223], v[50:53]
	v_mfma_f32_16x16x32_bf16 v[74:77], v[194:197], v[228:231], v[74:77]
	v_mfma_f32_16x16x32_bf16 v[42:45], v[204:207], v[228:231], v[42:45]
	v_mfma_f32_16x16x32_bf16 v[130:133], v[194:197], v[236:239], v[130:133]
	v_mfma_f32_16x16x32_bf16 v[34:37], v[204:207], v[236:239], v[34:37]
	s_setprio 0
	s_barrier
	s_add_i32 s8, s55, s0
	v_lshl_add_u64 v[242:243], v[240:241], 0, v[150:151]
	s_mov_b32 m0, s8
	ds_read_b128 v[208:211], v182 offset:16384
	ds_read_b128 v[212:215], v182 offset:17408
	ds_read_b128 v[216:219], v182 offset:18432
	ds_read_b128 v[220:223], v182 offset:19456
	ds_read_b128 v[224:227], v182 offset:20480
	ds_read_b128 v[228:231], v182 offset:21504
	ds_read_b128 v[232:235], v182 offset:22528
	ds_read_b128 v[236:239], v182 offset:23552
	global_load_lds_dwordx4 v[242:243], off
	v_lshl_add_u64 v[244:245], v[240:241], 0, v[152:153]
	s_add_i32 m0, s8, 0x2000
	v_lshl_add_u64 v[246:247], v[240:241], 0, s[22:23]
	s_add_i32 s8, s56, s0
	global_load_lds_dwordx4 v[244:245], off
	v_lshl_add_u64 v[248:249], v[246:247], 0, v[150:151]
	s_mov_b32 m0, s8
	v_lshl_add_u64 v[246:247], v[246:247], 0, v[152:153]
	global_load_lds_dwordx4 v[248:249], off
	s_add_i32 m0, s8, 0x2000
	v_lshl_add_u64 v[248:249], v[198:199], 0, v[152:153]
	global_load_lds_dwordx4 v[246:247], off
	v_lshl_add_u64 v[246:247], v[198:199], 0, v[150:151]
	s_mov_b32 m0, s1
	s_nop 0
	global_load_lds_dwordx4 v[246:247], off
	s_mov_b32 m0, s2
	s_nop 0
	global_load_lds_dwordx4 v[248:249], off
	s_waitcnt vmcnt(8)
	s_waitcnt lgkmcnt(0)
	s_barrier
	s_setprio 1
	s_waitcnt lgkmcnt(0)
	v_mfma_f32_16x16x32_bf16 v[30:33], v[94:97], v[208:211], 0
	v_mfma_f32_16x16x32_bf16 v[126:129], v[174:177], v[208:211], 0
	v_mfma_f32_16x16x32_bf16 v[22:25], v[94:97], v[216:219], 0
	v_mfma_f32_16x16x32_bf16 v[70:73], v[174:177], v[216:219], 0
	v_mfma_f32_16x16x32_bf16 v[14:17], v[94:97], v[224:227], 0
	v_mfma_f32_16x16x32_bf16 v[66:69], v[174:177], v[224:227], 0
	v_mfma_f32_16x16x32_bf16 v[6:9], v[94:97], v[232:235], 0
	v_mfma_f32_16x16x32_bf16 v[30:33], v[98:101], v[212:215], v[30:33]
	v_mfma_f32_16x16x32_bf16 v[126:129], v[186:189], v[212:215], v[126:129]
	v_mfma_f32_16x16x32_bf16 v[22:25], v[98:101], v[220:223], v[22:25]
	v_mfma_f32_16x16x32_bf16 v[70:73], v[186:189], v[220:223], v[70:73]
	v_mfma_f32_16x16x32_bf16 v[14:17], v[98:101], v[228:231], v[14:17]
	v_mfma_f32_16x16x32_bf16 v[66:69], v[186:189], v[228:231], v[66:69]
	v_mfma_f32_16x16x32_bf16 v[6:9], v[98:101], v[236:239], v[6:9]
	v_mfma_f32_16x16x32_bf16 v[94:97], v[174:177], v[232:235], 0
	v_mfma_f32_16x16x32_bf16 v[94:97], v[186:189], v[236:239], v[94:97]
	v_mfma_f32_16x16x32_bf16 v[26:29], v[200:203], v[208:211], 0
	v_mfma_f32_16x16x32_bf16 v[58:61], v[190:193], v[216:219], 0
	v_mfma_f32_16x16x32_bf16 v[18:21], v[200:203], v[216:219], 0
	v_mfma_f32_16x16x32_bf16 v[54:57], v[190:193], v[224:227], 0
	v_mfma_f32_16x16x32_bf16 v[10:13], v[200:203], v[224:227], 0
	v_mfma_f32_16x16x32_bf16 v[114:117], v[190:193], v[232:235], 0
	v_mfma_f32_16x16x32_bf16 v[2:5], v[200:203], v[232:235], 0
	v_mfma_f32_16x16x32_bf16 v[98:101], v[190:193], v[208:211], 0
	v_mfma_f32_16x16x32_bf16 v[26:29], v[204:207], v[212:215], v[26:29]
	v_mfma_f32_16x16x32_bf16 v[58:61], v[194:197], v[220:223], v[58:61]
	v_mfma_f32_16x16x32_bf16 v[18:21], v[204:207], v[220:223], v[18:21]
	v_mfma_f32_16x16x32_bf16 v[54:57], v[194:197], v[228:231], v[54:57]
	v_mfma_f32_16x16x32_bf16 v[10:13], v[204:207], v[228:231], v[10:13]
	v_mfma_f32_16x16x32_bf16 v[114:117], v[194:197], v[236:239], v[114:117]
	v_mfma_f32_16x16x32_bf16 v[2:5], v[204:207], v[236:239], v[2:5]
	v_mfma_f32_16x16x32_bf16 v[98:101], v[194:197], v[212:215], v[98:101]
	s_setprio 0
	s_barrier
	s_add_i32 s8, 0, 0x18000
	v_add_u32_e32 v85, s8, v180
	s_add_i32 s9, 0, 0x1c000
	ds_read_b128 v[118:121], v85
	ds_read_b128 v[122:125], v85 offset:1024
	ds_read_b128 v[174:177], v85 offset:2048
	ds_read_b128 v[186:189], v85 offset:3072
	v_add_u32_e32 v85, s9, v180
	ds_read_b128 v[190:193], v85
	ds_read_b128 v[194:197], v85 offset:1024
	ds_read_b128 v[200:203], v85 offset:2048
	ds_read_b128 v[204:207], v85 offset:3072
	v_lshl_add_u64 v[198:199], v[198:199], 0, s[22:23]
	s_mov_b32 m0, s3
	v_lshl_add_u64 v[250:251], v[198:199], 0, v[150:151]
	ds_read_b128 v[208:211], v182 offset:32768
	ds_read_b128 v[212:215], v182 offset:33792
	ds_read_b128 v[216:219], v182 offset:34816
	ds_read_b128 v[220:223], v182 offset:35840
	ds_read_b128 v[224:227], v182 offset:36864
	ds_read_b128 v[228:231], v182 offset:37888
	ds_read_b128 v[232:235], v182 offset:38912
	ds_read_b128 v[236:239], v182 offset:39936
	global_load_lds_dwordx4 v[250:251], off
	v_lshl_add_u64 v[198:199], v[198:199], 0, v[152:153]
	s_mov_b32 m0, s21
	s_nop 0
	global_load_lds_dwordx4 v[198:199], off
	s_waitcnt vmcnt(8)
	s_waitcnt lgkmcnt(0)
	s_barrier
	s_setprio 1
	s_waitcnt lgkmcnt(0)
	v_mfma_f32_16x16x32_bf16 v[102:105], v[118:121], v[208:211], v[102:105]
	v_mfma_f32_16x16x32_bf16 v[142:145], v[174:177], v[208:211], v[142:145]
	v_mfma_f32_16x16x32_bf16 v[62:65], v[118:121], v[216:219], v[62:65]
	v_mfma_f32_16x16x32_bf16 v[110:113], v[174:177], v[216:219], v[110:113]
	v_mfma_f32_16x16x32_bf16 v[46:49], v[118:121], v[224:227], v[46:49]
	v_mfma_f32_16x16x32_bf16 v[78:81], v[174:177], v[224:227], v[78:81]
	v_mfma_f32_16x16x32_bf16 v[38:41], v[118:121], v[232:235], v[38:41]
	v_mfma_f32_16x16x32_bf16 v[134:137], v[174:177], v[232:235], v[134:137]
	v_mfma_f32_16x16x32_bf16 v[102:105], v[122:125], v[212:215], v[102:105]
	v_mfma_f32_16x16x32_bf16 v[142:145], v[186:189], v[212:215], v[142:145]
	v_mfma_f32_16x16x32_bf16 v[62:65], v[122:125], v[220:223], v[62:65]
	v_mfma_f32_16x16x32_bf16 v[110:113], v[186:189], v[220:223], v[110:113]
	v_mfma_f32_16x16x32_bf16 v[46:49], v[122:125], v[228:231], v[46:49]
	v_mfma_f32_16x16x32_bf16 v[78:81], v[186:189], v[228:231], v[78:81]
	v_mfma_f32_16x16x32_bf16 v[38:41], v[122:125], v[236:239], v[38:41]
	v_mfma_f32_16x16x32_bf16 v[134:137], v[186:189], v[236:239], v[134:137]
	v_mfma_f32_16x16x32_bf16 v[138:141], v[190:193], v[208:211], v[138:141]
	v_mfma_f32_16x16x32_bf16 v[90:93], v[200:203], v[208:211], v[90:93]
	v_mfma_f32_16x16x32_bf16 v[106:109], v[190:193], v[216:219], v[106:109]
	v_mfma_f32_16x16x32_bf16 v[50:53], v[200:203], v[216:219], v[50:53]
	v_mfma_f32_16x16x32_bf16 v[74:77], v[190:193], v[224:227], v[74:77]
	v_mfma_f32_16x16x32_bf16 v[42:45], v[200:203], v[224:227], v[42:45]
	v_mfma_f32_16x16x32_bf16 v[130:133], v[190:193], v[232:235], v[130:133]
	v_mfma_f32_16x16x32_bf16 v[34:37], v[200:203], v[232:235], v[34:37]
	v_mfma_f32_16x16x32_bf16 v[138:141], v[194:197], v[212:215], v[138:141]
	v_mfma_f32_16x16x32_bf16 v[90:93], v[204:207], v[212:215], v[90:93]
	v_mfma_f32_16x16x32_bf16 v[106:109], v[194:197], v[220:223], v[106:109]
	v_mfma_f32_16x16x32_bf16 v[50:53], v[204:207], v[220:223], v[50:53]
	v_mfma_f32_16x16x32_bf16 v[74:77], v[194:197], v[228:231], v[74:77]
	v_mfma_f32_16x16x32_bf16 v[42:45], v[204:207], v[228:231], v[42:45]
	v_mfma_f32_16x16x32_bf16 v[130:133], v[194:197], v[236:239], v[130:133]
	v_mfma_f32_16x16x32_bf16 v[34:37], v[204:207], v[236:239], v[34:37]
	s_setprio 0
	s_barrier
	s_add_i32 s8, s8, s0
	v_lshl_add_u64 v[198:199], v[242:243], 0, s[26:27]
	s_mov_b32 m0, s8
	ds_read_b128 v[208:211], v182 offset:49152
	ds_read_b128 v[212:215], v182 offset:50176
	ds_read_b128 v[216:219], v182 offset:51200
	ds_read_b128 v[220:223], v182 offset:52224
	ds_read_b128 v[224:227], v182 offset:53248
	ds_read_b128 v[228:231], v182 offset:54272
	ds_read_b128 v[232:235], v182 offset:55296
	ds_read_b128 v[236:239], v182 offset:56320
	global_load_lds_dwordx4 v[198:199], off
	v_lshl_add_u64 v[198:199], v[244:245], 0, s[26:27]
	s_add_i32 m0, s8, 0x2000
	s_add_i32 s8, s9, s0
	global_load_lds_dwordx4 v[198:199], off
	v_lshl_add_u64 v[198:199], v[240:241], 0, s[28:29]
	v_lshl_add_u64 v[240:241], v[198:199], 0, v[150:151]
	s_mov_b32 m0, s8
	v_lshl_add_u64 v[198:199], v[198:199], 0, v[152:153]
	global_load_lds_dwordx4 v[240:241], off
	s_add_i32 m0, s8, 0x2000
	s_nop 0
	global_load_lds_dwordx4 v[198:199], off
	v_lshl_add_u64 v[198:199], v[246:247], 0, s[26:27]
	s_mov_b32 m0, s35
	s_nop 0
	global_load_lds_dwordx4 v[198:199], off
	v_lshl_add_u64 v[198:199], v[248:249], 0, s[26:27]
	s_mov_b32 m0, s50
	s_nop 0
	global_load_lds_dwordx4 v[198:199], off
	s_waitcnt vmcnt(8)
	s_waitcnt lgkmcnt(0)
	s_barrier
	s_setprio 1
	s_waitcnt lgkmcnt(0)
	v_mfma_f32_16x16x32_bf16 v[30:33], v[118:121], v[208:211], v[30:33]
	v_mfma_f32_16x16x32_bf16 v[126:129], v[174:177], v[208:211], v[126:129]
	v_mfma_f32_16x16x32_bf16 v[22:25], v[118:121], v[216:219], v[22:25]
	v_mfma_f32_16x16x32_bf16 v[70:73], v[174:177], v[216:219], v[70:73]
	v_mfma_f32_16x16x32_bf16 v[14:17], v[118:121], v[224:227], v[14:17]
	v_mfma_f32_16x16x32_bf16 v[66:69], v[174:177], v[224:227], v[66:69]
	v_mfma_f32_16x16x32_bf16 v[6:9], v[118:121], v[232:235], v[6:9]
	v_mfma_f32_16x16x32_bf16 v[94:97], v[174:177], v[232:235], v[94:97]
	v_mfma_f32_16x16x32_bf16 v[30:33], v[122:125], v[212:215], v[30:33]
	v_mfma_f32_16x16x32_bf16 v[126:129], v[186:189], v[212:215], v[126:129]
	v_mfma_f32_16x16x32_bf16 v[22:25], v[122:125], v[220:223], v[22:25]
	v_mfma_f32_16x16x32_bf16 v[70:73], v[186:189], v[220:223], v[70:73]
	v_mfma_f32_16x16x32_bf16 v[14:17], v[122:125], v[228:231], v[14:17]
	v_mfma_f32_16x16x32_bf16 v[66:69], v[186:189], v[228:231], v[66:69]
	v_mfma_f32_16x16x32_bf16 v[6:9], v[122:125], v[236:239], v[6:9]
	v_mfma_f32_16x16x32_bf16 v[118:121], v[186:189], v[236:239], v[94:97]
	v_mfma_f32_16x16x32_bf16 v[94:97], v[190:193], v[208:211], v[98:101]
	v_mfma_f32_16x16x32_bf16 v[122:125], v[194:197], v[212:215], v[94:97]
	v_mfma_f32_16x16x32_bf16 v[26:29], v[200:203], v[208:211], v[26:29]
	v_mfma_f32_16x16x32_bf16 v[58:61], v[190:193], v[216:219], v[58:61]
	v_mfma_f32_16x16x32_bf16 v[18:21], v[200:203], v[216:219], v[18:21]
	v_mfma_f32_16x16x32_bf16 v[54:57], v[190:193], v[224:227], v[54:57]
	v_mfma_f32_16x16x32_bf16 v[10:13], v[200:203], v[224:227], v[10:13]
	v_mfma_f32_16x16x32_bf16 v[94:97], v[190:193], v[232:235], v[114:117]
	v_mfma_f32_16x16x32_bf16 v[2:5], v[200:203], v[232:235], v[2:5]
	v_mfma_f32_16x16x32_bf16 v[26:29], v[204:207], v[212:215], v[26:29]
	v_mfma_f32_16x16x32_bf16 v[58:61], v[194:197], v[220:223], v[58:61]
	v_mfma_f32_16x16x32_bf16 v[18:21], v[204:207], v[220:223], v[18:21]
	v_mfma_f32_16x16x32_bf16 v[54:57], v[194:197], v[228:231], v[54:57]
	v_mfma_f32_16x16x32_bf16 v[10:13], v[204:207], v[228:231], v[10:13]
	v_mfma_f32_16x16x32_bf16 v[114:117], v[194:197], v[236:239], v[94:97]
	v_mfma_f32_16x16x32_bf16 v[2:5], v[204:207], v[236:239], v[2:5]
	s_setprio 0
	s_barrier
	s_add_i32 s7, s7, 2
	v_lshl_add_u64 v[86:87], v[86:87], 0, s[40:41]
	s_cmp_gt_u32 s7, 13
	v_lshl_add_u64 v[88:89], v[88:89], 0, s[40:41]
	s_cbranch_scc0 .LBB0_1252
	s_branch .Lpeel_exit_4
.LBB0_1252:
	ds_read_b128 v[94:97], v181
	ds_read_b128 v[98:101], v181 offset:1024
	ds_read_b128 v[174:177], v181 offset:2048
	ds_read_b128 v[186:189], v181 offset:3072
	ds_read_b128 v[190:193], v183
	ds_read_b128 v[194:197], v183 offset:1024
	ds_read_b128 v[200:203], v183 offset:2048
	ds_read_b128 v[204:207], v183 offset:3072
	s_cmp_eq_u32 s7, 12
	v_lshl_add_u64 v[198:199], v[86:87], 0, s[42:43]
	s_cselect_b64 vcc, -1, 0
	v_cndmask_b32_e32 v199, v199, v1, vcc
	v_cndmask_b32_e32 v198, v198, v82, vcc
	v_cndmask_b32_e32 v241, v89, v83, vcc
	v_cndmask_b32_e32 v240, v88, v84, vcc
	v_lshl_add_u64 v[242:243], v[86:87], 0, v[160:161]
	s_add_i32 m0, s1, 0xc000
	ds_read_b128 v[208:211], v182
	ds_read_b128 v[212:215], v182 offset:1024
	ds_read_b128 v[216:219], v182 offset:2048
	ds_read_b128 v[220:223], v182 offset:3072
	ds_read_b128 v[224:227], v182 offset:4096
	ds_read_b128 v[228:231], v182 offset:5120
	ds_read_b128 v[232:235], v182 offset:6144
	ds_read_b128 v[236:239], v182 offset:7168
	global_load_lds_dwordx4 v[242:243], off
	v_lshl_add_u64 v[242:243], v[86:87], 0, v[162:163]
	s_add_i32 m0, s1, 0xe000
	s_nop 0
	global_load_lds_dwordx4 v[242:243], off
	s_waitcnt vmcnt(8)
	s_waitcnt lgkmcnt(0)
	s_barrier
	s_setprio 1
	s_waitcnt lgkmcnt(0)
	v_mfma_f32_16x16x32_bf16 v[102:105], v[94:97], v[208:211], v[102:105]
	v_mfma_f32_16x16x32_bf16 v[142:145], v[174:177], v[208:211], v[142:145]
	v_mfma_f32_16x16x32_bf16 v[62:65], v[94:97], v[216:219], v[62:65]
	v_mfma_f32_16x16x32_bf16 v[110:113], v[174:177], v[216:219], v[110:113]
	v_mfma_f32_16x16x32_bf16 v[46:49], v[94:97], v[224:227], v[46:49]
	v_mfma_f32_16x16x32_bf16 v[78:81], v[174:177], v[224:227], v[78:81]
	v_mfma_f32_16x16x32_bf16 v[38:41], v[94:97], v[232:235], v[38:41]
	v_mfma_f32_16x16x32_bf16 v[134:137], v[174:177], v[232:235], v[134:137]
	v_mfma_f32_16x16x32_bf16 v[102:105], v[98:101], v[212:215], v[102:105]
	v_mfma_f32_16x16x32_bf16 v[142:145], v[186:189], v[212:215], v[142:145]
	v_mfma_f32_16x16x32_bf16 v[62:65], v[98:101], v[220:223], v[62:65]
	v_mfma_f32_16x16x32_bf16 v[110:113], v[186:189], v[220:223], v[110:113]
	v_mfma_f32_16x16x32_bf16 v[46:49], v[98:101], v[228:231], v[46:49]
	v_mfma_f32_16x16x32_bf16 v[78:81], v[186:189], v[228:231], v[78:81]
	v_mfma_f32_16x16x32_bf16 v[38:41], v[98:101], v[236:239], v[38:41]
	v_mfma_f32_16x16x32_bf16 v[134:137], v[186:189], v[236:239], v[134:137]
	v_mfma_f32_16x16x32_bf16 v[138:141], v[190:193], v[208:211], v[138:141]
	v_mfma_f32_16x16x32_bf16 v[90:93], v[200:203], v[208:211], v[90:93]
	v_mfma_f32_16x16x32_bf16 v[106:109], v[190:193], v[216:219], v[106:109]
	v_mfma_f32_16x16x32_bf16 v[50:53], v[200:203], v[216:219], v[50:53]
	v_mfma_f32_16x16x32_bf16 v[74:77], v[190:193], v[224:227], v[74:77]
	v_mfma_f32_16x16x32_bf16 v[42:45], v[200:203], v[224:227], v[42:45]
	v_mfma_f32_16x16x32_bf16 v[130:133], v[190:193], v[232:235], v[130:133]
	v_mfma_f32_16x16x32_bf16 v[34:37], v[200:203], v[232:235], v[34:37]
	v_mfma_f32_16x16x32_bf16 v[138:141], v[194:197], v[212:215], v[138:141]
	v_mfma_f32_16x16x32_bf16 v[90:93], v[204:207], v[212:215], v[90:93]
	v_mfma_f32_16x16x32_bf16 v[106:109], v[194:197], v[220:223], v[106:109]
	v_mfma_f32_16x16x32_bf16 v[50:53], v[204:207], v[220:223], v[50:53]
	v_mfma_f32_16x16x32_bf16 v[74:77], v[194:197], v[228:231], v[74:77]
	v_mfma_f32_16x16x32_bf16 v[42:45], v[204:207], v[228:231], v[42:45]
	v_mfma_f32_16x16x32_bf16 v[130:133], v[194:197], v[236:239], v[130:133]
	v_mfma_f32_16x16x32_bf16 v[34:37], v[204:207], v[236:239], v[34:37]
	s_setprio 0
	s_barrier
	s_add_i32 s8, s55, s0
	v_lshl_add_u64 v[242:243], v[240:241], 0, v[150:151]
	s_mov_b32 m0, s8
	ds_read_b128 v[208:211], v182 offset:16384
	ds_read_b128 v[212:215], v182 offset:17408
	ds_read_b128 v[216:219], v182 offset:18432
	ds_read_b128 v[220:223], v182 offset:19456
	ds_read_b128 v[224:227], v182 offset:20480
	ds_read_b128 v[228:231], v182 offset:21504
	ds_read_b128 v[232:235], v182 offset:22528
	ds_read_b128 v[236:239], v182 offset:23552
	global_load_lds_dwordx4 v[242:243], off
	v_lshl_add_u64 v[244:245], v[240:241], 0, v[152:153]
	s_add_i32 m0, s8, 0x2000
	v_lshl_add_u64 v[246:247], v[240:241], 0, s[22:23]
	s_add_i32 s8, s56, s0
	global_load_lds_dwordx4 v[244:245], off
	v_lshl_add_u64 v[248:249], v[246:247], 0, v[150:151]
	s_mov_b32 m0, s8
	v_lshl_add_u64 v[246:247], v[246:247], 0, v[152:153]
	global_load_lds_dwordx4 v[248:249], off
	s_add_i32 m0, s8, 0x2000
	v_lshl_add_u64 v[248:249], v[198:199], 0, v[152:153]
	global_load_lds_dwordx4 v[246:247], off
	v_lshl_add_u64 v[246:247], v[198:199], 0, v[150:151]
	s_mov_b32 m0, s1
	s_nop 0
	global_load_lds_dwordx4 v[246:247], off
	s_mov_b32 m0, s2
	s_nop 0
	global_load_lds_dwordx4 v[248:249], off
	s_waitcnt vmcnt(8)
	s_waitcnt lgkmcnt(0)
	s_barrier
	s_setprio 1
	s_waitcnt lgkmcnt(0)
	v_mfma_f32_16x16x32_bf16 v[30:33], v[94:97], v[208:211], v[30:33]
	v_mfma_f32_16x16x32_bf16 v[126:129], v[174:177], v[208:211], v[126:129]
	v_mfma_f32_16x16x32_bf16 v[22:25], v[94:97], v[216:219], v[22:25]
	v_mfma_f32_16x16x32_bf16 v[70:73], v[174:177], v[216:219], v[70:73]
	v_mfma_f32_16x16x32_bf16 v[14:17], v[94:97], v[224:227], v[14:17]
	v_mfma_f32_16x16x32_bf16 v[66:69], v[174:177], v[224:227], v[66:69]
	v_mfma_f32_16x16x32_bf16 v[6:9], v[94:97], v[232:235], v[6:9]
	v_mfma_f32_16x16x32_bf16 v[30:33], v[98:101], v[212:215], v[30:33]
	v_mfma_f32_16x16x32_bf16 v[126:129], v[186:189], v[212:215], v[126:129]
	v_mfma_f32_16x16x32_bf16 v[22:25], v[98:101], v[220:223], v[22:25]
	v_mfma_f32_16x16x32_bf16 v[70:73], v[186:189], v[220:223], v[70:73]
	v_mfma_f32_16x16x32_bf16 v[14:17], v[98:101], v[228:231], v[14:17]
	v_mfma_f32_16x16x32_bf16 v[66:69], v[186:189], v[228:231], v[66:69]
	v_mfma_f32_16x16x32_bf16 v[6:9], v[98:101], v[236:239], v[6:9]
	v_mfma_f32_16x16x32_bf16 v[94:97], v[174:177], v[232:235], v[118:121]
	v_mfma_f32_16x16x32_bf16 v[94:97], v[186:189], v[236:239], v[94:97]
	v_mfma_f32_16x16x32_bf16 v[26:29], v[200:203], v[208:211], v[26:29]
	v_mfma_f32_16x16x32_bf16 v[58:61], v[190:193], v[216:219], v[58:61]
	v_mfma_f32_16x16x32_bf16 v[18:21], v[200:203], v[216:219], v[18:21]
	v_mfma_f32_16x16x32_bf16 v[54:57], v[190:193], v[224:227], v[54:57]
	v_mfma_f32_16x16x32_bf16 v[10:13], v[200:203], v[224:227], v[10:13]
	v_mfma_f32_16x16x32_bf16 v[114:117], v[190:193], v[232:235], v[114:117]
	v_mfma_f32_16x16x32_bf16 v[2:5], v[200:203], v[232:235], v[2:5]
	v_mfma_f32_16x16x32_bf16 v[98:101], v[190:193], v[208:211], v[122:125]
	v_mfma_f32_16x16x32_bf16 v[26:29], v[204:207], v[212:215], v[26:29]
	v_mfma_f32_16x16x32_bf16 v[58:61], v[194:197], v[220:223], v[58:61]
	v_mfma_f32_16x16x32_bf16 v[18:21], v[204:207], v[220:223], v[18:21]
	v_mfma_f32_16x16x32_bf16 v[54:57], v[194:197], v[228:231], v[54:57]
	v_mfma_f32_16x16x32_bf16 v[10:13], v[204:207], v[228:231], v[10:13]
	v_mfma_f32_16x16x32_bf16 v[114:117], v[194:197], v[236:239], v[114:117]
	v_mfma_f32_16x16x32_bf16 v[2:5], v[204:207], v[236:239], v[2:5]
	v_mfma_f32_16x16x32_bf16 v[98:101], v[194:197], v[212:215], v[98:101]
	s_setprio 0
	s_barrier
	s_add_i32 s8, 0, 0x18000
	v_add_u32_e32 v85, s8, v180
	s_add_i32 s9, 0, 0x1c000
	ds_read_b128 v[118:121], v85
	ds_read_b128 v[122:125], v85 offset:1024
	ds_read_b128 v[174:177], v85 offset:2048
	ds_read_b128 v[186:189], v85 offset:3072
	v_add_u32_e32 v85, s9, v180
	ds_read_b128 v[190:193], v85
	ds_read_b128 v[194:197], v85 offset:1024
	ds_read_b128 v[200:203], v85 offset:2048
	ds_read_b128 v[204:207], v85 offset:3072
	v_lshl_add_u64 v[198:199], v[198:199], 0, s[22:23]
	s_mov_b32 m0, s3
	v_lshl_add_u64 v[250:251], v[198:199], 0, v[150:151]
	ds_read_b128 v[208:211], v182 offset:32768
	ds_read_b128 v[212:215], v182 offset:33792
	ds_read_b128 v[216:219], v182 offset:34816
	ds_read_b128 v[220:223], v182 offset:35840
	ds_read_b128 v[224:227], v182 offset:36864
	ds_read_b128 v[228:231], v182 offset:37888
	ds_read_b128 v[232:235], v182 offset:38912
	ds_read_b128 v[236:239], v182 offset:39936
	global_load_lds_dwordx4 v[250:251], off
	v_lshl_add_u64 v[198:199], v[198:199], 0, v[152:153]
	s_mov_b32 m0, s21
	s_nop 0
	global_load_lds_dwordx4 v[198:199], off
	s_waitcnt vmcnt(8)
	s_waitcnt lgkmcnt(0)
	s_barrier
	s_setprio 1
	s_waitcnt lgkmcnt(0)
	v_mfma_f32_16x16x32_bf16 v[102:105], v[118:121], v[208:211], v[102:105]
	v_mfma_f32_16x16x32_bf16 v[142:145], v[174:177], v[208:211], v[142:145]
	v_mfma_f32_16x16x32_bf16 v[62:65], v[118:121], v[216:219], v[62:65]
	v_mfma_f32_16x16x32_bf16 v[110:113], v[174:177], v[216:219], v[110:113]
	v_mfma_f32_16x16x32_bf16 v[46:49], v[118:121], v[224:227], v[46:49]
	v_mfma_f32_16x16x32_bf16 v[78:81], v[174:177], v[224:227], v[78:81]
	v_mfma_f32_16x16x32_bf16 v[38:41], v[118:121], v[232:235], v[38:41]
	v_mfma_f32_16x16x32_bf16 v[134:137], v[174:177], v[232:235], v[134:137]
	v_mfma_f32_16x16x32_bf16 v[102:105], v[122:125], v[212:215], v[102:105]
	v_mfma_f32_16x16x32_bf16 v[142:145], v[186:189], v[212:215], v[142:145]
	v_mfma_f32_16x16x32_bf16 v[62:65], v[122:125], v[220:223], v[62:65]
	v_mfma_f32_16x16x32_bf16 v[110:113], v[186:189], v[220:223], v[110:113]
	v_mfma_f32_16x16x32_bf16 v[46:49], v[122:125], v[228:231], v[46:49]
	v_mfma_f32_16x16x32_bf16 v[78:81], v[186:189], v[228:231], v[78:81]
	v_mfma_f32_16x16x32_bf16 v[38:41], v[122:125], v[236:239], v[38:41]
	v_mfma_f32_16x16x32_bf16 v[134:137], v[186:189], v[236:239], v[134:137]
	v_mfma_f32_16x16x32_bf16 v[138:141], v[190:193], v[208:211], v[138:141]
	v_mfma_f32_16x16x32_bf16 v[90:93], v[200:203], v[208:211], v[90:93]
	v_mfma_f32_16x16x32_bf16 v[106:109], v[190:193], v[216:219], v[106:109]
	v_mfma_f32_16x16x32_bf16 v[50:53], v[200:203], v[216:219], v[50:53]
	v_mfma_f32_16x16x32_bf16 v[74:77], v[190:193], v[224:227], v[74:77]
	v_mfma_f32_16x16x32_bf16 v[42:45], v[200:203], v[224:227], v[42:45]
	v_mfma_f32_16x16x32_bf16 v[130:133], v[190:193], v[232:235], v[130:133]
	v_mfma_f32_16x16x32_bf16 v[34:37], v[200:203], v[232:235], v[34:37]
	v_mfma_f32_16x16x32_bf16 v[138:141], v[194:197], v[212:215], v[138:141]
	v_mfma_f32_16x16x32_bf16 v[90:93], v[204:207], v[212:215], v[90:93]
	v_mfma_f32_16x16x32_bf16 v[106:109], v[194:197], v[220:223], v[106:109]
	v_mfma_f32_16x16x32_bf16 v[50:53], v[204:207], v[220:223], v[50:53]
	v_mfma_f32_16x16x32_bf16 v[74:77], v[194:197], v[228:231], v[74:77]
	v_mfma_f32_16x16x32_bf16 v[42:45], v[204:207], v[228:231], v[42:45]
	v_mfma_f32_16x16x32_bf16 v[130:133], v[194:197], v[236:239], v[130:133]
	v_mfma_f32_16x16x32_bf16 v[34:37], v[204:207], v[236:239], v[34:37]
	s_setprio 0
	s_barrier
	s_add_i32 s8, s8, s0
	v_lshl_add_u64 v[198:199], v[242:243], 0, s[26:27]
	s_mov_b32 m0, s8
	ds_read_b128 v[208:211], v182 offset:49152
	ds_read_b128 v[212:215], v182 offset:50176
	ds_read_b128 v[216:219], v182 offset:51200
	ds_read_b128 v[220:223], v182 offset:52224
	ds_read_b128 v[224:227], v182 offset:53248
	ds_read_b128 v[228:231], v182 offset:54272
	ds_read_b128 v[232:235], v182 offset:55296
	ds_read_b128 v[236:239], v182 offset:56320
	global_load_lds_dwordx4 v[198:199], off
	v_lshl_add_u64 v[198:199], v[244:245], 0, s[26:27]
	s_add_i32 m0, s8, 0x2000
	s_add_i32 s8, s9, s0
	global_load_lds_dwordx4 v[198:199], off
	v_lshl_add_u64 v[198:199], v[240:241], 0, s[28:29]
	v_lshl_add_u64 v[240:241], v[198:199], 0, v[150:151]
	s_mov_b32 m0, s8
	v_lshl_add_u64 v[198:199], v[198:199], 0, v[152:153]
	global_load_lds_dwordx4 v[240:241], off
	s_add_i32 m0, s8, 0x2000
	s_nop 0
	global_load_lds_dwordx4 v[198:199], off
	v_lshl_add_u64 v[198:199], v[246:247], 0, s[26:27]
	s_mov_b32 m0, s35
	s_nop 0
	global_load_lds_dwordx4 v[198:199], off
	v_lshl_add_u64 v[198:199], v[248:249], 0, s[26:27]
	s_mov_b32 m0, s50
	s_nop 0
	global_load_lds_dwordx4 v[198:199], off
	s_waitcnt vmcnt(8)
	s_waitcnt lgkmcnt(0)
	s_barrier
	s_setprio 1
	s_waitcnt lgkmcnt(0)
	v_mfma_f32_16x16x32_bf16 v[30:33], v[118:121], v[208:211], v[30:33]
	v_mfma_f32_16x16x32_bf16 v[126:129], v[174:177], v[208:211], v[126:129]
	v_mfma_f32_16x16x32_bf16 v[22:25], v[118:121], v[216:219], v[22:25]
	v_mfma_f32_16x16x32_bf16 v[70:73], v[174:177], v[216:219], v[70:73]
	v_mfma_f32_16x16x32_bf16 v[14:17], v[118:121], v[224:227], v[14:17]
	v_mfma_f32_16x16x32_bf16 v[66:69], v[174:177], v[224:227], v[66:69]
	v_mfma_f32_16x16x32_bf16 v[6:9], v[118:121], v[232:235], v[6:9]
	v_mfma_f32_16x16x32_bf16 v[94:97], v[174:177], v[232:235], v[94:97]
	v_mfma_f32_16x16x32_bf16 v[30:33], v[122:125], v[212:215], v[30:33]
	v_mfma_f32_16x16x32_bf16 v[126:129], v[186:189], v[212:215], v[126:129]
	v_mfma_f32_16x16x32_bf16 v[22:25], v[122:125], v[220:223], v[22:25]
	v_mfma_f32_16x16x32_bf16 v[70:73], v[186:189], v[220:223], v[70:73]
	v_mfma_f32_16x16x32_bf16 v[14:17], v[122:125], v[228:231], v[14:17]
	v_mfma_f32_16x16x32_bf16 v[66:69], v[186:189], v[228:231], v[66:69]
	v_mfma_f32_16x16x32_bf16 v[6:9], v[122:125], v[236:239], v[6:9]
	v_mfma_f32_16x16x32_bf16 v[118:121], v[186:189], v[236:239], v[94:97]
	v_mfma_f32_16x16x32_bf16 v[94:97], v[190:193], v[208:211], v[98:101]
	v_mfma_f32_16x16x32_bf16 v[122:125], v[194:197], v[212:215], v[94:97]
	v_mfma_f32_16x16x32_bf16 v[26:29], v[200:203], v[208:211], v[26:29]
	v_mfma_f32_16x16x32_bf16 v[58:61], v[190:193], v[216:219], v[58:61]
	v_mfma_f32_16x16x32_bf16 v[18:21], v[200:203], v[216:219], v[18:21]
	v_mfma_f32_16x16x32_bf16 v[54:57], v[190:193], v[224:227], v[54:57]
	v_mfma_f32_16x16x32_bf16 v[10:13], v[200:203], v[224:227], v[10:13]
	v_mfma_f32_16x16x32_bf16 v[94:97], v[190:193], v[232:235], v[114:117]
	v_mfma_f32_16x16x32_bf16 v[2:5], v[200:203], v[232:235], v[2:5]
	v_mfma_f32_16x16x32_bf16 v[26:29], v[204:207], v[212:215], v[26:29]
	v_mfma_f32_16x16x32_bf16 v[58:61], v[194:197], v[220:223], v[58:61]
	v_mfma_f32_16x16x32_bf16 v[18:21], v[204:207], v[220:223], v[18:21]
	v_mfma_f32_16x16x32_bf16 v[54:57], v[194:197], v[228:231], v[54:57]
	v_mfma_f32_16x16x32_bf16 v[10:13], v[204:207], v[228:231], v[10:13]
	v_mfma_f32_16x16x32_bf16 v[114:117], v[194:197], v[236:239], v[94:97]
	v_mfma_f32_16x16x32_bf16 v[2:5], v[204:207], v[236:239], v[2:5]
	s_setprio 0
	s_barrier
	s_add_i32 s7, s7, 2
	v_lshl_add_u64 v[86:87], v[86:87], 0, s[40:41]
	s_cmp_gt_u32 s7, 13
	v_lshl_add_u64 v[88:89], v[88:89], 0, s[40:41]
	s_cbranch_scc0 .LBB0_1252

.LBB0_1382:
	s_ashr_i32 s35, s34, 31
	s_lshl_b64 s[42:43], s[34:35], 20
	s_ashr_i32 s37, s36, 31
	s_ashr_i32 s31, s30, 31
	v_lshl_add_u64 v[0:1], v[168:169], 0, s[42:43]
	s_lshl_b64 s[42:43], s[36:37], 7
	s_lshl_b64 s[44:45], s[30:31], 20
	v_lshl_add_u64 v[182:183], v[0:1], 0, s[42:43]
	v_lshl_add_u64 v[0:1], v[160:161], 0, s[44:45]
	v_lshl_add_u64 v[184:185], v[0:1], 0, s[42:43]
	v_mov_b32_e32 v64, 0
	v_cndmask_b32_e64 v129, v5, v183, s[38:39]
	v_cndmask_b32_e64 v128, v4, v182, s[38:39]
	v_cndmask_b32_e64 v131, v3, v185, s[38:39]
	v_cndmask_b32_e64 v130, v2, v184, s[38:39]
	s_add_i32 s31, s5, -2
	v_lshl_add_u64 v[132:133], v[4:5], 0, s[18:19]
	v_lshl_add_u64 v[134:135], v[2:3], 0, s[24:25]
	s_mov_b32 s35, 0
	v_add_u32_e32 v148, s57, v194
	v_add_u32_e32 v197, s58, v194
	ds_read_b128 v[136:139], v148
	ds_read_b128 v[140:143], v148 offset:1024
	ds_read_b128 v[144:147], v148 offset:2048
	ds_read_b128 v[148:151], v148 offset:3072
	ds_read_b128 v[152:155], v197
	ds_read_b128 v[156:159], v197 offset:1024
	ds_read_b128 v[186:189], v197 offset:2048
	ds_read_b128 v[198:201], v197 offset:3072
	s_cmp_eq_u32 s31, s35
	v_lshl_add_u64 v[190:191], v[132:133], 0, s[26:27]
	s_cselect_b64 vcc, -1, 0
	s_add_i32 s35, s35, 2
	v_cndmask_b32_e32 v191, v191, v129, vcc
	v_cndmask_b32_e32 v190, v190, v128, vcc
	v_cndmask_b32_e32 v235, v135, v131, vcc
	v_cndmask_b32_e32 v234, v134, v130, vcc
	v_lshl_add_u64 v[236:237], v[132:133], 0, v[178:179]
	s_add_i32 m0, s47, 0xc000
	ds_read_b128 v[202:205], v195
	ds_read_b128 v[206:209], v195 offset:1024
	ds_read_b128 v[210:213], v195 offset:2048
	ds_read_b128 v[214:217], v195 offset:3072
	ds_read_b128 v[218:221], v195 offset:4096
	ds_read_b128 v[222:225], v195 offset:5120
	ds_read_b128 v[226:229], v195 offset:6144
	ds_read_b128 v[230:233], v195 offset:7168
	global_load_lds_dwordx4 v[236:237], off
	v_lshl_add_u64 v[236:237], v[132:133], 0, v[180:181]
	s_add_i32 m0, s47, 0xe000
	s_nop 0
	global_load_lds_dwordx4 v[236:237], off
	s_waitcnt vmcnt(8)
	s_waitcnt lgkmcnt(0)
	s_barrier
	s_setprio 1
	s_waitcnt lgkmcnt(0)
	v_mfma_f32_16x16x32_bf16 v[60:63], v[136:139], v[202:205], 0
	v_mfma_f32_16x16x32_bf16 v[56:59], v[144:147], v[202:205], 0
	v_mfma_f32_16x16x32_bf16 v[52:55], v[136:139], v[210:213], 0
	v_mfma_f32_16x16x32_bf16 v[48:51], v[144:147], v[210:213], 0
	v_mfma_f32_16x16x32_bf16 v[44:47], v[136:139], v[218:221], 0
	v_mfma_f32_16x16x32_bf16 v[40:43], v[144:147], v[218:221], 0
	v_mfma_f32_16x16x32_bf16 v[36:39], v[136:139], v[226:229], 0
	v_mfma_f32_16x16x32_bf16 v[32:35], v[144:147], v[226:229], 0
	v_mfma_f32_16x16x32_bf16 v[60:63], v[140:143], v[206:209], v[60:63]
	v_mfma_f32_16x16x32_bf16 v[56:59], v[148:151], v[206:209], v[56:59]
	v_mfma_f32_16x16x32_bf16 v[52:55], v[140:143], v[214:217], v[52:55]
	v_mfma_f32_16x16x32_bf16 v[48:51], v[148:151], v[214:217], v[48:51]
	v_mfma_f32_16x16x32_bf16 v[44:47], v[140:143], v[222:225], v[44:47]
	v_mfma_f32_16x16x32_bf16 v[40:43], v[148:151], v[222:225], v[40:43]
	v_mfma_f32_16x16x32_bf16 v[36:39], v[140:143], v[230:233], v[36:39]
	v_mfma_f32_16x16x32_bf16 v[32:35], v[148:151], v[230:233], v[32:35]
	v_mfma_f32_16x16x32_bf16 v[28:31], v[152:155], v[202:205], 0
	v_mfma_f32_16x16x32_bf16 v[24:27], v[186:189], v[202:205], 0
	v_mfma_f32_16x16x32_bf16 v[20:23], v[152:155], v[210:213], 0
	v_mfma_f32_16x16x32_bf16 v[16:19], v[186:189], v[210:213], 0
	v_mfma_f32_16x16x32_bf16 v[12:15], v[152:155], v[218:221], 0
	v_mfma_f32_16x16x32_bf16 v[8:11], v[186:189], v[218:221], 0
	v_mfma_f32_16x16x32_bf16 v[4:7], v[152:155], v[226:229], 0
	v_mfma_f32_16x16x32_bf16 v[0:3], v[186:189], v[226:229], 0
	v_mfma_f32_16x16x32_bf16 v[28:31], v[156:159], v[206:209], v[28:31]
	v_mfma_f32_16x16x32_bf16 v[24:27], v[198:201], v[206:209], v[24:27]
	v_mfma_f32_16x16x32_bf16 v[20:23], v[156:159], v[214:217], v[20:23]
	v_mfma_f32_16x16x32_bf16 v[16:19], v[198:201], v[214:217], v[16:19]
	v_mfma_f32_16x16x32_bf16 v[12:15], v[156:159], v[222:225], v[12:15]
	v_mfma_f32_16x16x32_bf16 v[8:11], v[198:201], v[222:225], v[8:11]
	v_mfma_f32_16x16x32_bf16 v[4:7], v[156:159], v[230:233], v[4:7]
	v_mfma_f32_16x16x32_bf16 v[0:3], v[198:201], v[230:233], v[0:3]
	s_setprio 0
	s_barrier
	s_add_i32 s37, s57, s3
	v_lshl_add_u64 v[236:237], v[234:235], 0, v[162:163]
	s_mov_b32 m0, s37
	ds_read_b128 v[202:205], v195 offset:16384
	ds_read_b128 v[206:209], v195 offset:17408
	ds_read_b128 v[210:213], v195 offset:18432
	ds_read_b128 v[214:217], v195 offset:19456
	ds_read_b128 v[218:221], v195 offset:20480
	ds_read_b128 v[222:225], v195 offset:21504
	ds_read_b128 v[226:229], v195 offset:22528
	ds_read_b128 v[230:233], v195 offset:23552
	global_load_lds_dwordx4 v[236:237], off
	v_lshl_add_u64 v[238:239], v[234:235], 0, v[164:165]
	s_add_i32 m0, s37, 0x2000
	v_lshl_add_u64 v[240:241], v[234:235], 0, s[12:13]
	s_add_i32 s37, s58, s3
	global_load_lds_dwordx4 v[238:239], off
	v_lshl_add_u64 v[242:243], v[240:241], 0, v[162:163]
	s_mov_b32 m0, s37
	v_lshl_add_u64 v[240:241], v[240:241], 0, v[164:165]
	global_load_lds_dwordx4 v[242:243], off
	s_add_i32 m0, s37, 0x2000
	v_lshl_add_u64 v[242:243], v[190:191], 0, v[164:165]
	global_load_lds_dwordx4 v[240:241], off
	v_lshl_add_u64 v[240:241], v[190:191], 0, v[162:163]
	s_mov_b32 m0, s47
	s_nop 0
	global_load_lds_dwordx4 v[240:241], off
	s_mov_b32 m0, s48
	s_nop 0
	global_load_lds_dwordx4 v[242:243], off
	s_waitcnt vmcnt(8)
	s_waitcnt lgkmcnt(0)
	s_barrier
	s_setprio 1
	s_waitcnt lgkmcnt(0)
	v_mfma_f32_16x16x32_bf16 v[124:127], v[136:139], v[202:205], 0
	v_mfma_f32_16x16x32_bf16 v[120:123], v[144:147], v[202:205], 0
	v_mfma_f32_16x16x32_bf16 v[116:119], v[136:139], v[210:213], 0
	v_mfma_f32_16x16x32_bf16 v[112:115], v[144:147], v[210:213], 0
	v_mfma_f32_16x16x32_bf16 v[108:111], v[136:139], v[218:221], 0
	v_mfma_f32_16x16x32_bf16 v[104:107], v[144:147], v[218:221], 0
	v_mfma_f32_16x16x32_bf16 v[100:103], v[136:139], v[226:229], 0
	v_mfma_f32_16x16x32_bf16 v[96:99], v[144:147], v[226:229], 0
	v_mfma_f32_16x16x32_bf16 v[124:127], v[140:143], v[206:209], v[124:127]
	v_mfma_f32_16x16x32_bf16 v[120:123], v[148:151], v[206:209], v[120:123]
	v_mfma_f32_16x16x32_bf16 v[116:119], v[140:143], v[214:217], v[116:119]
	v_mfma_f32_16x16x32_bf16 v[112:115], v[148:151], v[214:217], v[112:115]
	v_mfma_f32_16x16x32_bf16 v[108:111], v[140:143], v[222:225], v[108:111]
	v_mfma_f32_16x16x32_bf16 v[104:107], v[148:151], v[222:225], v[104:107]
	v_mfma_f32_16x16x32_bf16 v[100:103], v[140:143], v[230:233], v[100:103]
	v_mfma_f32_16x16x32_bf16 v[96:99], v[148:151], v[230:233], v[96:99]
	v_mfma_f32_16x16x32_bf16 v[92:95], v[152:155], v[202:205], 0
	v_mfma_f32_16x16x32_bf16 v[88:91], v[186:189], v[202:205], 0
	v_mfma_f32_16x16x32_bf16 v[84:87], v[152:155], v[210:213], 0
	v_mfma_f32_16x16x32_bf16 v[80:83], v[186:189], v[210:213], 0
	v_mfma_f32_16x16x32_bf16 v[76:79], v[152:155], v[218:221], 0
	v_mfma_f32_16x16x32_bf16 v[72:75], v[186:189], v[218:221], 0
	v_mfma_f32_16x16x32_bf16 v[68:71], v[152:155], v[226:229], 0
	v_mfma_f32_16x16x32_bf16 v[64:67], v[186:189], v[226:229], 0
	v_mfma_f32_16x16x32_bf16 v[92:95], v[156:159], v[206:209], v[92:95]
	v_mfma_f32_16x16x32_bf16 v[88:91], v[198:201], v[206:209], v[88:91]
	v_mfma_f32_16x16x32_bf16 v[84:87], v[156:159], v[214:217], v[84:87]
	v_mfma_f32_16x16x32_bf16 v[80:83], v[198:201], v[214:217], v[80:83]
	v_mfma_f32_16x16x32_bf16 v[76:79], v[156:159], v[222:225], v[76:79]
	v_mfma_f32_16x16x32_bf16 v[72:75], v[198:201], v[222:225], v[72:75]
	v_mfma_f32_16x16x32_bf16 v[68:71], v[156:159], v[230:233], v[68:71]
	v_mfma_f32_16x16x32_bf16 v[64:67], v[198:201], v[230:233], v[64:67]
	s_setprio 0
	s_barrier
	s_add_i32 s37, 0, 0x18000
	s_add_i32 s41, 0, 0x1c000
	v_add_u32_e32 v148, s37, v194
	v_add_u32_e32 v197, s41, v194
	ds_read_b128 v[136:139], v148
	ds_read_b128 v[140:143], v148 offset:1024
	ds_read_b128 v[144:147], v148 offset:2048
	ds_read_b128 v[148:151], v148 offset:3072
	ds_read_b128 v[152:155], v197
	ds_read_b128 v[156:159], v197 offset:1024
	ds_read_b128 v[186:189], v197 offset:2048
	ds_read_b128 v[198:201], v197 offset:3072
	v_lshl_add_u64 v[190:191], v[190:191], 0, s[12:13]
	s_mov_b32 m0, s49
	v_lshl_add_u64 v[244:245], v[190:191], 0, v[162:163]
	ds_read_b128 v[202:205], v195 offset:32768
	ds_read_b128 v[206:209], v195 offset:33792
	ds_read_b128 v[210:213], v195 offset:34816
	ds_read_b128 v[214:217], v195 offset:35840
	ds_read_b128 v[218:221], v195 offset:36864
	ds_read_b128 v[222:225], v195 offset:37888
	ds_read_b128 v[226:229], v195 offset:38912
	ds_read_b128 v[230:233], v195 offset:39936
	global_load_lds_dwordx4 v[244:245], off
	v_lshl_add_u64 v[190:191], v[190:191], 0, v[164:165]
	s_mov_b32 m0, s50
	s_nop 0
	global_load_lds_dwordx4 v[190:191], off
	s_waitcnt vmcnt(8)
	s_waitcnt lgkmcnt(0)
	s_barrier
	s_setprio 1
	s_waitcnt lgkmcnt(0)
	v_mfma_f32_16x16x32_bf16 v[60:63], v[136:139], v[202:205], v[60:63]
	v_mfma_f32_16x16x32_bf16 v[56:59], v[144:147], v[202:205], v[56:59]
	v_mfma_f32_16x16x32_bf16 v[52:55], v[136:139], v[210:213], v[52:55]
	v_mfma_f32_16x16x32_bf16 v[48:51], v[144:147], v[210:213], v[48:51]
	v_mfma_f32_16x16x32_bf16 v[44:47], v[136:139], v[218:221], v[44:47]
	v_mfma_f32_16x16x32_bf16 v[40:43], v[144:147], v[218:221], v[40:43]
	v_mfma_f32_16x16x32_bf16 v[36:39], v[136:139], v[226:229], v[36:39]
	v_mfma_f32_16x16x32_bf16 v[32:35], v[144:147], v[226:229], v[32:35]
	v_mfma_f32_16x16x32_bf16 v[60:63], v[140:143], v[206:209], v[60:63]
	v_mfma_f32_16x16x32_bf16 v[56:59], v[148:151], v[206:209], v[56:59]
	v_mfma_f32_16x16x32_bf16 v[52:55], v[140:143], v[214:217], v[52:55]
	v_mfma_f32_16x16x32_bf16 v[48:51], v[148:151], v[214:217], v[48:51]
	v_mfma_f32_16x16x32_bf16 v[44:47], v[140:143], v[222:225], v[44:47]
	v_mfma_f32_16x16x32_bf16 v[40:43], v[148:151], v[222:225], v[40:43]
	v_mfma_f32_16x16x32_bf16 v[36:39], v[140:143], v[230:233], v[36:39]
	v_mfma_f32_16x16x32_bf16 v[32:35], v[148:151], v[230:233], v[32:35]
	v_mfma_f32_16x16x32_bf16 v[28:31], v[152:155], v[202:205], v[28:31]
	v_mfma_f32_16x16x32_bf16 v[24:27], v[186:189], v[202:205], v[24:27]
	v_mfma_f32_16x16x32_bf16 v[20:23], v[152:155], v[210:213], v[20:23]
	v_mfma_f32_16x16x32_bf16 v[16:19], v[186:189], v[210:213], v[16:19]
	v_mfma_f32_16x16x32_bf16 v[12:15], v[152:155], v[218:221], v[12:15]
	v_mfma_f32_16x16x32_bf16 v[8:11], v[186:189], v[218:221], v[8:11]
	v_mfma_f32_16x16x32_bf16 v[4:7], v[152:155], v[226:229], v[4:7]
	v_mfma_f32_16x16x32_bf16 v[0:3], v[186:189], v[226:229], v[0:3]
	v_mfma_f32_16x16x32_bf16 v[28:31], v[156:159], v[206:209], v[28:31]
	v_mfma_f32_16x16x32_bf16 v[24:27], v[198:201], v[206:209], v[24:27]
	v_mfma_f32_16x16x32_bf16 v[20:23], v[156:159], v[214:217], v[20:23]
	v_mfma_f32_16x16x32_bf16 v[16:19], v[198:201], v[214:217], v[16:19]
	v_mfma_f32_16x16x32_bf16 v[12:15], v[156:159], v[222:225], v[12:15]
	v_mfma_f32_16x16x32_bf16 v[8:11], v[198:201], v[222:225], v[8:11]
	v_mfma_f32_16x16x32_bf16 v[4:7], v[156:159], v[230:233], v[4:7]
	v_mfma_f32_16x16x32_bf16 v[0:3], v[198:201], v[230:233], v[0:3]
	s_setprio 0
	s_barrier
	s_add_i32 s37, s37, s3
	v_lshl_add_u64 v[190:191], v[236:237], 0, s[16:17]
	s_mov_b32 m0, s37
	ds_read_b128 v[202:205], v195 offset:49152
	ds_read_b128 v[206:209], v195 offset:50176
	ds_read_b128 v[210:213], v195 offset:51200
	ds_read_b128 v[214:217], v195 offset:52224
	ds_read_b128 v[218:221], v195 offset:53248
	ds_read_b128 v[222:225], v195 offset:54272
	ds_read_b128 v[226:229], v195 offset:55296
	ds_read_b128 v[230:233], v195 offset:56320
	global_load_lds_dwordx4 v[190:191], off
	v_lshl_add_u64 v[190:191], v[238:239], 0, s[16:17]
	s_add_i32 m0, s37, 0x2000
	s_add_i32 s37, s41, s3
	global_load_lds_dwordx4 v[190:191], off
	v_lshl_add_u64 v[190:191], v[234:235], 0, s[18:19]
	v_lshl_add_u64 v[234:235], v[190:191], 0, v[162:163]
	s_mov_b32 m0, s37
	v_lshl_add_u64 v[190:191], v[190:191], 0, v[164:165]
	global_load_lds_dwordx4 v[234:235], off
	s_add_i32 m0, s37, 0x2000
	s_nop 0
	global_load_lds_dwordx4 v[190:191], off
	v_lshl_add_u64 v[190:191], v[240:241], 0, s[16:17]
	s_mov_b32 m0, s52
	s_nop 0
	global_load_lds_dwordx4 v[190:191], off
	v_lshl_add_u64 v[190:191], v[242:243], 0, s[16:17]
	s_mov_b32 m0, s53
	s_nop 0
	global_load_lds_dwordx4 v[190:191], off
	s_waitcnt vmcnt(8)
	s_waitcnt lgkmcnt(0)
	s_barrier
	s_setprio 1
	s_waitcnt lgkmcnt(0)
	v_mfma_f32_16x16x32_bf16 v[124:127], v[136:139], v[202:205], v[124:127]
	v_mfma_f32_16x16x32_bf16 v[120:123], v[144:147], v[202:205], v[120:123]
	v_mfma_f32_16x16x32_bf16 v[116:119], v[136:139], v[210:213], v[116:119]
	v_mfma_f32_16x16x32_bf16 v[112:115], v[144:147], v[210:213], v[112:115]
	v_mfma_f32_16x16x32_bf16 v[108:111], v[136:139], v[218:221], v[108:111]
	v_mfma_f32_16x16x32_bf16 v[104:107], v[144:147], v[218:221], v[104:107]
	v_mfma_f32_16x16x32_bf16 v[100:103], v[136:139], v[226:229], v[100:103]
	v_mfma_f32_16x16x32_bf16 v[96:99], v[144:147], v[226:229], v[96:99]
	v_mfma_f32_16x16x32_bf16 v[124:127], v[140:143], v[206:209], v[124:127]
	v_mfma_f32_16x16x32_bf16 v[120:123], v[148:151], v[206:209], v[120:123]
	v_mfma_f32_16x16x32_bf16 v[116:119], v[140:143], v[214:217], v[116:119]
	v_mfma_f32_16x16x32_bf16 v[112:115], v[148:151], v[214:217], v[112:115]
	v_mfma_f32_16x16x32_bf16 v[108:111], v[140:143], v[222:225], v[108:111]
	v_mfma_f32_16x16x32_bf16 v[104:107], v[148:151], v[222:225], v[104:107]
	v_mfma_f32_16x16x32_bf16 v[100:103], v[140:143], v[230:233], v[100:103]
	v_mfma_f32_16x16x32_bf16 v[96:99], v[148:151], v[230:233], v[96:99]
	v_mfma_f32_16x16x32_bf16 v[92:95], v[152:155], v[202:205], v[92:95]
	v_mfma_f32_16x16x32_bf16 v[88:91], v[186:189], v[202:205], v[88:91]
	v_mfma_f32_16x16x32_bf16 v[84:87], v[152:155], v[210:213], v[84:87]
	v_mfma_f32_16x16x32_bf16 v[80:83], v[186:189], v[210:213], v[80:83]
	v_mfma_f32_16x16x32_bf16 v[76:79], v[152:155], v[218:221], v[76:79]
	v_mfma_f32_16x16x32_bf16 v[72:75], v[186:189], v[218:221], v[72:75]
	v_mfma_f32_16x16x32_bf16 v[68:71], v[152:155], v[226:229], v[68:71]
	v_mfma_f32_16x16x32_bf16 v[64:67], v[186:189], v[226:229], v[64:67]
	v_mfma_f32_16x16x32_bf16 v[92:95], v[156:159], v[206:209], v[92:95]
	v_mfma_f32_16x16x32_bf16 v[88:91], v[198:201], v[206:209], v[88:91]
	v_mfma_f32_16x16x32_bf16 v[84:87], v[156:159], v[214:217], v[84:87]
	v_mfma_f32_16x16x32_bf16 v[80:83], v[198:201], v[214:217], v[80:83]
	v_mfma_f32_16x16x32_bf16 v[76:79], v[156:159], v[222:225], v[76:79]
	v_mfma_f32_16x16x32_bf16 v[72:75], v[198:201], v[222:225], v[72:75]
	v_mfma_f32_16x16x32_bf16 v[68:71], v[156:159], v[230:233], v[68:71]
	v_mfma_f32_16x16x32_bf16 v[64:67], v[198:201], v[230:233], v[64:67]
	s_setprio 0
	s_barrier
	v_lshl_add_u64 v[132:133], v[132:133], 0, s[24:25]
	s_cmp_ge_i32 s35, s5
	v_lshl_add_u64 v[134:135], v[134:135], 0, s[24:25]
	s_cbranch_scc0 .LBB0_1383
	s_branch .Lpeel_exit_5
.LBB0_1383:
	v_add_u32_e32 v148, s57, v194
	v_add_u32_e32 v197, s58, v194
	ds_read_b128 v[136:139], v148
	ds_read_b128 v[140:143], v148 offset:1024
	ds_read_b128 v[144:147], v148 offset:2048
	ds_read_b128 v[148:151], v148 offset:3072
	ds_read_b128 v[152:155], v197
	ds_read_b128 v[156:159], v197 offset:1024
	ds_read_b128 v[186:189], v197 offset:2048
	ds_read_b128 v[198:201], v197 offset:3072
	s_cmp_eq_u32 s31, s35
	v_lshl_add_u64 v[190:191], v[132:133], 0, s[26:27]
	s_cselect_b64 vcc, -1, 0
	s_add_i32 s35, s35, 2
	v_cndmask_b32_e32 v191, v191, v129, vcc
	v_cndmask_b32_e32 v190, v190, v128, vcc
	v_cndmask_b32_e32 v235, v135, v131, vcc
	v_cndmask_b32_e32 v234, v134, v130, vcc
	v_lshl_add_u64 v[236:237], v[132:133], 0, v[178:179]
	s_add_i32 m0, s47, 0xc000
	ds_read_b128 v[202:205], v195
	ds_read_b128 v[206:209], v195 offset:1024
	ds_read_b128 v[210:213], v195 offset:2048
	ds_read_b128 v[214:217], v195 offset:3072
	ds_read_b128 v[218:221], v195 offset:4096
	ds_read_b128 v[222:225], v195 offset:5120
	ds_read_b128 v[226:229], v195 offset:6144
	ds_read_b128 v[230:233], v195 offset:7168
	global_load_lds_dwordx4 v[236:237], off
	v_lshl_add_u64 v[236:237], v[132:133], 0, v[180:181]
	s_add_i32 m0, s47, 0xe000
	s_nop 0
	global_load_lds_dwordx4 v[236:237], off
	s_waitcnt vmcnt(8)
	s_waitcnt lgkmcnt(0)
	s_barrier
	s_setprio 1
	s_waitcnt lgkmcnt(0)
	v_mfma_f32_16x16x32_bf16 v[60:63], v[136:139], v[202:205], v[60:63]
	v_mfma_f32_16x16x32_bf16 v[56:59], v[144:147], v[202:205], v[56:59]
	v_mfma_f32_16x16x32_bf16 v[52:55], v[136:139], v[210:213], v[52:55]
	v_mfma_f32_16x16x32_bf16 v[48:51], v[144:147], v[210:213], v[48:51]
	v_mfma_f32_16x16x32_bf16 v[44:47], v[136:139], v[218:221], v[44:47]
	v_mfma_f32_16x16x32_bf16 v[40:43], v[144:147], v[218:221], v[40:43]
	v_mfma_f32_16x16x32_bf16 v[36:39], v[136:139], v[226:229], v[36:39]
	v_mfma_f32_16x16x32_bf16 v[32:35], v[144:147], v[226:229], v[32:35]
	v_mfma_f32_16x16x32_bf16 v[60:63], v[140:143], v[206:209], v[60:63]
	v_mfma_f32_16x16x32_bf16 v[56:59], v[148:151], v[206:209], v[56:59]
	v_mfma_f32_16x16x32_bf16 v[52:55], v[140:143], v[214:217], v[52:55]
	v_mfma_f32_16x16x32_bf16 v[48:51], v[148:151], v[214:217], v[48:51]
	v_mfma_f32_16x16x32_bf16 v[44:47], v[140:143], v[222:225], v[44:47]
	v_mfma_f32_16x16x32_bf16 v[40:43], v[148:151], v[222:225], v[40:43]
	v_mfma_f32_16x16x32_bf16 v[36:39], v[140:143], v[230:233], v[36:39]
	v_mfma_f32_16x16x32_bf16 v[32:35], v[148:151], v[230:233], v[32:35]
	v_mfma_f32_16x16x32_bf16 v[28:31], v[152:155], v[202:205], v[28:31]
	v_mfma_f32_16x16x32_bf16 v[24:27], v[186:189], v[202:205], v[24:27]
	v_mfma_f32_16x16x32_bf16 v[20:23], v[152:155], v[210:213], v[20:23]
	v_mfma_f32_16x16x32_bf16 v[16:19], v[186:189], v[210:213], v[16:19]
	v_mfma_f32_16x16x32_bf16 v[12:15], v[152:155], v[218:221], v[12:15]
	v_mfma_f32_16x16x32_bf16 v[8:11], v[186:189], v[218:221], v[8:11]
	v_mfma_f32_16x16x32_bf16 v[4:7], v[152:155], v[226:229], v[4:7]
	v_mfma_f32_16x16x32_bf16 v[0:3], v[186:189], v[226:229], v[0:3]
	v_mfma_f32_16x16x32_bf16 v[28:31], v[156:159], v[206:209], v[28:31]
	v_mfma_f32_16x16x32_bf16 v[24:27], v[198:201], v[206:209], v[24:27]
	v_mfma_f32_16x16x32_bf16 v[20:23], v[156:159], v[214:217], v[20:23]
	v_mfma_f32_16x16x32_bf16 v[16:19], v[198:201], v[214:217], v[16:19]
	v_mfma_f32_16x16x32_bf16 v[12:15], v[156:159], v[222:225], v[12:15]
	v_mfma_f32_16x16x32_bf16 v[8:11], v[198:201], v[222:225], v[8:11]
	v_mfma_f32_16x16x32_bf16 v[4:7], v[156:159], v[230:233], v[4:7]
	v_mfma_f32_16x16x32_bf16 v[0:3], v[198:201], v[230:233], v[0:3]
	s_setprio 0
	s_barrier
	s_add_i32 s37, s57, s3
	v_lshl_add_u64 v[236:237], v[234:235], 0, v[162:163]
	s_mov_b32 m0, s37
	ds_read_b128 v[202:205], v195 offset:16384
	ds_read_b128 v[206:209], v195 offset:17408
	ds_read_b128 v[210:213], v195 offset:18432
	ds_read_b128 v[214:217], v195 offset:19456
	ds_read_b128 v[218:221], v195 offset:20480
	ds_read_b128 v[222:225], v195 offset:21504
	ds_read_b128 v[226:229], v195 offset:22528
	ds_read_b128 v[230:233], v195 offset:23552
	global_load_lds_dwordx4 v[236:237], off
	v_lshl_add_u64 v[238:239], v[234:235], 0, v[164:165]
	s_add_i32 m0, s37, 0x2000
	v_lshl_add_u64 v[240:241], v[234:235], 0, s[12:13]
	s_add_i32 s37, s58, s3
	global_load_lds_dwordx4 v[238:239], off
	v_lshl_add_u64 v[242:243], v[240:241], 0, v[162:163]
	s_mov_b32 m0, s37
	v_lshl_add_u64 v[240:241], v[240:241], 0, v[164:165]
	global_load_lds_dwordx4 v[242:243], off
	s_add_i32 m0, s37, 0x2000
	v_lshl_add_u64 v[242:243], v[190:191], 0, v[164:165]
	global_load_lds_dwordx4 v[240:241], off
	v_lshl_add_u64 v[240:241], v[190:191], 0, v[162:163]
	s_mov_b32 m0, s47
	s_nop 0
	global_load_lds_dwordx4 v[240:241], off
	s_mov_b32 m0, s48
	s_nop 0
	global_load_lds_dwordx4 v[242:243], off
	s_waitcnt vmcnt(8)
	s_waitcnt lgkmcnt(0)
	s_barrier
	s_setprio 1
	s_waitcnt lgkmcnt(0)
	v_mfma_f32_16x16x32_bf16 v[124:127], v[136:139], v[202:205], v[124:127]
	v_mfma_f32_16x16x32_bf16 v[120:123], v[144:147], v[202:205], v[120:123]
	v_mfma_f32_16x16x32_bf16 v[116:119], v[136:139], v[210:213], v[116:119]
	v_mfma_f32_16x16x32_bf16 v[112:115], v[144:147], v[210:213], v[112:115]
	v_mfma_f32_16x16x32_bf16 v[108:111], v[136:139], v[218:221], v[108:111]
	v_mfma_f32_16x16x32_bf16 v[104:107], v[144:147], v[218:221], v[104:107]
	v_mfma_f32_16x16x32_bf16 v[100:103], v[136:139], v[226:229], v[100:103]
	v_mfma_f32_16x16x32_bf16 v[96:99], v[144:147], v[226:229], v[96:99]
	v_mfma_f32_16x16x32_bf16 v[124:127], v[140:143], v[206:209], v[124:127]
	v_mfma_f32_16x16x32_bf16 v[120:123], v[148:151], v[206:209], v[120:123]
	v_mfma_f32_16x16x32_bf16 v[116:119], v[140:143], v[214:217], v[116:119]
	v_mfma_f32_16x16x32_bf16 v[112:115], v[148:151], v[214:217], v[112:115]
	v_mfma_f32_16x16x32_bf16 v[108:111], v[140:143], v[222:225], v[108:111]
	v_mfma_f32_16x16x32_bf16 v[104:107], v[148:151], v[222:225], v[104:107]
	v_mfma_f32_16x16x32_bf16 v[100:103], v[140:143], v[230:233], v[100:103]
	v_mfma_f32_16x16x32_bf16 v[96:99], v[148:151], v[230:233], v[96:99]
	v_mfma_f32_16x16x32_bf16 v[92:95], v[152:155], v[202:205], v[92:95]
	v_mfma_f32_16x16x32_bf16 v[88:91], v[186:189], v[202:205], v[88:91]
	v_mfma_f32_16x16x32_bf16 v[84:87], v[152:155], v[210:213], v[84:87]
	v_mfma_f32_16x16x32_bf16 v[80:83], v[186:189], v[210:213], v[80:83]
	v_mfma_f32_16x16x32_bf16 v[76:79], v[152:155], v[218:221], v[76:79]
	v_mfma_f32_16x16x32_bf16 v[72:75], v[186:189], v[218:221], v[72:75]
	v_mfma_f32_16x16x32_bf16 v[68:71], v[152:155], v[226:229], v[68:71]
	v_mfma_f32_16x16x32_bf16 v[64:67], v[186:189], v[226:229], v[64:67]
	v_mfma_f32_16x16x32_bf16 v[92:95], v[156:159], v[206:209], v[92:95]
	v_mfma_f32_16x16x32_bf16 v[88:91], v[198:201], v[206:209], v[88:91]
	v_mfma_f32_16x16x32_bf16 v[84:87], v[156:159], v[214:217], v[84:87]
	v_mfma_f32_16x16x32_bf16 v[80:83], v[198:201], v[214:217], v[80:83]
	v_mfma_f32_16x16x32_bf16 v[76:79], v[156:159], v[222:225], v[76:79]
	v_mfma_f32_16x16x32_bf16 v[72:75], v[198:201], v[222:225], v[72:75]
	v_mfma_f32_16x16x32_bf16 v[68:71], v[156:159], v[230:233], v[68:71]
	v_mfma_f32_16x16x32_bf16 v[64:67], v[198:201], v[230:233], v[64:67]
	s_setprio 0
	s_barrier
	s_add_i32 s37, 0, 0x18000
	s_add_i32 s41, 0, 0x1c000
	v_add_u32_e32 v148, s37, v194
	v_add_u32_e32 v197, s41, v194
	ds_read_b128 v[136:139], v148
	ds_read_b128 v[140:143], v148 offset:1024
	ds_read_b128 v[144:147], v148 offset:2048
	ds_read_b128 v[148:151], v148 offset:3072
	ds_read_b128 v[152:155], v197
	ds_read_b128 v[156:159], v197 offset:1024
	ds_read_b128 v[186:189], v197 offset:2048
	ds_read_b128 v[198:201], v197 offset:3072
	v_lshl_add_u64 v[190:191], v[190:191], 0, s[12:13]
	s_mov_b32 m0, s49
	v_lshl_add_u64 v[244:245], v[190:191], 0, v[162:163]
	ds_read_b128 v[202:205], v195 offset:32768
	ds_read_b128 v[206:209], v195 offset:33792
	ds_read_b128 v[210:213], v195 offset:34816
	ds_read_b128 v[214:217], v195 offset:35840
	ds_read_b128 v[218:221], v195 offset:36864
	ds_read_b128 v[222:225], v195 offset:37888
	ds_read_b128 v[226:229], v195 offset:38912
	ds_read_b128 v[230:233], v195 offset:39936
	global_load_lds_dwordx4 v[244:245], off
	v_lshl_add_u64 v[190:191], v[190:191], 0, v[164:165]
	s_mov_b32 m0, s50
	s_nop 0
	global_load_lds_dwordx4 v[190:191], off
	s_waitcnt vmcnt(8)
	s_waitcnt lgkmcnt(0)
	s_barrier
	s_setprio 1
	s_waitcnt lgkmcnt(0)
	v_mfma_f32_16x16x32_bf16 v[60:63], v[136:139], v[202:205], v[60:63]
	v_mfma_f32_16x16x32_bf16 v[56:59], v[144:147], v[202:205], v[56:59]
	v_mfma_f32_16x16x32_bf16 v[52:55], v[136:139], v[210:213], v[52:55]
	v_mfma_f32_16x16x32_bf16 v[48:51], v[144:147], v[210:213], v[48:51]
	v_mfma_f32_16x16x32_bf16 v[44:47], v[136:139], v[218:221], v[44:47]
	v_mfma_f32_16x16x32_bf16 v[40:43], v[144:147], v[218:221], v[40:43]
	v_mfma_f32_16x16x32_bf16 v[36:39], v[136:139], v[226:229], v[36:39]
	v_mfma_f32_16x16x32_bf16 v[32:35], v[144:147], v[226:229], v[32:35]
	v_mfma_f32_16x16x32_bf16 v[60:63], v[140:143], v[206:209], v[60:63]
	v_mfma_f32_16x16x32_bf16 v[56:59], v[148:151], v[206:209], v[56:59]
	v_mfma_f32_16x16x32_bf16 v[52:55], v[140:143], v[214:217], v[52:55]
	v_mfma_f32_16x16x32_bf16 v[48:51], v[148:151], v[214:217], v[48:51]
	v_mfma_f32_16x16x32_bf16 v[44:47], v[140:143], v[222:225], v[44:47]
	v_mfma_f32_16x16x32_bf16 v[40:43], v[148:151], v[222:225], v[40:43]
	v_mfma_f32_16x16x32_bf16 v[36:39], v[140:143], v[230:233], v[36:39]
	v_mfma_f32_16x16x32_bf16 v[32:35], v[148:151], v[230:233], v[32:35]
	v_mfma_f32_16x16x32_bf16 v[28:31], v[152:155], v[202:205], v[28:31]
	v_mfma_f32_16x16x32_bf16 v[24:27], v[186:189], v[202:205], v[24:27]
	v_mfma_f32_16x16x32_bf16 v[20:23], v[152:155], v[210:213], v[20:23]
	v_mfma_f32_16x16x32_bf16 v[16:19], v[186:189], v[210:213], v[16:19]
	v_mfma_f32_16x16x32_bf16 v[12:15], v[152:155], v[218:221], v[12:15]
	v_mfma_f32_16x16x32_bf16 v[8:11], v[186:189], v[218:221], v[8:11]
	v_mfma_f32_16x16x32_bf16 v[4:7], v[152:155], v[226:229], v[4:7]
	v_mfma_f32_16x16x32_bf16 v[0:3], v[186:189], v[226:229], v[0:3]
	v_mfma_f32_16x16x32_bf16 v[28:31], v[156:159], v[206:209], v[28:31]
	v_mfma_f32_16x16x32_bf16 v[24:27], v[198:201], v[206:209], v[24:27]
	v_mfma_f32_16x16x32_bf16 v[20:23], v[156:159], v[214:217], v[20:23]
	v_mfma_f32_16x16x32_bf16 v[16:19], v[198:201], v[214:217], v[16:19]
	v_mfma_f32_16x16x32_bf16 v[12:15], v[156:159], v[222:225], v[12:15]
	v_mfma_f32_16x16x32_bf16 v[8:11], v[198:201], v[222:225], v[8:11]
	v_mfma_f32_16x16x32_bf16 v[4:7], v[156:159], v[230:233], v[4:7]
	v_mfma_f32_16x16x32_bf16 v[0:3], v[198:201], v[230:233], v[0:3]
	s_setprio 0
	s_barrier
	s_add_i32 s37, s37, s3
	v_lshl_add_u64 v[190:191], v[236:237], 0, s[16:17]
	s_mov_b32 m0, s37
	ds_read_b128 v[202:205], v195 offset:49152
	ds_read_b128 v[206:209], v195 offset:50176
	ds_read_b128 v[210:213], v195 offset:51200
	ds_read_b128 v[214:217], v195 offset:52224
	ds_read_b128 v[218:221], v195 offset:53248
	ds_read_b128 v[222:225], v195 offset:54272
	ds_read_b128 v[226:229], v195 offset:55296
	ds_read_b128 v[230:233], v195 offset:56320
	global_load_lds_dwordx4 v[190:191], off
	v_lshl_add_u64 v[190:191], v[238:239], 0, s[16:17]
	s_add_i32 m0, s37, 0x2000
	s_add_i32 s37, s41, s3
	global_load_lds_dwordx4 v[190:191], off
	v_lshl_add_u64 v[190:191], v[234:235], 0, s[18:19]
	v_lshl_add_u64 v[234:235], v[190:191], 0, v[162:163]
	s_mov_b32 m0, s37
	v_lshl_add_u64 v[190:191], v[190:191], 0, v[164:165]
	global_load_lds_dwordx4 v[234:235], off
	s_add_i32 m0, s37, 0x2000
	s_nop 0
	global_load_lds_dwordx4 v[190:191], off
	v_lshl_add_u64 v[190:191], v[240:241], 0, s[16:17]
	s_mov_b32 m0, s52
	s_nop 0
	global_load_lds_dwordx4 v[190:191], off
	v_lshl_add_u64 v[190:191], v[242:243], 0, s[16:17]
	s_mov_b32 m0, s53
	s_nop 0
	global_load_lds_dwordx4 v[190:191], off
	s_waitcnt vmcnt(8)
	s_waitcnt lgkmcnt(0)
	s_barrier
	s_setprio 1
	s_waitcnt lgkmcnt(0)
	v_mfma_f32_16x16x32_bf16 v[124:127], v[136:139], v[202:205], v[124:127]
	v_mfma_f32_16x16x32_bf16 v[120:123], v[144:147], v[202:205], v[120:123]
	v_mfma_f32_16x16x32_bf16 v[116:119], v[136:139], v[210:213], v[116:119]
	v_mfma_f32_16x16x32_bf16 v[112:115], v[144:147], v[210:213], v[112:115]
	v_mfma_f32_16x16x32_bf16 v[108:111], v[136:139], v[218:221], v[108:111]
	v_mfma_f32_16x16x32_bf16 v[104:107], v[144:147], v[218:221], v[104:107]
	v_mfma_f32_16x16x32_bf16 v[100:103], v[136:139], v[226:229], v[100:103]
	v_mfma_f32_16x16x32_bf16 v[96:99], v[144:147], v[226:229], v[96:99]
	v_mfma_f32_16x16x32_bf16 v[124:127], v[140:143], v[206:209], v[124:127]
	v_mfma_f32_16x16x32_bf16 v[120:123], v[148:151], v[206:209], v[120:123]
	v_mfma_f32_16x16x32_bf16 v[116:119], v[140:143], v[214:217], v[116:119]
	v_mfma_f32_16x16x32_bf16 v[112:115], v[148:151], v[214:217], v[112:115]
	v_mfma_f32_16x16x32_bf16 v[108:111], v[140:143], v[222:225], v[108:111]
	v_mfma_f32_16x16x32_bf16 v[104:107], v[148:151], v[222:225], v[104:107]
	v_mfma_f32_16x16x32_bf16 v[100:103], v[140:143], v[230:233], v[100:103]
	v_mfma_f32_16x16x32_bf16 v[96:99], v[148:151], v[230:233], v[96:99]
	v_mfma_f32_16x16x32_bf16 v[92:95], v[152:155], v[202:205], v[92:95]
	v_mfma_f32_16x16x32_bf16 v[88:91], v[186:189], v[202:205], v[88:91]
	v_mfma_f32_16x16x32_bf16 v[84:87], v[152:155], v[210:213], v[84:87]
	v_mfma_f32_16x16x32_bf16 v[80:83], v[186:189], v[210:213], v[80:83]
	v_mfma_f32_16x16x32_bf16 v[76:79], v[152:155], v[218:221], v[76:79]
	v_mfma_f32_16x16x32_bf16 v[72:75], v[186:189], v[218:221], v[72:75]
	v_mfma_f32_16x16x32_bf16 v[68:71], v[152:155], v[226:229], v[68:71]
	v_mfma_f32_16x16x32_bf16 v[64:67], v[186:189], v[226:229], v[64:67]
	v_mfma_f32_16x16x32_bf16 v[92:95], v[156:159], v[206:209], v[92:95]
	v_mfma_f32_16x16x32_bf16 v[88:91], v[198:201], v[206:209], v[88:91]
	v_mfma_f32_16x16x32_bf16 v[84:87], v[156:159], v[214:217], v[84:87]
	v_mfma_f32_16x16x32_bf16 v[80:83], v[198:201], v[214:217], v[80:83]
	v_mfma_f32_16x16x32_bf16 v[76:79], v[156:159], v[222:225], v[76:79]
	v_mfma_f32_16x16x32_bf16 v[72:75], v[198:201], v[222:225], v[72:75]
	v_mfma_f32_16x16x32_bf16 v[68:71], v[156:159], v[230:233], v[68:71]
	v_mfma_f32_16x16x32_bf16 v[64:67], v[198:201], v[230:233], v[64:67]
	s_setprio 0
	s_barrier
	v_lshl_add_u64 v[132:133], v[132:133], 0, s[24:25]
	s_cmp_ge_i32 s35, s5
	v_lshl_add_u64 v[134:135], v[134:135], 0, s[24:25]
	s_cbranch_scc0 .LBB0_1383
